# residual-GEMM epilogues: f32 output stores regrouped to 8 rows x full 128-byte lines per instruction (lane L <-> L^8 tuple exchange via ds_swizzle), was 16 rows x 64 bytes
# speedup vs baseline: 1.0107x; 1.0107x over previous
; #define PG8_STAGE(bufoff, gbase, voff) do { _Pragma("unroll") for (int _i = 0; _i < 2; ++_i) \
;         __builtin_amdgcn_global_load_lds((const unsigned*)((const char*)(gbase) + (voff)[_i]), (PG8_LAS unsigned*)(lds + (bufoff) + ldsw + _i * 8192), 16, 0, 0); } while (0)
; #define PG8_LDA(dst, b, h) do { _Pragma("unroll") for (int m = 0; m < 4; ++m) _Pragma("unroll") for (int k = 0; k < 2; ++k) dst[m][k] = *(const PG8_LAS bf16x8*)(lds + PG8_SA(b, h) + aoff + m * 2048 + k * 1024); } while (0)
; #define PG8_LDB(dst, b, h) do { _Pragma("unroll") for (int n = 0; n < 2; ++n) _Pragma("unroll") for (int k = 0; k < 2; ++k) dst[n][k] = *(const PG8_LAS bf16x8*)(lds + PG8_SB(b, h) + boff + n * 2048 + k * 1024); } while (0)
; #define PG8_MMA(ai, bj, At, Bt) do { __builtin_amdgcn_s_setprio(1); _Pragma("unroll") for (int m = 0; m < 4; ++m) _Pragma("unroll") for (int n = 0; n < 2; ++n) _Pragma("unroll") for (int k = 0; k < 2; ++k) \
;         acc[ai][bj][m][n] = __builtin_amdgcn_mfma_f32_16x16x32_bf16(Bt[n][k], At[m][k], acc[ai][bj][m][n], 0, 0, 0); __builtin_amdgcn_s_setprio(0); } while (0)
; #define PG8_WAIT_V(n) asm volatile("s_waitcnt vmcnt(" #n ")" ::: "memory")
; #define PG8_WAIT_L(n) asm volatile("s_waitcnt lgkmcnt(" #n ")" ::: "memory")
; #define PG8_BAR __builtin_amdgcn_s_barrier()
; #define PG8_SCHED __builtin_amdgcn_sched_barrier(0)
; template <class Epi, class Sched, bool ALIGN_EPI = false, bool SP2 = false>
; __device__ __forceinline__ void gemm_phase(PG8_LAS unsigned char* lds, const Gemm g, const Sched& S, const Epi& E) {
;     ...
;             PG8_LDB(B0, 0, 0); PG8_LDB(B1, 0, 1); PG8_SCHED; PG8_LDA(At, 0, 0); PG8_STAGE(PG8_SA(1, 1), a1 + hstep, voffA);
;             PG8_WAIT_V(8); PG8_WAIT_L(0); PG8_BAR; PG8_MMA(0, 0, At, B0); PG8_MMA(0, 1, At, B1); PG8_BAR; PG8_SCHED;
;             PG8_LDA(At, 0, 1); PG8_STAGE(PG8_SB(0, 0), b2, voffB); PG8_STAGE(PG8_SB(0, 1), b2 + hstep, voffB); PG8_STAGE(PG8_SA(0, 0), a2, voffA);
;             PG8_WAIT_V(8); PG8_WAIT_L(0); PG8_BAR; PG8_MMA(1, 0, At, B0); PG8_MMA(1, 1, At, B1); PG8_BAR; PG8_SCHED;
.LBB0_658:
	ds_read_b128 v[144:147], v151
	ds_read_b128 v[156:159], v151 offset:1024
	ds_read_b128 v[160:163], v151 offset:2048
	ds_read_b128 v[168:171], v151 offset:3072
	ds_read_b128 v[172:175], v152
	ds_read_b128 v[176:179], v152 offset:1024
	ds_read_b128 v[180:183], v152 offset:2048
	ds_read_b128 v[184:187], v152 offset:3072
	s_add_u32 s26, s24, 0xfffc0080
	s_addc_u32 s27, s25, -1
	s_cmp_eq_u32 s50, 12
	s_cselect_b32 s29, s17, s27
	s_cselect_b32 s28, s23, s26
	s_cselect_b32 s27, s15, s49
	s_cselect_b32 s26, s47, s48
	v_lshl_add_u64 v[164:165], s[24:25], 0, v[136:137]
	s_add_i32 m0, s34, 0xc000
	ds_read_b128 v[188:191], v153
	ds_read_b128 v[192:195], v153 offset:1024
	ds_read_b128 v[196:199], v153 offset:2048
	ds_read_b128 v[200:203], v153 offset:3072
	ds_read_b128 v[204:207], v153 offset:4096
	ds_read_b128 v[208:211], v153 offset:5120
	ds_read_b128 v[212:215], v153 offset:6144
	ds_read_b128 v[216:219], v153 offset:7168
	global_load_lds_dwordx4 v[164:165], off
	v_lshl_add_u64 v[164:165], s[24:25], 0, v[138:139]
	s_add_i32 m0, s34, 0xe000
	s_nop 0
	global_load_lds_dwordx4 v[164:165], off
	s_waitcnt vmcnt(8)
	s_waitcnt lgkmcnt(0)
	s_barrier
	s_setprio 1
	s_waitcnt lgkmcnt(0)
	v_mfma_f32_16x16x32_bf16 v[124:127], v[144:147], v[188:191], v[124:127]
	v_mfma_f32_16x16x32_bf16 v[120:123], v[160:163], v[188:191], v[120:123]
	v_mfma_f32_16x16x32_bf16 v[108:111], v[144:147], v[196:199], v[108:111]
	v_mfma_f32_16x16x32_bf16 v[104:107], v[160:163], v[196:199], v[104:107]
	v_mfma_f32_16x16x32_bf16 v[92:95], v[144:147], v[204:207], v[92:95]
	v_mfma_f32_16x16x32_bf16 v[88:91], v[160:163], v[204:207], v[88:91]
	v_mfma_f32_16x16x32_bf16 v[76:79], v[144:147], v[212:215], v[76:79]
	v_mfma_f32_16x16x32_bf16 v[72:75], v[160:163], v[212:215], v[72:75]
	v_mfma_f32_16x16x32_bf16 v[124:127], v[156:159], v[192:195], v[124:127]
	v_mfma_f32_16x16x32_bf16 v[120:123], v[168:171], v[192:195], v[120:123]
	v_mfma_f32_16x16x32_bf16 v[108:111], v[156:159], v[200:203], v[108:111]
	v_mfma_f32_16x16x32_bf16 v[104:107], v[168:171], v[200:203], v[104:107]
	v_mfma_f32_16x16x32_bf16 v[92:95], v[156:159], v[208:211], v[92:95]
	v_mfma_f32_16x16x32_bf16 v[88:91], v[168:171], v[208:211], v[88:91]
	v_mfma_f32_16x16x32_bf16 v[76:79], v[156:159], v[216:219], v[76:79]
	v_mfma_f32_16x16x32_bf16 v[72:75], v[168:171], v[216:219], v[72:75]
	s_setprio 0
	s_setprio 1
	v_mfma_f32_16x16x32_bf16 v[116:119], v[172:175], v[188:191], v[116:119]
	v_mfma_f32_16x16x32_bf16 v[112:115], v[180:183], v[188:191], v[112:115]
	v_mfma_f32_16x16x32_bf16 v[100:103], v[172:175], v[196:199], v[100:103]
	v_mfma_f32_16x16x32_bf16 v[96:99], v[180:183], v[196:199], v[96:99]
	v_mfma_f32_16x16x32_bf16 v[84:87], v[172:175], v[204:207], v[84:87]
	v_mfma_f32_16x16x32_bf16 v[80:83], v[180:183], v[204:207], v[80:83]
	v_mfma_f32_16x16x32_bf16 v[68:71], v[172:175], v[212:215], v[68:71]
	v_mfma_f32_16x16x32_bf16 v[64:67], v[180:183], v[212:215], v[64:67]
	v_mfma_f32_16x16x32_bf16 v[116:119], v[176:179], v[192:195], v[116:119]
	v_mfma_f32_16x16x32_bf16 v[112:115], v[184:187], v[192:195], v[112:115]
	v_mfma_f32_16x16x32_bf16 v[100:103], v[176:179], v[200:203], v[100:103]
	v_mfma_f32_16x16x32_bf16 v[96:99], v[184:187], v[200:203], v[96:99]
	v_mfma_f32_16x16x32_bf16 v[84:87], v[176:179], v[208:211], v[84:87]
	v_mfma_f32_16x16x32_bf16 v[80:83], v[184:187], v[208:211], v[80:83]
	v_mfma_f32_16x16x32_bf16 v[68:71], v[176:179], v[216:219], v[68:71]
	v_mfma_f32_16x16x32_bf16 v[64:67], v[184:187], v[216:219], v[64:67]
	s_setprio 0
	s_barrier
	s_add_i32 s51, s44, s33
	v_lshl_add_u64 v[164:165], s[26:27], 0, v[130:131]
	s_mov_b32 m0, s51
	ds_read_b128 v[188:191], v153 offset:16384
	ds_read_b128 v[192:195], v153 offset:17408
	ds_read_b128 v[196:199], v153 offset:18432
	ds_read_b128 v[200:203], v153 offset:19456
	ds_read_b128 v[204:207], v153 offset:20480
	ds_read_b128 v[208:211], v153 offset:21504
	ds_read_b128 v[212:215], v153 offset:22528
	ds_read_b128 v[216:219], v153 offset:23552
	global_load_lds_dwordx4 v[164:165], off
	s_add_i32 m0, s51, 0x2000
	s_add_u32 s52, s26, 0x40000
	v_lshl_add_u64 v[220:221], s[26:27], 0, v[134:135]
	s_addc_u32 s53, s27, 0
	s_add_i32 s51, s45, s33
	global_load_lds_dwordx4 v[220:221], off
	v_lshl_add_u64 v[222:223], s[52:53], 0, v[130:131]
	s_mov_b32 m0, s51
	v_lshl_add_u64 v[224:225], s[28:29], 0, v[132:133]
	global_load_lds_dwordx4 v[222:223], off
	v_lshl_add_u64 v[222:223], s[52:53], 0, v[134:135]
	s_add_i32 m0, s51, 0x2000
	s_nop 0
	global_load_lds_dwordx4 v[222:223], off
	v_lshl_add_u64 v[222:223], s[28:29], 0, v[128:129]
	s_mov_b32 m0, s34
	s_nop 0
	global_load_lds_dwordx4 v[222:223], off
	s_mov_b32 m0, s35
	s_nop 0
	global_load_lds_dwordx4 v[224:225], off
	s_waitcnt vmcnt(8)
	s_waitcnt lgkmcnt(0)
	s_barrier
; #define PG8_STAGE(bufoff, gbase, voff) do { _Pragma("unroll") for (int _i = 0; _i < 2; ++_i) \
;         __builtin_amdgcn_global_load_lds((const unsigned*)((const char*)(gbase) + (voff)[_i]), (PG8_LAS unsigned*)(lds + (bufoff) + ldsw + _i * 8192), 16, 0, 0); } while (0)
; #define PG8_LDA(dst, b, h) do { _Pragma("unroll") for (int m = 0; m < 4; ++m) _Pragma("unroll") for (int k = 0; k < 2; ++k) dst[m][k] = *(const PG8_LAS bf16x8*)(lds + PG8_SA(b, h) + aoff + m * 2048 + k * 1024); } while (0)
; #define PG8_LDB(dst, b, h) do { _Pragma("unroll") for (int n = 0; n < 2; ++n) _Pragma("unroll") for (int k = 0; k < 2; ++k) dst[n][k] = *(const PG8_LAS bf16x8*)(lds + PG8_SB(b, h) + boff + n * 2048 + k * 1024); } while (0)
; #define PG8_MMA(ai, bj, At, Bt) do { __builtin_amdgcn_s_setprio(1); _Pragma("unroll") for (int m = 0; m < 4; ++m) _Pragma("unroll") for (int n = 0; n < 2; ++n) _Pragma("unroll") for (int k = 0; k < 2; ++k) \
;         acc[ai][bj][m][n] = __builtin_amdgcn_mfma_f32_16x16x32_bf16(Bt[n][k], At[m][k], acc[ai][bj][m][n], 0, 0, 0); __builtin_amdgcn_s_setprio(0); } while (0)
; #define PG8_WAIT_V(n) asm volatile("s_waitcnt vmcnt(" #n ")" ::: "memory")
; #define PG8_WAIT_L(n) asm volatile("s_waitcnt lgkmcnt(" #n ")" ::: "memory")
; #define PG8_BAR __builtin_amdgcn_s_barrier()
; #define PG8_SCHED __builtin_amdgcn_sched_barrier(0)
; template <class Epi, class Sched, bool ALIGN_EPI = false, bool SP2 = false>
; __device__ __forceinline__ void gemm_phase(PG8_LAS unsigned char* lds, const Gemm g, const Sched& S, const Epi& E) {
;     ...
;             PG8_WAIT_V(8); PG8_WAIT_L(0); PG8_BAR; PG8_MMA(1, 0, At, B0); PG8_MMA(1, 1, At, B1); PG8_BAR; PG8_SCHED;
;             PG8_LDB(B0, 1, 0); PG8_LDB(B1, 1, 1); PG8_SCHED; PG8_LDA(At, 1, 0); PG8_STAGE(PG8_SA(0, 1), a2 + hstep, voffA);
;             PG8_WAIT_V(8); PG8_WAIT_L(0); PG8_BAR; PG8_MMA(0, 0, At, B0); PG8_MMA(0, 1, At, B1); PG8_BAR; PG8_SCHED;
;             PG8_LDA(At, 1, 1); PG8_STAGE(PG8_SB(1, 0), b3, voffB); PG8_STAGE(PG8_SB(1, 1), b3 + hstep, voffB); PG8_STAGE(PG8_SA(1, 0), a3, voffA);
	s_setprio 1
	s_waitcnt lgkmcnt(0)
	v_mfma_f32_16x16x32_bf16 v[60:63], v[144:147], v[188:191], v[60:63]
	v_mfma_f32_16x16x32_bf16 v[56:59], v[160:163], v[188:191], v[56:59]
	v_mfma_f32_16x16x32_bf16 v[44:47], v[144:147], v[196:199], v[44:47]
	v_mfma_f32_16x16x32_bf16 v[40:43], v[160:163], v[196:199], v[40:43]
	v_mfma_f32_16x16x32_bf16 v[28:31], v[144:147], v[204:207], v[28:31]
	v_mfma_f32_16x16x32_bf16 v[24:27], v[160:163], v[204:207], v[24:27]
	v_mfma_f32_16x16x32_bf16 v[12:15], v[144:147], v[212:215], v[12:15]
	v_mfma_f32_16x16x32_bf16 v[8:11], v[160:163], v[212:215], v[8:11]
	v_mfma_f32_16x16x32_bf16 v[60:63], v[156:159], v[192:195], v[60:63]
	v_mfma_f32_16x16x32_bf16 v[56:59], v[168:171], v[192:195], v[56:59]
	v_mfma_f32_16x16x32_bf16 v[44:47], v[156:159], v[200:203], v[44:47]
	v_mfma_f32_16x16x32_bf16 v[40:43], v[168:171], v[200:203], v[40:43]
	v_mfma_f32_16x16x32_bf16 v[28:31], v[156:159], v[208:211], v[28:31]
	v_mfma_f32_16x16x32_bf16 v[24:27], v[168:171], v[208:211], v[24:27]
	v_mfma_f32_16x16x32_bf16 v[12:15], v[156:159], v[216:219], v[12:15]
	v_mfma_f32_16x16x32_bf16 v[8:11], v[168:171], v[216:219], v[8:11]
	s_setprio 0
	s_setprio 1
	v_mfma_f32_16x16x32_bf16 v[52:55], v[172:175], v[188:191], v[52:55]
	v_mfma_f32_16x16x32_bf16 v[48:51], v[180:183], v[188:191], v[48:51]
	v_mfma_f32_16x16x32_bf16 v[36:39], v[172:175], v[196:199], v[36:39]
	v_mfma_f32_16x16x32_bf16 v[32:35], v[180:183], v[196:199], v[32:35]
	v_mfma_f32_16x16x32_bf16 v[20:23], v[172:175], v[204:207], v[20:23]
	v_mfma_f32_16x16x32_bf16 v[16:19], v[180:183], v[204:207], v[16:19]
	v_mfma_f32_16x16x32_bf16 v[4:7], v[172:175], v[212:215], v[4:7]
	v_mfma_f32_16x16x32_bf16 v[0:3], v[180:183], v[212:215], v[0:3]
	v_mfma_f32_16x16x32_bf16 v[52:55], v[176:179], v[192:195], v[52:55]
	v_mfma_f32_16x16x32_bf16 v[48:51], v[184:187], v[192:195], v[48:51]
	v_mfma_f32_16x16x32_bf16 v[36:39], v[176:179], v[200:203], v[36:39]
	v_mfma_f32_16x16x32_bf16 v[32:35], v[184:187], v[200:203], v[32:35]
	v_mfma_f32_16x16x32_bf16 v[20:23], v[176:179], v[208:211], v[20:23]
	v_mfma_f32_16x16x32_bf16 v[16:19], v[184:187], v[208:211], v[16:19]
	v_mfma_f32_16x16x32_bf16 v[4:7], v[176:179], v[216:219], v[4:7]
	v_mfma_f32_16x16x32_bf16 v[0:3], v[184:187], v[216:219], v[0:3]
	s_setprio 0
	s_barrier
	s_add_i32 s51, 0, 0x18000
	v_add_u32_e32 v155, s51, v149
	s_add_i32 s52, 0, 0x1c000
	ds_read_b128 v[144:147], v155
	ds_read_b128 v[156:159], v155 offset:1024
	ds_read_b128 v[160:163], v155 offset:2048
	ds_read_b128 v[168:171], v155 offset:3072
	v_add_u32_e32 v155, s52, v149
	ds_read_b128 v[172:175], v155
	ds_read_b128 v[176:179], v155 offset:1024
	ds_read_b128 v[180:183], v155 offset:2048
	ds_read_b128 v[184:187], v155 offset:3072
	s_add_u32 s28, s28, 0x40000
	s_addc_u32 s29, s29, 0
	s_mov_b32 m0, s36
	v_lshl_add_u64 v[226:227], s[28:29], 0, v[128:129]
	ds_read_b128 v[188:191], v153 offset:32768
	ds_read_b128 v[192:195], v153 offset:33792
	ds_read_b128 v[196:199], v153 offset:34816
	ds_read_b128 v[200:203], v153 offset:35840
	ds_read_b128 v[204:207], v153 offset:36864
	ds_read_b128 v[208:211], v153 offset:37888
	ds_read_b128 v[212:215], v153 offset:38912
	ds_read_b128 v[216:219], v153 offset:39936
	global_load_lds_dwordx4 v[226:227], off
	v_lshl_add_u64 v[226:227], s[28:29], 0, v[132:133]
	s_mov_b32 m0, s37
	s_nop 0
	global_load_lds_dwordx4 v[226:227], off
	s_waitcnt vmcnt(8)
	s_waitcnt lgkmcnt(0)
	s_barrier
	s_setprio 1
	s_waitcnt lgkmcnt(0)
	v_mfma_f32_16x16x32_bf16 v[124:127], v[144:147], v[188:191], v[124:127]
	v_mfma_f32_16x16x32_bf16 v[120:123], v[160:163], v[188:191], v[120:123]
	v_mfma_f32_16x16x32_bf16 v[108:111], v[144:147], v[196:199], v[108:111]
	v_mfma_f32_16x16x32_bf16 v[104:107], v[160:163], v[196:199], v[104:107]
	v_mfma_f32_16x16x32_bf16 v[92:95], v[144:147], v[204:207], v[92:95]
	v_mfma_f32_16x16x32_bf16 v[88:91], v[160:163], v[204:207], v[88:91]
	v_mfma_f32_16x16x32_bf16 v[76:79], v[144:147], v[212:215], v[76:79]
	v_mfma_f32_16x16x32_bf16 v[72:75], v[160:163], v[212:215], v[72:75]
	v_mfma_f32_16x16x32_bf16 v[124:127], v[156:159], v[192:195], v[124:127]
	v_mfma_f32_16x16x32_bf16 v[120:123], v[168:171], v[192:195], v[120:123]
	v_mfma_f32_16x16x32_bf16 v[108:111], v[156:159], v[200:203], v[108:111]
	v_mfma_f32_16x16x32_bf16 v[104:107], v[168:171], v[200:203], v[104:107]
	v_mfma_f32_16x16x32_bf16 v[92:95], v[156:159], v[208:211], v[92:95]
	v_mfma_f32_16x16x32_bf16 v[88:91], v[168:171], v[208:211], v[88:91]
	v_mfma_f32_16x16x32_bf16 v[76:79], v[156:159], v[216:219], v[76:79]
	v_mfma_f32_16x16x32_bf16 v[72:75], v[168:171], v[216:219], v[72:75]
	s_setprio 0
	s_setprio 1
	v_mfma_f32_16x16x32_bf16 v[116:119], v[172:175], v[188:191], v[116:119]
	v_mfma_f32_16x16x32_bf16 v[112:115], v[180:183], v[188:191], v[112:115]
	v_mfma_f32_16x16x32_bf16 v[100:103], v[172:175], v[196:199], v[100:103]
	v_mfma_f32_16x16x32_bf16 v[96:99], v[180:183], v[196:199], v[96:99]
	v_mfma_f32_16x16x32_bf16 v[84:87], v[172:175], v[204:207], v[84:87]
	v_mfma_f32_16x16x32_bf16 v[80:83], v[180:183], v[204:207], v[80:83]
	v_mfma_f32_16x16x32_bf16 v[68:71], v[172:175], v[212:215], v[68:71]
	v_mfma_f32_16x16x32_bf16 v[64:67], v[180:183], v[212:215], v[64:67]
	v_mfma_f32_16x16x32_bf16 v[116:119], v[176:179], v[192:195], v[116:119]
	v_mfma_f32_16x16x32_bf16 v[112:115], v[184:187], v[192:195], v[112:115]
	v_mfma_f32_16x16x32_bf16 v[100:103], v[176:179], v[200:203], v[100:103]
	v_mfma_f32_16x16x32_bf16 v[96:99], v[184:187], v[200:203], v[96:99]
	v_mfma_f32_16x16x32_bf16 v[84:87], v[176:179], v[208:211], v[84:87]
	v_mfma_f32_16x16x32_bf16 v[80:83], v[184:187], v[208:211], v[80:83]
	v_mfma_f32_16x16x32_bf16 v[68:71], v[176:179], v[216:219], v[68:71]
	v_mfma_f32_16x16x32_bf16 v[64:67], v[184:187], v[216:219], v[64:67]
	s_setprio 0
	s_barrier
; #define PG8_LAS __attribute__((address_space(3)))
; #define PG8_STAGE(bufoff, gbase, voff) do { _Pragma("unroll") for (int _i = 0; _i < 2; ++_i) \
;         __builtin_amdgcn_global_load_lds((const unsigned*)((const char*)(gbase) + (voff)[_i]), (PG8_LAS unsigned*)(lds + (bufoff) + ldsw + _i * 8192), 16, 0, 0); } while (0)
; #define PG8_LDA(dst, b, h) do { _Pragma("unroll") for (int m = 0; m < 4; ++m) _Pragma("unroll") for (int k = 0; k < 2; ++k) dst[m][k] = *(const PG8_LAS bf16x8*)(lds + PG8_SA(b, h) + aoff + m * 2048 + k * 1024); } while (0)
; #define PG8_MMA(ai, bj, At, Bt) do { __builtin_amdgcn_s_setprio(1); _Pragma("unroll") for (int m = 0; m < 4; ++m) _Pragma("unroll") for (int n = 0; n < 2; ++n) _Pragma("unroll") for (int k = 0; k < 2; ++k) \
;         acc[ai][bj][m][n] = __builtin_amdgcn_mfma_f32_16x16x32_bf16(Bt[n][k], At[m][k], acc[ai][bj][m][n], 0, 0, 0); __builtin_amdgcn_s_setprio(0); } while (0)
; #define PG8_WAIT_V(n) asm volatile("s_waitcnt vmcnt(" #n ")" ::: "memory")
; #define PG8_WAIT_L(n) asm volatile("s_waitcnt lgkmcnt(" #n ")" ::: "memory")
; #define PG8_BAR __builtin_amdgcn_s_barrier()
; #define PG8_SCHED __builtin_amdgcn_sched_barrier(0)
;     __device__ __forceinline__ void operator()(const f32x4 (&acc)[2][2][4][2], const Unit& u, int wr, int wc, int fr, int fq, const PG8_LAS float*) const {
;         const int row0 = u.pm * BM + wr * 64 + fr; const int col0 = u.pn * BM + wc * 32 + 8 * fq;
; #pragma unroll
;         for (int ai = 0; ai < 2; ++ai)
; #pragma unroll
;             for (int m = 0; m < 4; ++m) { const int row = row0 + ai * HALF + m * 16; const size_t off = (size_t)row * ldc + col0; float ss = 0.f;
; template <class Epi, class Sched, bool ALIGN_EPI = false, bool SP2 = false>
; __device__ __forceinline__ void gemm_phase(PG8_LAS unsigned char* lds, const Gemm g, const Sched& S, const Epi& E) {
;     ...
;             PG8_LDA(At, 1, 1); PG8_STAGE(PG8_SB(1, 0), b3, voffB); PG8_STAGE(PG8_SB(1, 1), b3 + hstep, voffB); PG8_STAGE(PG8_SA(1, 0), a3, voffA);
;             PG8_WAIT_V(8); PG8_WAIT_L(0); PG8_BAR; PG8_MMA(1, 0, At, B0); PG8_MMA(1, 1, At, B1); PG8_BAR; PG8_SCHED;
	s_add_i32 s28, s51, s33
	v_lshl_add_u64 v[164:165], v[164:165], 0, s[10:11]
	s_mov_b32 m0, s28
	ds_read_b128 v[188:191], v153 offset:49152
	ds_read_b128 v[192:195], v153 offset:50176
	ds_read_b128 v[196:199], v153 offset:51200
	ds_read_b128 v[200:203], v153 offset:52224
	ds_read_b128 v[204:207], v153 offset:53248
	ds_read_b128 v[208:211], v153 offset:54272
	ds_read_b128 v[212:215], v153 offset:55296
	ds_read_b128 v[216:219], v153 offset:56320
	global_load_lds_dwordx4 v[164:165], off
	s_add_i32 m0, s28, 0x2000
	s_add_u32 s26, s26, 0x40080
	v_lshl_add_u64 v[164:165], v[220:221], 0, s[10:11]
	s_addc_u32 s27, s27, 0
	s_add_i32 s28, s52, s33
	global_load_lds_dwordx4 v[164:165], off
	v_lshl_add_u64 v[164:165], s[26:27], 0, v[130:131]
	s_mov_b32 m0, s28
	s_nop 0
	global_load_lds_dwordx4 v[164:165], off
	v_lshl_add_u64 v[164:165], s[26:27], 0, v[134:135]
	s_add_i32 m0, s28, 0x2000
	s_nop 0
	global_load_lds_dwordx4 v[164:165], off
	v_lshl_add_u64 v[164:165], v[222:223], 0, s[10:11]
	s_mov_b32 m0, s39
	s_nop 0
	global_load_lds_dwordx4 v[164:165], off
	v_lshl_add_u64 v[164:165], v[224:225], 0, s[10:11]
	s_mov_b32 m0, s40
	s_nop 0
	global_load_lds_dwordx4 v[164:165], off
	s_waitcnt vmcnt(8)
	s_waitcnt lgkmcnt(0)
	s_barrier
	s_setprio 1
	s_waitcnt lgkmcnt(0)
	v_mfma_f32_16x16x32_bf16 v[60:63], v[144:147], v[188:191], v[60:63]
	v_mfma_f32_16x16x32_bf16 v[56:59], v[160:163], v[188:191], v[56:59]
	v_mfma_f32_16x16x32_bf16 v[44:47], v[144:147], v[196:199], v[44:47]
	v_mfma_f32_16x16x32_bf16 v[40:43], v[160:163], v[196:199], v[40:43]
	v_mfma_f32_16x16x32_bf16 v[28:31], v[144:147], v[204:207], v[28:31]
	v_mfma_f32_16x16x32_bf16 v[24:27], v[160:163], v[204:207], v[24:27]
	v_mfma_f32_16x16x32_bf16 v[12:15], v[144:147], v[212:215], v[12:15]
	v_mfma_f32_16x16x32_bf16 v[8:11], v[160:163], v[212:215], v[8:11]
	v_mfma_f32_16x16x32_bf16 v[60:63], v[156:159], v[192:195], v[60:63]
	v_mfma_f32_16x16x32_bf16 v[56:59], v[168:171], v[192:195], v[56:59]
	v_mfma_f32_16x16x32_bf16 v[44:47], v[156:159], v[200:203], v[44:47]
	v_mfma_f32_16x16x32_bf16 v[40:43], v[168:171], v[200:203], v[40:43]
	v_mfma_f32_16x16x32_bf16 v[28:31], v[156:159], v[208:211], v[28:31]
	v_mfma_f32_16x16x32_bf16 v[24:27], v[168:171], v[208:211], v[24:27]
	v_mfma_f32_16x16x32_bf16 v[12:15], v[156:159], v[216:219], v[12:15]
	v_mfma_f32_16x16x32_bf16 v[8:11], v[168:171], v[216:219], v[8:11]
	s_setprio 0
	s_setprio 1
	v_mfma_f32_16x16x32_bf16 v[52:55], v[172:175], v[188:191], v[52:55]
	v_mfma_f32_16x16x32_bf16 v[48:51], v[180:183], v[188:191], v[48:51]
	v_mfma_f32_16x16x32_bf16 v[36:39], v[172:175], v[196:199], v[36:39]
	v_mfma_f32_16x16x32_bf16 v[32:35], v[180:183], v[196:199], v[32:35]
	v_mfma_f32_16x16x32_bf16 v[20:23], v[172:175], v[204:207], v[20:23]
	v_mfma_f32_16x16x32_bf16 v[16:19], v[180:183], v[204:207], v[16:19]
	v_mfma_f32_16x16x32_bf16 v[4:7], v[172:175], v[212:215], v[4:7]
	v_mfma_f32_16x16x32_bf16 v[0:3], v[180:183], v[212:215], v[0:3]
	v_mfma_f32_16x16x32_bf16 v[52:55], v[176:179], v[192:195], v[52:55]
	v_mfma_f32_16x16x32_bf16 v[48:51], v[184:187], v[192:195], v[48:51]
	v_mfma_f32_16x16x32_bf16 v[36:39], v[176:179], v[200:203], v[36:39]
	v_mfma_f32_16x16x32_bf16 v[32:35], v[184:187], v[200:203], v[32:35]
	v_mfma_f32_16x16x32_bf16 v[20:23], v[176:179], v[208:211], v[20:23]
	v_mfma_f32_16x16x32_bf16 v[16:19], v[184:187], v[208:211], v[16:19]
	v_mfma_f32_16x16x32_bf16 v[4:7], v[176:179], v[216:219], v[4:7]
	v_mfma_f32_16x16x32_bf16 v[0:3], v[184:187], v[216:219], v[0:3]
	s_setprio 0
	s_barrier
	s_add_i32 s50, s50, 2
	s_add_u32 s24, s24, 0x100
	s_addc_u32 s25, s25, 0
	s_add_u32 s48, s48, 0x100
	s_addc_u32 s49, s49, 0
	s_cmp_gt_u32 s50, 13
	s_cbranch_scc0 .LBB0_658
	v_mbcnt_lo_u32_b32 v234, -1, 0
	v_mbcnt_hi_u32_b32 v234, -1, v234
	v_bfe_u32 v234, v234, 3, 1
	v_sub_u32_e32 v231, 0, v234
	v_and_b32_e32 v230, 0xffff8010, v231
	v_and_b32_e32 v235, 0x7ff0, v231
	v_sub_u32_e32 v244, 0x8000, v235
	v_mov_b32_e32 v245, 0
	s_mov_b32 s98, 0xff00ff
	s_mov_b32 s99, 0xff00ff
	s_and_b64 vcc, exec, s[12:13]
	s_cbranch_vccz .LBB0_661
	s_barrier
.LBB0_661:
	v_lshl_add_u32 v146, s22, 8, v148
	v_lshl_or_b32 v144, s6, 8, v150
	v_ashrrev_i32_e32 v147, 31, v146
	v_ashrrev_i32_e32 v145, 31, v144
	v_lshlrev_b64 v[156:157], 10, v[146:147]
	v_lshl_add_u64 v[164:165], v[156:157], 0, v[144:145]
	v_readlane_b32 s48, v254, 3
	v_lshlrev_b64 v[168:169], 2, v[164:165]
	v_readlane_b32 s49, v254, 4
	v_readlane_b32 s22, v254, 39
	v_readlane_b32 s23, v254, 40
	v_lshl_add_u64 v[170:171], s[48:49], 0, v[168:169]
	global_load_dwordx4 v[156:159], v[170:171], off
	global_load_dwordx4 v[160:163], v[170:171], off offset:16
	v_lshl_add_u64 v[164:165], v[164:165], 1, s[22:23]
	v_lshl_add_u64 v[172:173], s[68:69], 0, v[168:169]
	v_xor_b32_e32 v155, 32, v154
	s_lshl_b32 s22, s6, 2
	s_ashr_i32 s23, s22, 31
	v_readlane_b32 s50, v254, 5
	v_readlane_b32 s51, v254, 6
	v_readlane_b32 s52, v254, 7
	v_readlane_b32 s53, v254, 8
	v_readlane_b32 s54, v254, 9
	v_readlane_b32 s55, v254, 10
	v_readlane_b32 s56, v254, 11
	v_readlane_b32 s57, v254, 12
	v_readlane_b32 s58, v254, 13
	v_readlane_b32 s59, v254, 14
	v_readlane_b32 s60, v254, 15
	v_readlane_b32 s61, v254, 16
	v_readlane_b32 s62, v254, 17
	v_readlane_b32 s63, v254, 18
	s_waitcnt vmcnt(0)
; __device__ __forceinline__ unsigned cvt_pk_bf16(float lo, float hi) { const f32x2_t v = {lo, hi}; const bf16x2_t b = __builtin_convertvector(v, bf16x2_t); return __builtin_bit_cast(unsigned, b); }
;     __device__ __forceinline__ void operator()(const f32x4 (&acc)[2][2][4][2], const Unit& u, int wr, int wc, int fr, int fq, const PG8_LAS float*) const {
;     ...
;             for (int m = 0; m < 4; ++m) { const int row = row0 + ai * HALF + m * 16; const size_t off = (size_t)row * ldc + col0; float ss = 0.f;
; #pragma unroll
;                 for (int bj = 0; bj < 2; ++bj) {
;                     const f32x4 b0 = *(const f32x4*)(base + off + bj * HALF), b1 = *(const f32x4*)(base + off + bj * HALF + 4);
;                     const f32x4 v0 = b0 + acc[ai][bj][m][0], v1 = b1 + acc[ai][bj][m][1];
;                     *(f32x4*)(out + off + bj * HALF) = v0; *(f32x4*)(out + off + bj * HALF + 4) = v1;
;                     if (xb) { u32x4 w; w.x = cvt_pk_bf16(v0[0], v0[1]); w.y = cvt_pk_bf16(v0[2], v0[3]); w.z = cvt_pk_bf16(v1[0], v1[1]); w.w = cvt_pk_bf16(v1[2], v1[3]);
;                         *(u32x4*)(xb + off + bj * HALF) = w;
;                         ss += ((v0[0] * v0[0] + v0[1] * v0[1]) + (v0[2] * v0[2] + v0[3] * v0[3])) + ((v1[0] * v1[0] + v1[1] * v1[1]) + (v1[2] * v1[2] + v1[3] * v1[3])); } }
;                 if (xb) { ss += __shfl_xor(ss, 16); ss += __shfl_xor(ss, 32); if (fq == 0) ssq[(size_t)row * 16 + u.pn * 4 + wc] = ss; } }
	v_pk_add_f32 v[126:127], v[126:127], v[158:159]
	v_pk_add_f32 v[124:125], v[124:125], v[156:157]
	v_pk_add_f32 v[158:159], v[122:123], v[162:163]
	v_pk_add_f32 v[156:157], v[120:121], v[160:161]
	v_cvt_pk_bf16_f32 v120, v124, v125
	v_cvt_pk_bf16_f32 v121, v126, v127
	v_cvt_pk_bf16_f32 v122, v156, v157
	v_cvt_pk_bf16_f32 v123, v158, v159
	v_lshl_add_u64 v[228:229], v[172:173], 0, v[230:231]
	v_lshl_add_u64 v[232:233], v[172:173], 0, v[244:245]
	ds_swizzle_b32 v236, v156 offset:swizzle(SWAP,8)
	ds_swizzle_b32 v237, v157 offset:swizzle(SWAP,8)
	ds_swizzle_b32 v238, v158 offset:swizzle(SWAP,8)
	ds_swizzle_b32 v239, v159 offset:swizzle(SWAP,8)
	ds_swizzle_b32 v240, v124 offset:swizzle(SWAP,8)
	ds_swizzle_b32 v241, v125 offset:swizzle(SWAP,8)
	ds_swizzle_b32 v242, v126 offset:swizzle(SWAP,8)
	ds_swizzle_b32 v243, v127 offset:swizzle(SWAP,8)
	s_waitcnt lgkmcnt(0)
	v_cndmask_b32_e64 v236, v236, v124, s[98:99]
	v_cndmask_b32_e64 v237, v237, v125, s[98:99]
	v_cndmask_b32_e64 v238, v238, v126, s[98:99]
	v_cndmask_b32_e64 v239, v239, v127, s[98:99]
	v_cndmask_b32_e64 v240, v156, v240, s[98:99]
	v_cndmask_b32_e64 v241, v157, v241, s[98:99]
	v_cndmask_b32_e64 v242, v158, v242, s[98:99]
	v_cndmask_b32_e64 v243, v159, v243, s[98:99]
	global_store_dwordx4 v[228:229], v[236:239], off
	global_store_dwordx4 v[232:233], v[240:243], off
	global_store_dwordx4 v[164:165], v[120:123], off
	global_load_dwordx4 v[160:163], v[170:171], off offset:512
	s_nop 0
	global_load_dwordx4 v[168:171], v[170:171], off offset:528
	v_mul_f32_e32 v122, v125, v125
	v_mul_f32_e32 v123, v127, v127
	v_mul_f32_e32 v125, v157, v157
	v_mul_f32_e32 v127, v159, v159
	v_fmac_f32_e32 v122, v124, v124
	v_fmac_f32_e32 v123, v126, v126
	v_fmac_f32_e32 v125, v156, v156
	v_fmac_f32_e32 v127, v158, v158
	v_add_f32_e32 v122, v122, v123
	v_add_f32_e32 v123, v125, v127
	v_add_f32_e32 v126, v122, v123
	v_and_b32_e32 v121, 64, v154
	v_xor_b32_e32 v120, 16, v154
	v_add_u32_e32 v121, 64, v121
	v_cmp_lt_i32_e32 vcc, v120, v121
	s_waitcnt vmcnt(1)
	v_pk_add_f32 v[118:119], v[118:119], v[162:163]
	v_pk_add_f32 v[116:117], v[116:117], v[160:161]
	s_waitcnt vmcnt(0)
	v_pk_add_f32 v[124:125], v[114:115], v[170:171]
	v_pk_add_f32 v[122:123], v[112:113], v[168:169]
	v_mul_f32_e32 v112, v117, v117
	v_mul_f32_e32 v113, v119, v119
	v_mul_f32_e32 v114, v123, v123
	v_mul_f32_e32 v115, v125, v125
	v_fmac_f32_e32 v112, v116, v116
	v_fmac_f32_e32 v113, v118, v118
	v_fmac_f32_e32 v114, v122, v122
	v_fmac_f32_e32 v115, v124, v124
	v_add_f32_e32 v112, v112, v113
	v_add_f32_e32 v113, v114, v115
	v_cndmask_b32_e32 v120, v154, v120, vcc
	v_add_f32_e32 v112, v112, v113
	v_lshlrev_b32_e32 v120, 2, v120
	v_add_f32_e32 v112, v126, v112
	ds_bpermute_b32 v113, v120, v112
	v_cmp_lt_i32_e32 vcc, v155, v121
	v_lshl_add_u64 v[228:229], v[172:173], 0, v[230:231]
	v_lshl_add_u64 v[232:233], v[172:173], 0, v[244:245]
	ds_swizzle_b32 v236, v122 offset:swizzle(SWAP,8)
	ds_swizzle_b32 v237, v123 offset:swizzle(SWAP,8)
	ds_swizzle_b32 v238, v124 offset:swizzle(SWAP,8)
	ds_swizzle_b32 v239, v125 offset:swizzle(SWAP,8)
	ds_swizzle_b32 v240, v116 offset:swizzle(SWAP,8)
	ds_swizzle_b32 v241, v117 offset:swizzle(SWAP,8)
	ds_swizzle_b32 v242, v118 offset:swizzle(SWAP,8)
	ds_swizzle_b32 v243, v119 offset:swizzle(SWAP,8)
	s_waitcnt lgkmcnt(0)
	v_cndmask_b32_e64 v236, v236, v116, s[98:99]
	v_cndmask_b32_e64 v237, v237, v117, s[98:99]
	v_cndmask_b32_e64 v238, v238, v118, s[98:99]
	v_cndmask_b32_e64 v239, v239, v119, s[98:99]
	v_cndmask_b32_e64 v240, v122, v240, s[98:99]
	v_cndmask_b32_e64 v241, v123, v241, s[98:99]
	v_cndmask_b32_e64 v242, v124, v242, s[98:99]
	v_cndmask_b32_e64 v243, v125, v243, s[98:99]
	global_store_dwordx4 v[228:229], v[236:239], off offset:512
	global_store_dwordx4 v[232:233], v[240:243], off offset:512
	v_cndmask_b32_e32 v114, v154, v155, vcc
	v_lshlrev_b32_e32 v114, 2, v114
	s_waitcnt lgkmcnt(0)
	v_add_f32_e32 v112, v112, v113
	ds_bpermute_b32 v113, v114, v112
	v_cvt_pk_bf16_f32 v116, v116, v117
	v_cvt_pk_bf16_f32 v117, v118, v119
	v_cvt_pk_bf16_f32 v118, v122, v123
	v_cvt_pk_bf16_f32 v119, v124, v125
	global_store_dwordx4 v[164:165], v[116:119], off offset:256
	s_and_saveexec_b64 s[24:25], s[2:3]
	s_cbranch_execz .LBB0_663
	v_readlane_b32 s26, v254, 41
	s_waitcnt lgkmcnt(0)
	v_add_f32_e32 v115, v112, v113
	v_lshlrev_b64 v[112:113], 6, v[146:147]
	v_readlane_b32 s27, v254, 42
	s_lshl_b32 s6, s38, 2
	s_nop 0
	v_lshl_add_u64 v[112:113], s[26:27], 0, v[112:113]
	v_lshl_add_u64 v[112:113], s[22:23], 2, v[112:113]
	v_lshl_add_u64 v[112:113], v[112:113], 0, s[6:7]
	global_store_dword v[112:113], v115, off
; __device__ __forceinline__ unsigned cvt_pk_bf16(float lo, float hi) { const f32x2_t v = {lo, hi}; const bf16x2_t b = __builtin_convertvector(v, bf16x2_t); return __builtin_bit_cast(unsigned, b); }
;     __device__ __forceinline__ void operator()(const f32x4 (&acc)[2][2][4][2], const Unit& u, int wr, int wc, int fr, int fq, const PG8_LAS float*) const {
;     ...
;             for (int m = 0; m < 4; ++m) { const int row = row0 + ai * HALF + m * 16; const size_t off = (size_t)row * ldc + col0; float ss = 0.f;
; #pragma unroll
;                 for (int bj = 0; bj < 2; ++bj) {
;                     const f32x4 b0 = *(const f32x4*)(base + off + bj * HALF), b1 = *(const f32x4*)(base + off + bj * HALF + 4);
;                     const f32x4 v0 = b0 + acc[ai][bj][m][0], v1 = b1 + acc[ai][bj][m][1];
;                     *(f32x4*)(out + off + bj * HALF) = v0; *(f32x4*)(out + off + bj * HALF + 4) = v1;
;                     if (xb) { u32x4 w; w.x = cvt_pk_bf16(v0[0], v0[1]); w.y = cvt_pk_bf16(v0[2], v0[3]); w.z = cvt_pk_bf16(v1[0], v1[1]); w.w = cvt_pk_bf16(v1[2], v1[3]);
;                         *(u32x4*)(xb + off + bj * HALF) = w;
;                         ss += ((v0[0] * v0[0] + v0[1] * v0[1]) + (v0[2] * v0[2] + v0[3] * v0[3])) + ((v1[0] * v1[0] + v1[1] * v1[1]) + (v1[2] * v1[2] + v1[3] * v1[3])); } }
;                 if (xb) { ss += __shfl_xor(ss, 16); ss += __shfl_xor(ss, 32); if (fq == 0) ssq[(size_t)row * 16 + u.pn * 4 + wc] = ss; } }
.LBB0_663:
	s_or_b64 exec, exec, s[24:25]
	v_or_b32_e32 v112, 16, v146
	s_waitcnt lgkmcnt(0)
	v_ashrrev_i32_e32 v113, 31, v112
	v_lshlrev_b64 v[116:117], 10, v[112:113]
	v_lshl_add_u64 v[126:127], v[116:117], 0, v[144:145]
	v_readlane_b32 s48, v254, 3
	v_lshlrev_b64 v[156:157], 2, v[126:127]
	v_readlane_b32 s49, v254, 4
	v_readlane_b32 s24, v254, 39
	v_readlane_b32 s25, v254, 40
	v_lshl_add_u64 v[158:159], s[48:49], 0, v[156:157]
	global_load_dwordx4 v[116:119], v[158:159], off
	global_load_dwordx4 v[122:125], v[158:159], off offset:16
	v_lshl_add_u64 v[126:127], v[126:127], 1, s[24:25]
	v_lshl_add_u64 v[156:157], s[68:69], 0, v[156:157]
	v_readlane_b32 s50, v254, 5
	v_readlane_b32 s51, v254, 6
	v_readlane_b32 s52, v254, 7
	v_readlane_b32 s53, v254, 8
	v_readlane_b32 s54, v254, 9
	v_readlane_b32 s55, v254, 10
	v_readlane_b32 s56, v254, 11
	v_readlane_b32 s57, v254, 12
	v_readlane_b32 s58, v254, 13
	v_readlane_b32 s59, v254, 14
	v_readlane_b32 s60, v254, 15
	v_readlane_b32 s61, v254, 16
	v_readlane_b32 s62, v254, 17
	v_readlane_b32 s63, v254, 18
	s_waitcnt vmcnt(1)
	v_pk_add_f32 v[110:111], v[110:111], v[118:119]
	v_pk_add_f32 v[108:109], v[108:109], v[116:117]
	s_waitcnt vmcnt(0)
	v_pk_add_f32 v[106:107], v[106:107], v[124:125]
	v_pk_add_f32 v[104:105], v[104:105], v[122:123]
	v_cvt_pk_bf16_f32 v116, v108, v109
	v_cvt_pk_bf16_f32 v117, v110, v111
	v_cvt_pk_bf16_f32 v118, v104, v105
	v_cvt_pk_bf16_f32 v119, v106, v107
	v_lshl_add_u64 v[228:229], v[156:157], 0, v[230:231]
	v_lshl_add_u64 v[232:233], v[156:157], 0, v[244:245]
	ds_swizzle_b32 v236, v104 offset:swizzle(SWAP,8)
	ds_swizzle_b32 v237, v105 offset:swizzle(SWAP,8)
	ds_swizzle_b32 v238, v106 offset:swizzle(SWAP,8)
	ds_swizzle_b32 v239, v107 offset:swizzle(SWAP,8)
	ds_swizzle_b32 v240, v108 offset:swizzle(SWAP,8)
	ds_swizzle_b32 v241, v109 offset:swizzle(SWAP,8)
	ds_swizzle_b32 v242, v110 offset:swizzle(SWAP,8)
	ds_swizzle_b32 v243, v111 offset:swizzle(SWAP,8)
	s_waitcnt lgkmcnt(0)
	v_cndmask_b32_e64 v236, v236, v108, s[98:99]
	v_cndmask_b32_e64 v237, v237, v109, s[98:99]
	v_cndmask_b32_e64 v238, v238, v110, s[98:99]
	v_cndmask_b32_e64 v239, v239, v111, s[98:99]
	v_cndmask_b32_e64 v240, v104, v240, s[98:99]
	v_cndmask_b32_e64 v241, v105, v241, s[98:99]
	v_cndmask_b32_e64 v242, v106, v242, s[98:99]
	v_cndmask_b32_e64 v243, v107, v243, s[98:99]
	global_store_dwordx4 v[228:229], v[236:239], off
	global_store_dwordx4 v[232:233], v[240:243], off
	global_store_dwordx4 v[126:127], v[116:119], off
	global_load_dwordx4 v[116:119], v[158:159], off offset:512
	s_nop 0
	global_load_dwordx4 v[122:125], v[158:159], off offset:528
	v_mul_f32_e32 v109, v109, v109
	v_mul_f32_e32 v111, v111, v111
	v_mul_f32_e32 v105, v105, v105
	v_mul_f32_e32 v107, v107, v107
	v_fmac_f32_e32 v109, v108, v108
	v_fmac_f32_e32 v111, v110, v110
	v_fmac_f32_e32 v105, v104, v104
	v_fmac_f32_e32 v107, v106, v106
	v_add_f32_e32 v104, v109, v111
	v_add_f32_e32 v105, v105, v107
	v_add_f32_e32 v108, v104, v105
	s_waitcnt vmcnt(1)
	v_pk_add_f32 v[102:103], v[102:103], v[118:119]
	v_pk_add_f32 v[100:101], v[100:101], v[116:117]
	s_waitcnt vmcnt(0)
	v_pk_add_f32 v[106:107], v[98:99], v[124:125]
	v_pk_add_f32 v[104:105], v[96:97], v[122:123]
	v_mul_f32_e32 v96, v101, v101
	v_mul_f32_e32 v97, v103, v103
	v_mul_f32_e32 v98, v105, v105
	v_mul_f32_e32 v99, v107, v107
	v_fmac_f32_e32 v96, v100, v100
	v_fmac_f32_e32 v97, v102, v102
	v_fmac_f32_e32 v98, v104, v104
	v_fmac_f32_e32 v99, v106, v106
	v_add_f32_e32 v96, v96, v97
	v_add_f32_e32 v97, v98, v99
	v_add_f32_e32 v96, v96, v97
	v_add_f32_e32 v96, v108, v96
	ds_bpermute_b32 v97, v120, v96
	v_lshl_add_u64 v[228:229], v[156:157], 0, v[230:231]
	v_lshl_add_u64 v[232:233], v[156:157], 0, v[244:245]
	ds_swizzle_b32 v236, v104 offset:swizzle(SWAP,8)
	ds_swizzle_b32 v237, v105 offset:swizzle(SWAP,8)
	ds_swizzle_b32 v238, v106 offset:swizzle(SWAP,8)
	ds_swizzle_b32 v239, v107 offset:swizzle(SWAP,8)
	ds_swizzle_b32 v240, v100 offset:swizzle(SWAP,8)
	ds_swizzle_b32 v241, v101 offset:swizzle(SWAP,8)
	ds_swizzle_b32 v242, v102 offset:swizzle(SWAP,8)
	ds_swizzle_b32 v243, v103 offset:swizzle(SWAP,8)
	s_waitcnt lgkmcnt(0)
	v_cndmask_b32_e64 v236, v236, v100, s[98:99]
	v_cndmask_b32_e64 v237, v237, v101, s[98:99]
	v_cndmask_b32_e64 v238, v238, v102, s[98:99]
	v_cndmask_b32_e64 v239, v239, v103, s[98:99]
	v_cndmask_b32_e64 v240, v104, v240, s[98:99]
	v_cndmask_b32_e64 v241, v105, v241, s[98:99]
	v_cndmask_b32_e64 v242, v106, v242, s[98:99]
	v_cndmask_b32_e64 v243, v107, v243, s[98:99]
	global_store_dwordx4 v[228:229], v[236:239], off offset:512
	global_store_dwordx4 v[232:233], v[240:243], off offset:512
	v_cvt_pk_bf16_f32 v98, v100, v101
	v_cvt_pk_bf16_f32 v99, v102, v103
	v_cvt_pk_bf16_f32 v100, v104, v105
	s_waitcnt lgkmcnt(0)
	v_add_f32_e32 v96, v96, v97
	ds_bpermute_b32 v97, v114, v96
	v_cvt_pk_bf16_f32 v101, v106, v107
	global_store_dwordx4 v[126:127], v[98:101], off offset:256
	s_and_saveexec_b64 s[24:25], s[2:3]
	s_cbranch_execz .LBB0_665
	v_readlane_b32 s26, v254, 41
	s_waitcnt lgkmcnt(0)
	v_add_f32_e32 v98, v96, v97
	v_lshlrev_b64 v[96:97], 6, v[112:113]
	v_readlane_b32 s27, v254, 42
	s_lshl_b32 s6, s38, 2
	s_nop 0
	v_lshl_add_u64 v[96:97], s[26:27], 0, v[96:97]
	v_lshl_add_u64 v[96:97], s[22:23], 2, v[96:97]
	v_lshl_add_u64 v[96:97], v[96:97], 0, s[6:7]
	global_store_dword v[96:97], v98, off
; __device__ __forceinline__ unsigned cvt_pk_bf16(float lo, float hi) { const f32x2_t v = {lo, hi}; const bf16x2_t b = __builtin_convertvector(v, bf16x2_t); return __builtin_bit_cast(unsigned, b); }
;     __device__ __forceinline__ void operator()(const f32x4 (&acc)[2][2][4][2], const Unit& u, int wr, int wc, int fr, int fq, const PG8_LAS float*) const {
;     ...
;             for (int m = 0; m < 4; ++m) { const int row = row0 + ai * HALF + m * 16; const size_t off = (size_t)row * ldc + col0; float ss = 0.f;
; #pragma unroll
;                 for (int bj = 0; bj < 2; ++bj) {
;                     const f32x4 b0 = *(const f32x4*)(base + off + bj * HALF), b1 = *(const f32x4*)(base + off + bj * HALF + 4);
;                     const f32x4 v0 = b0 + acc[ai][bj][m][0], v1 = b1 + acc[ai][bj][m][1];
;                     *(f32x4*)(out + off + bj * HALF) = v0; *(f32x4*)(out + off + bj * HALF + 4) = v1;
;                     if (xb) { u32x4 w; w.x = cvt_pk_bf16(v0[0], v0[1]); w.y = cvt_pk_bf16(v0[2], v0[3]); w.z = cvt_pk_bf16(v1[0], v1[1]); w.w = cvt_pk_bf16(v1[2], v1[3]);
;                         *(u32x4*)(xb + off + bj * HALF) = w;
;                         ss += ((v0[0] * v0[0] + v0[1] * v0[1]) + (v0[2] * v0[2] + v0[3] * v0[3])) + ((v1[0] * v1[0] + v1[1] * v1[1]) + (v1[2] * v1[2] + v1[3] * v1[3])); } }
;                 if (xb) { ss += __shfl_xor(ss, 16); ss += __shfl_xor(ss, 32); if (fq == 0) ssq[(size_t)row * 16 + u.pn * 4 + wc] = ss; } }
.LBB0_665:
	s_or_b64 exec, exec, s[24:25]
	v_or_b32_e32 v96, 32, v146
	s_waitcnt lgkmcnt(0)
	v_ashrrev_i32_e32 v97, 31, v96
	v_lshlrev_b64 v[98:99], 10, v[96:97]
	v_lshl_add_u64 v[106:107], v[98:99], 0, v[144:145]
	v_readlane_b32 s48, v254, 3
	v_lshlrev_b64 v[108:109], 2, v[106:107]
	v_readlane_b32 s49, v254, 4
	v_readlane_b32 s24, v254, 39
	v_readlane_b32 s25, v254, 40
	v_lshl_add_u64 v[110:111], s[48:49], 0, v[108:109]
	global_load_dwordx4 v[98:101], v[110:111], off
	global_load_dwordx4 v[102:105], v[110:111], off offset:16
	v_lshl_add_u64 v[106:107], v[106:107], 1, s[24:25]
	v_lshl_add_u64 v[108:109], s[68:69], 0, v[108:109]
	v_readlane_b32 s50, v254, 5
	v_readlane_b32 s51, v254, 6
	v_readlane_b32 s52, v254, 7
	v_readlane_b32 s53, v254, 8
	v_readlane_b32 s54, v254, 9
	v_readlane_b32 s55, v254, 10
	v_readlane_b32 s56, v254, 11
	v_readlane_b32 s57, v254, 12
	v_readlane_b32 s58, v254, 13
	v_readlane_b32 s59, v254, 14
	v_readlane_b32 s60, v254, 15
	v_readlane_b32 s61, v254, 16
	v_readlane_b32 s62, v254, 17
	v_readlane_b32 s63, v254, 18
	s_waitcnt vmcnt(1)
	v_pk_add_f32 v[94:95], v[94:95], v[100:101]
	v_pk_add_f32 v[92:93], v[92:93], v[98:99]
	s_waitcnt vmcnt(0)
	v_pk_add_f32 v[90:91], v[90:91], v[104:105]
	v_pk_add_f32 v[88:89], v[88:89], v[102:103]
	v_cvt_pk_bf16_f32 v98, v92, v93
	v_cvt_pk_bf16_f32 v99, v94, v95
	v_cvt_pk_bf16_f32 v100, v88, v89
	v_cvt_pk_bf16_f32 v101, v90, v91
	v_lshl_add_u64 v[228:229], v[108:109], 0, v[230:231]
	v_lshl_add_u64 v[232:233], v[108:109], 0, v[244:245]
	ds_swizzle_b32 v236, v88 offset:swizzle(SWAP,8)
	ds_swizzle_b32 v237, v89 offset:swizzle(SWAP,8)
	ds_swizzle_b32 v238, v90 offset:swizzle(SWAP,8)
	ds_swizzle_b32 v239, v91 offset:swizzle(SWAP,8)
	ds_swizzle_b32 v240, v92 offset:swizzle(SWAP,8)
	ds_swizzle_b32 v241, v93 offset:swizzle(SWAP,8)
	ds_swizzle_b32 v242, v94 offset:swizzle(SWAP,8)
	ds_swizzle_b32 v243, v95 offset:swizzle(SWAP,8)
	s_waitcnt lgkmcnt(0)
	v_cndmask_b32_e64 v236, v236, v92, s[98:99]
	v_cndmask_b32_e64 v237, v237, v93, s[98:99]
	v_cndmask_b32_e64 v238, v238, v94, s[98:99]
	v_cndmask_b32_e64 v239, v239, v95, s[98:99]
	v_cndmask_b32_e64 v240, v88, v240, s[98:99]
	v_cndmask_b32_e64 v241, v89, v241, s[98:99]
	v_cndmask_b32_e64 v242, v90, v242, s[98:99]
	v_cndmask_b32_e64 v243, v91, v243, s[98:99]
	global_store_dwordx4 v[228:229], v[236:239], off
	global_store_dwordx4 v[232:233], v[240:243], off
	global_store_dwordx4 v[106:107], v[98:101], off
	global_load_dwordx4 v[98:101], v[110:111], off offset:512
	s_nop 0
	global_load_dwordx4 v[102:105], v[110:111], off offset:528
	v_mul_f32_e32 v93, v93, v93
	v_mul_f32_e32 v95, v95, v95
	v_mul_f32_e32 v89, v89, v89
	v_mul_f32_e32 v91, v91, v91
	v_fmac_f32_e32 v93, v92, v92
	v_fmac_f32_e32 v95, v94, v94
	v_fmac_f32_e32 v89, v88, v88
	v_fmac_f32_e32 v91, v90, v90
	v_add_f32_e32 v88, v93, v95
	v_add_f32_e32 v89, v89, v91
	v_add_f32_e32 v92, v88, v89
	s_waitcnt vmcnt(1)
	v_pk_add_f32 v[86:87], v[86:87], v[100:101]
	v_pk_add_f32 v[84:85], v[84:85], v[98:99]
	s_waitcnt vmcnt(0)
	v_pk_add_f32 v[90:91], v[82:83], v[104:105]
	v_pk_add_f32 v[88:89], v[80:81], v[102:103]
	v_mul_f32_e32 v80, v85, v85
	v_mul_f32_e32 v81, v87, v87
	v_mul_f32_e32 v82, v89, v89
	v_mul_f32_e32 v83, v91, v91
	v_fmac_f32_e32 v80, v84, v84
	v_fmac_f32_e32 v81, v86, v86
	v_fmac_f32_e32 v82, v88, v88
	v_fmac_f32_e32 v83, v90, v90
	v_add_f32_e32 v80, v80, v81
	v_add_f32_e32 v81, v82, v83
	v_add_f32_e32 v80, v80, v81
	v_add_f32_e32 v80, v92, v80
	ds_bpermute_b32 v81, v120, v80
	v_lshl_add_u64 v[228:229], v[108:109], 0, v[230:231]
	v_lshl_add_u64 v[232:233], v[108:109], 0, v[244:245]
	ds_swizzle_b32 v236, v88 offset:swizzle(SWAP,8)
	ds_swizzle_b32 v237, v89 offset:swizzle(SWAP,8)
	ds_swizzle_b32 v238, v90 offset:swizzle(SWAP,8)
	ds_swizzle_b32 v239, v91 offset:swizzle(SWAP,8)
	ds_swizzle_b32 v240, v84 offset:swizzle(SWAP,8)
	ds_swizzle_b32 v241, v85 offset:swizzle(SWAP,8)
	ds_swizzle_b32 v242, v86 offset:swizzle(SWAP,8)
	ds_swizzle_b32 v243, v87 offset:swizzle(SWAP,8)
	s_waitcnt lgkmcnt(0)
	v_cndmask_b32_e64 v236, v236, v84, s[98:99]
	v_cndmask_b32_e64 v237, v237, v85, s[98:99]
	v_cndmask_b32_e64 v238, v238, v86, s[98:99]
	v_cndmask_b32_e64 v239, v239, v87, s[98:99]
	v_cndmask_b32_e64 v240, v88, v240, s[98:99]
	v_cndmask_b32_e64 v241, v89, v241, s[98:99]
	v_cndmask_b32_e64 v242, v90, v242, s[98:99]
	v_cndmask_b32_e64 v243, v91, v243, s[98:99]
	global_store_dwordx4 v[228:229], v[236:239], off offset:512
	global_store_dwordx4 v[232:233], v[240:243], off offset:512
	v_cvt_pk_bf16_f32 v82, v84, v85
	v_cvt_pk_bf16_f32 v83, v86, v87
	v_cvt_pk_bf16_f32 v84, v88, v89
	s_waitcnt lgkmcnt(0)
	v_add_f32_e32 v80, v80, v81
	ds_bpermute_b32 v81, v114, v80
	v_cvt_pk_bf16_f32 v85, v90, v91
	global_store_dwordx4 v[106:107], v[82:85], off offset:256
	s_and_saveexec_b64 s[24:25], s[2:3]
	s_cbranch_execz .LBB0_667
	v_readlane_b32 s26, v254, 41
	s_waitcnt lgkmcnt(0)
	v_add_f32_e32 v82, v80, v81
	v_lshlrev_b64 v[80:81], 6, v[96:97]
	v_readlane_b32 s27, v254, 42
	s_lshl_b32 s6, s38, 2
	s_nop 0
	v_lshl_add_u64 v[80:81], s[26:27], 0, v[80:81]
	v_lshl_add_u64 v[80:81], s[22:23], 2, v[80:81]
	v_lshl_add_u64 v[80:81], v[80:81], 0, s[6:7]
	global_store_dword v[80:81], v82, off
; __device__ __forceinline__ unsigned cvt_pk_bf16(float lo, float hi) { const f32x2_t v = {lo, hi}; const bf16x2_t b = __builtin_convertvector(v, bf16x2_t); return __builtin_bit_cast(unsigned, b); }
;     __device__ __forceinline__ void operator()(const f32x4 (&acc)[2][2][4][2], const Unit& u, int wr, int wc, int fr, int fq, const PG8_LAS float*) const {
;     ...
;             for (int m = 0; m < 4; ++m) { const int row = row0 + ai * HALF + m * 16; const size_t off = (size_t)row * ldc + col0; float ss = 0.f;
; #pragma unroll
;                 for (int bj = 0; bj < 2; ++bj) {
;                     const f32x4 b0 = *(const f32x4*)(base + off + bj * HALF), b1 = *(const f32x4*)(base + off + bj * HALF + 4);
;                     const f32x4 v0 = b0 + acc[ai][bj][m][0], v1 = b1 + acc[ai][bj][m][1];
;                     *(f32x4*)(out + off + bj * HALF) = v0; *(f32x4*)(out + off + bj * HALF + 4) = v1;
;                     if (xb) { u32x4 w; w.x = cvt_pk_bf16(v0[0], v0[1]); w.y = cvt_pk_bf16(v0[2], v0[3]); w.z = cvt_pk_bf16(v1[0], v1[1]); w.w = cvt_pk_bf16(v1[2], v1[3]);
;                         *(u32x4*)(xb + off + bj * HALF) = w;
;                         ss += ((v0[0] * v0[0] + v0[1] * v0[1]) + (v0[2] * v0[2] + v0[3] * v0[3])) + ((v1[0] * v1[0] + v1[1] * v1[1]) + (v1[2] * v1[2] + v1[3] * v1[3])); } }
;                 if (xb) { ss += __shfl_xor(ss, 16); ss += __shfl_xor(ss, 32); if (fq == 0) ssq[(size_t)row * 16 + u.pn * 4 + wc] = ss; } }
.LBB0_667:
	s_or_b64 exec, exec, s[24:25]
	v_or_b32_e32 v80, 48, v146
	s_waitcnt lgkmcnt(0)
	v_ashrrev_i32_e32 v81, 31, v80
	v_lshlrev_b64 v[82:83], 10, v[80:81]
	v_lshl_add_u64 v[90:91], v[82:83], 0, v[144:145]
	v_readlane_b32 s48, v254, 3
	v_lshlrev_b64 v[92:93], 2, v[90:91]
	v_readlane_b32 s49, v254, 4
	v_readlane_b32 s24, v254, 39
	v_readlane_b32 s25, v254, 40
	v_lshl_add_u64 v[94:95], s[48:49], 0, v[92:93]
	global_load_dwordx4 v[82:85], v[94:95], off
	global_load_dwordx4 v[86:89], v[94:95], off offset:16
	v_lshl_add_u64 v[90:91], v[90:91], 1, s[24:25]
	v_lshl_add_u64 v[92:93], s[68:69], 0, v[92:93]
	v_readlane_b32 s50, v254, 5
	v_readlane_b32 s51, v254, 6
	v_readlane_b32 s52, v254, 7
	v_readlane_b32 s53, v254, 8
	v_readlane_b32 s54, v254, 9
	v_readlane_b32 s55, v254, 10
	v_readlane_b32 s56, v254, 11
	v_readlane_b32 s57, v254, 12
	v_readlane_b32 s58, v254, 13
	v_readlane_b32 s59, v254, 14
	v_readlane_b32 s60, v254, 15
	v_readlane_b32 s61, v254, 16
	v_readlane_b32 s62, v254, 17
	v_readlane_b32 s63, v254, 18
	s_waitcnt vmcnt(1)
	v_pk_add_f32 v[78:79], v[78:79], v[84:85]
	v_pk_add_f32 v[76:77], v[76:77], v[82:83]
	s_waitcnt vmcnt(0)
	v_pk_add_f32 v[74:75], v[74:75], v[88:89]
	v_pk_add_f32 v[72:73], v[72:73], v[86:87]
	v_cvt_pk_bf16_f32 v82, v76, v77
	v_cvt_pk_bf16_f32 v83, v78, v79
	v_cvt_pk_bf16_f32 v84, v72, v73
	v_cvt_pk_bf16_f32 v85, v74, v75
	v_lshl_add_u64 v[228:229], v[92:93], 0, v[230:231]
	v_lshl_add_u64 v[232:233], v[92:93], 0, v[244:245]
	ds_swizzle_b32 v236, v72 offset:swizzle(SWAP,8)
	ds_swizzle_b32 v237, v73 offset:swizzle(SWAP,8)
	ds_swizzle_b32 v238, v74 offset:swizzle(SWAP,8)
	ds_swizzle_b32 v239, v75 offset:swizzle(SWAP,8)
	ds_swizzle_b32 v240, v76 offset:swizzle(SWAP,8)
	ds_swizzle_b32 v241, v77 offset:swizzle(SWAP,8)
	ds_swizzle_b32 v242, v78 offset:swizzle(SWAP,8)
	ds_swizzle_b32 v243, v79 offset:swizzle(SWAP,8)
	s_waitcnt lgkmcnt(0)
	v_cndmask_b32_e64 v236, v236, v76, s[98:99]
	v_cndmask_b32_e64 v237, v237, v77, s[98:99]
	v_cndmask_b32_e64 v238, v238, v78, s[98:99]
	v_cndmask_b32_e64 v239, v239, v79, s[98:99]
	v_cndmask_b32_e64 v240, v72, v240, s[98:99]
	v_cndmask_b32_e64 v241, v73, v241, s[98:99]
	v_cndmask_b32_e64 v242, v74, v242, s[98:99]
	v_cndmask_b32_e64 v243, v75, v243, s[98:99]
	global_store_dwordx4 v[228:229], v[236:239], off
	global_store_dwordx4 v[232:233], v[240:243], off
	global_store_dwordx4 v[90:91], v[82:85], off
	global_load_dwordx4 v[82:85], v[94:95], off offset:512
	s_nop 0
	global_load_dwordx4 v[86:89], v[94:95], off offset:528
	v_mul_f32_e32 v77, v77, v77
	v_mul_f32_e32 v79, v79, v79
	v_mul_f32_e32 v73, v73, v73
	v_mul_f32_e32 v75, v75, v75
	v_fmac_f32_e32 v77, v76, v76
	v_fmac_f32_e32 v79, v78, v78
	v_fmac_f32_e32 v73, v72, v72
	v_fmac_f32_e32 v75, v74, v74
	v_add_f32_e32 v72, v77, v79
	v_add_f32_e32 v73, v73, v75
	v_add_f32_e32 v76, v72, v73
	s_waitcnt vmcnt(1)
	v_pk_add_f32 v[70:71], v[70:71], v[84:85]
	v_pk_add_f32 v[68:69], v[68:69], v[82:83]
	s_waitcnt vmcnt(0)
	v_pk_add_f32 v[74:75], v[66:67], v[88:89]
	v_pk_add_f32 v[72:73], v[64:65], v[86:87]
	v_mul_f32_e32 v64, v69, v69
	v_mul_f32_e32 v65, v71, v71
	v_mul_f32_e32 v66, v73, v73
	v_mul_f32_e32 v67, v75, v75
	v_fmac_f32_e32 v64, v68, v68
	v_fmac_f32_e32 v65, v70, v70
	v_fmac_f32_e32 v66, v72, v72
	v_fmac_f32_e32 v67, v74, v74
	v_add_f32_e32 v64, v64, v65
	v_add_f32_e32 v65, v66, v67
	v_add_f32_e32 v64, v64, v65
	v_add_f32_e32 v64, v76, v64
	ds_bpermute_b32 v65, v120, v64
	v_lshl_add_u64 v[228:229], v[92:93], 0, v[230:231]
	v_lshl_add_u64 v[232:233], v[92:93], 0, v[244:245]
	ds_swizzle_b32 v236, v72 offset:swizzle(SWAP,8)
	ds_swizzle_b32 v237, v73 offset:swizzle(SWAP,8)
	ds_swizzle_b32 v238, v74 offset:swizzle(SWAP,8)
	ds_swizzle_b32 v239, v75 offset:swizzle(SWAP,8)
	ds_swizzle_b32 v240, v68 offset:swizzle(SWAP,8)
	ds_swizzle_b32 v241, v69 offset:swizzle(SWAP,8)
	ds_swizzle_b32 v242, v70 offset:swizzle(SWAP,8)
	ds_swizzle_b32 v243, v71 offset:swizzle(SWAP,8)
	s_waitcnt lgkmcnt(0)
	v_cndmask_b32_e64 v236, v236, v68, s[98:99]
	v_cndmask_b32_e64 v237, v237, v69, s[98:99]
	v_cndmask_b32_e64 v238, v238, v70, s[98:99]
	v_cndmask_b32_e64 v239, v239, v71, s[98:99]
	v_cndmask_b32_e64 v240, v72, v240, s[98:99]
	v_cndmask_b32_e64 v241, v73, v241, s[98:99]
	v_cndmask_b32_e64 v242, v74, v242, s[98:99]
	v_cndmask_b32_e64 v243, v75, v243, s[98:99]
	global_store_dwordx4 v[228:229], v[236:239], off offset:512
	global_store_dwordx4 v[232:233], v[240:243], off offset:512
	v_cvt_pk_bf16_f32 v66, v68, v69
	v_cvt_pk_bf16_f32 v67, v70, v71
	v_cvt_pk_bf16_f32 v68, v72, v73
	s_waitcnt lgkmcnt(0)
	v_add_f32_e32 v64, v64, v65
	ds_bpermute_b32 v65, v114, v64
	v_cvt_pk_bf16_f32 v69, v74, v75
	global_store_dwordx4 v[90:91], v[66:69], off offset:256
	s_and_saveexec_b64 s[24:25], s[2:3]
	s_cbranch_execz .LBB0_669
	v_readlane_b32 s26, v254, 41
	s_waitcnt lgkmcnt(0)
	v_add_f32_e32 v66, v64, v65
	v_lshlrev_b64 v[64:65], 6, v[80:81]
	v_readlane_b32 s27, v254, 42
	s_lshl_b32 s6, s38, 2
	s_nop 0
	v_lshl_add_u64 v[64:65], s[26:27], 0, v[64:65]
	v_lshl_add_u64 v[64:65], s[22:23], 2, v[64:65]
	v_lshl_add_u64 v[64:65], v[64:65], 0, s[6:7]
	global_store_dword v[64:65], v66, off
; __device__ __forceinline__ unsigned cvt_pk_bf16(float lo, float hi) { const f32x2_t v = {lo, hi}; const bf16x2_t b = __builtin_convertvector(v, bf16x2_t); return __builtin_bit_cast(unsigned, b); }
;     __device__ __forceinline__ void operator()(const f32x4 (&acc)[2][2][4][2], const Unit& u, int wr, int wc, int fr, int fq, const PG8_LAS float*) const {
;     ...
;             for (int m = 0; m < 4; ++m) { const int row = row0 + ai * HALF + m * 16; const size_t off = (size_t)row * ldc + col0; float ss = 0.f;
; #pragma unroll
;                 for (int bj = 0; bj < 2; ++bj) {
;                     const f32x4 b0 = *(const f32x4*)(base + off + bj * HALF), b1 = *(const f32x4*)(base + off + bj * HALF + 4);
;                     const f32x4 v0 = b0 + acc[ai][bj][m][0], v1 = b1 + acc[ai][bj][m][1];
;                     *(f32x4*)(out + off + bj * HALF) = v0; *(f32x4*)(out + off + bj * HALF + 4) = v1;
;                     if (xb) { u32x4 w; w.x = cvt_pk_bf16(v0[0], v0[1]); w.y = cvt_pk_bf16(v0[2], v0[3]); w.z = cvt_pk_bf16(v1[0], v1[1]); w.w = cvt_pk_bf16(v1[2], v1[3]);
;                         *(u32x4*)(xb + off + bj * HALF) = w;
;                         ss += ((v0[0] * v0[0] + v0[1] * v0[1]) + (v0[2] * v0[2] + v0[3] * v0[3])) + ((v1[0] * v1[0] + v1[1] * v1[1]) + (v1[2] * v1[2] + v1[3] * v1[3])); } }
;                 if (xb) { ss += __shfl_xor(ss, 16); ss += __shfl_xor(ss, 32); if (fq == 0) ssq[(size_t)row * 16 + u.pn * 4 + wc] = ss; } }
.LBB0_669:
	s_or_b64 exec, exec, s[24:25]
	v_add_u32_e32 v64, 0x80, v146
	s_waitcnt lgkmcnt(0)
	v_ashrrev_i32_e32 v65, 31, v64
	v_lshlrev_b64 v[66:67], 10, v[64:65]
	v_lshl_add_u64 v[74:75], v[66:67], 0, v[144:145]
	v_readlane_b32 s48, v254, 3
	v_lshlrev_b64 v[76:77], 2, v[74:75]
	v_readlane_b32 s49, v254, 4
	v_readlane_b32 s24, v254, 39
	v_readlane_b32 s25, v254, 40
	v_lshl_add_u64 v[78:79], s[48:49], 0, v[76:77]
	global_load_dwordx4 v[66:69], v[78:79], off
	global_load_dwordx4 v[70:73], v[78:79], off offset:16
	v_lshl_add_u64 v[74:75], v[74:75], 1, s[24:25]
	v_lshl_add_u64 v[76:77], s[68:69], 0, v[76:77]
	v_readlane_b32 s50, v254, 5
	v_readlane_b32 s51, v254, 6
	v_readlane_b32 s52, v254, 7
	v_readlane_b32 s53, v254, 8
	v_readlane_b32 s54, v254, 9
	v_readlane_b32 s55, v254, 10
	v_readlane_b32 s56, v254, 11
	v_readlane_b32 s57, v254, 12
	v_readlane_b32 s58, v254, 13
	v_readlane_b32 s59, v254, 14
	v_readlane_b32 s60, v254, 15
	v_readlane_b32 s61, v254, 16
	v_readlane_b32 s62, v254, 17
	v_readlane_b32 s63, v254, 18
	s_waitcnt vmcnt(1)
	v_pk_add_f32 v[62:63], v[62:63], v[68:69]
	v_pk_add_f32 v[60:61], v[60:61], v[66:67]
	s_waitcnt vmcnt(0)
	v_pk_add_f32 v[58:59], v[58:59], v[72:73]
	v_pk_add_f32 v[56:57], v[56:57], v[70:71]
	v_cvt_pk_bf16_f32 v66, v60, v61
	v_cvt_pk_bf16_f32 v67, v62, v63
	v_cvt_pk_bf16_f32 v68, v56, v57
	v_cvt_pk_bf16_f32 v69, v58, v59
	v_lshl_add_u64 v[228:229], v[76:77], 0, v[230:231]
	v_lshl_add_u64 v[232:233], v[76:77], 0, v[244:245]
	ds_swizzle_b32 v236, v56 offset:swizzle(SWAP,8)
	ds_swizzle_b32 v237, v57 offset:swizzle(SWAP,8)
	ds_swizzle_b32 v238, v58 offset:swizzle(SWAP,8)
	ds_swizzle_b32 v239, v59 offset:swizzle(SWAP,8)
	ds_swizzle_b32 v240, v60 offset:swizzle(SWAP,8)
	ds_swizzle_b32 v241, v61 offset:swizzle(SWAP,8)
	ds_swizzle_b32 v242, v62 offset:swizzle(SWAP,8)
	ds_swizzle_b32 v243, v63 offset:swizzle(SWAP,8)
	s_waitcnt lgkmcnt(0)
	v_cndmask_b32_e64 v236, v236, v60, s[98:99]
	v_cndmask_b32_e64 v237, v237, v61, s[98:99]
	v_cndmask_b32_e64 v238, v238, v62, s[98:99]
	v_cndmask_b32_e64 v239, v239, v63, s[98:99]
	v_cndmask_b32_e64 v240, v56, v240, s[98:99]
	v_cndmask_b32_e64 v241, v57, v241, s[98:99]
	v_cndmask_b32_e64 v242, v58, v242, s[98:99]
	v_cndmask_b32_e64 v243, v59, v243, s[98:99]
	global_store_dwordx4 v[228:229], v[236:239], off
	global_store_dwordx4 v[232:233], v[240:243], off
	global_store_dwordx4 v[74:75], v[66:69], off
	global_load_dwordx4 v[66:69], v[78:79], off offset:512
	s_nop 0
	global_load_dwordx4 v[70:73], v[78:79], off offset:528
	v_mul_f32_e32 v61, v61, v61
	v_mul_f32_e32 v63, v63, v63
	v_mul_f32_e32 v57, v57, v57
	v_mul_f32_e32 v59, v59, v59
	v_fmac_f32_e32 v61, v60, v60
	v_fmac_f32_e32 v63, v62, v62
	v_fmac_f32_e32 v57, v56, v56
	v_fmac_f32_e32 v59, v58, v58
	v_add_f32_e32 v56, v61, v63
	v_add_f32_e32 v57, v57, v59
	v_add_f32_e32 v60, v56, v57
	s_waitcnt vmcnt(1)
	v_pk_add_f32 v[54:55], v[54:55], v[68:69]
	v_pk_add_f32 v[52:53], v[52:53], v[66:67]
	s_waitcnt vmcnt(0)
	v_pk_add_f32 v[58:59], v[50:51], v[72:73]
	v_pk_add_f32 v[56:57], v[48:49], v[70:71]
	v_mul_f32_e32 v48, v53, v53
	v_mul_f32_e32 v49, v55, v55
	v_mul_f32_e32 v50, v57, v57
	v_mul_f32_e32 v51, v59, v59
	v_fmac_f32_e32 v48, v52, v52
	v_fmac_f32_e32 v49, v54, v54
	v_fmac_f32_e32 v50, v56, v56
	v_fmac_f32_e32 v51, v58, v58
	v_add_f32_e32 v48, v48, v49
	v_add_f32_e32 v49, v50, v51
	v_add_f32_e32 v48, v48, v49
	v_add_f32_e32 v48, v60, v48
	ds_bpermute_b32 v49, v120, v48
	v_lshl_add_u64 v[228:229], v[76:77], 0, v[230:231]
	v_lshl_add_u64 v[232:233], v[76:77], 0, v[244:245]
	ds_swizzle_b32 v236, v56 offset:swizzle(SWAP,8)
	ds_swizzle_b32 v237, v57 offset:swizzle(SWAP,8)
	ds_swizzle_b32 v238, v58 offset:swizzle(SWAP,8)
	ds_swizzle_b32 v239, v59 offset:swizzle(SWAP,8)
	ds_swizzle_b32 v240, v52 offset:swizzle(SWAP,8)
	ds_swizzle_b32 v241, v53 offset:swizzle(SWAP,8)
	ds_swizzle_b32 v242, v54 offset:swizzle(SWAP,8)
	ds_swizzle_b32 v243, v55 offset:swizzle(SWAP,8)
	s_waitcnt lgkmcnt(0)
	v_cndmask_b32_e64 v236, v236, v52, s[98:99]
	v_cndmask_b32_e64 v237, v237, v53, s[98:99]
	v_cndmask_b32_e64 v238, v238, v54, s[98:99]
	v_cndmask_b32_e64 v239, v239, v55, s[98:99]
	v_cndmask_b32_e64 v240, v56, v240, s[98:99]
	v_cndmask_b32_e64 v241, v57, v241, s[98:99]
	v_cndmask_b32_e64 v242, v58, v242, s[98:99]
	v_cndmask_b32_e64 v243, v59, v243, s[98:99]
	global_store_dwordx4 v[228:229], v[236:239], off offset:512
	global_store_dwordx4 v[232:233], v[240:243], off offset:512
	v_cvt_pk_bf16_f32 v50, v52, v53
	v_cvt_pk_bf16_f32 v51, v54, v55
	v_cvt_pk_bf16_f32 v52, v56, v57
	s_waitcnt lgkmcnt(0)
	v_add_f32_e32 v48, v48, v49
	ds_bpermute_b32 v49, v114, v48
	v_cvt_pk_bf16_f32 v53, v58, v59
	global_store_dwordx4 v[74:75], v[50:53], off offset:256
	s_and_saveexec_b64 s[24:25], s[2:3]
	s_cbranch_execz .LBB0_671
	v_readlane_b32 s26, v254, 41
	s_waitcnt lgkmcnt(0)
	v_add_f32_e32 v50, v48, v49
	v_lshlrev_b64 v[48:49], 6, v[64:65]
	v_readlane_b32 s27, v254, 42
	s_lshl_b32 s6, s38, 2
	s_nop 0
	v_lshl_add_u64 v[48:49], s[26:27], 0, v[48:49]
	v_lshl_add_u64 v[48:49], s[22:23], 2, v[48:49]
	v_lshl_add_u64 v[48:49], v[48:49], 0, s[6:7]
	global_store_dword v[48:49], v50, off
; __device__ __forceinline__ unsigned cvt_pk_bf16(float lo, float hi) { const f32x2_t v = {lo, hi}; const bf16x2_t b = __builtin_convertvector(v, bf16x2_t); return __builtin_bit_cast(unsigned, b); }
;     __device__ __forceinline__ void operator()(const f32x4 (&acc)[2][2][4][2], const Unit& u, int wr, int wc, int fr, int fq, const PG8_LAS float*) const {
;     ...
;             for (int m = 0; m < 4; ++m) { const int row = row0 + ai * HALF + m * 16; const size_t off = (size_t)row * ldc + col0; float ss = 0.f;
; #pragma unroll
;                 for (int bj = 0; bj < 2; ++bj) {
;                     const f32x4 b0 = *(const f32x4*)(base + off + bj * HALF), b1 = *(const f32x4*)(base + off + bj * HALF + 4);
;                     const f32x4 v0 = b0 + acc[ai][bj][m][0], v1 = b1 + acc[ai][bj][m][1];
;                     *(f32x4*)(out + off + bj * HALF) = v0; *(f32x4*)(out + off + bj * HALF + 4) = v1;
;                     if (xb) { u32x4 w; w.x = cvt_pk_bf16(v0[0], v0[1]); w.y = cvt_pk_bf16(v0[2], v0[3]); w.z = cvt_pk_bf16(v1[0], v1[1]); w.w = cvt_pk_bf16(v1[2], v1[3]);
;                         *(u32x4*)(xb + off + bj * HALF) = w;
;                         ss += ((v0[0] * v0[0] + v0[1] * v0[1]) + (v0[2] * v0[2] + v0[3] * v0[3])) + ((v1[0] * v1[0] + v1[1] * v1[1]) + (v1[2] * v1[2] + v1[3] * v1[3])); } }
;                 if (xb) { ss += __shfl_xor(ss, 16); ss += __shfl_xor(ss, 32); if (fq == 0) ssq[(size_t)row * 16 + u.pn * 4 + wc] = ss; } }
.LBB0_671:
	s_or_b64 exec, exec, s[24:25]
	v_add_u32_e32 v48, 0x90, v146
	s_waitcnt lgkmcnt(0)
	v_ashrrev_i32_e32 v49, 31, v48
	v_lshlrev_b64 v[50:51], 10, v[48:49]
	v_lshl_add_u64 v[58:59], v[50:51], 0, v[144:145]
	v_readlane_b32 s48, v254, 3
	v_lshlrev_b64 v[60:61], 2, v[58:59]
	v_readlane_b32 s49, v254, 4
	v_readlane_b32 s24, v254, 39
	v_readlane_b32 s25, v254, 40
	v_lshl_add_u64 v[62:63], s[48:49], 0, v[60:61]
	global_load_dwordx4 v[50:53], v[62:63], off
	global_load_dwordx4 v[54:57], v[62:63], off offset:16
	v_lshl_add_u64 v[58:59], v[58:59], 1, s[24:25]
	v_lshl_add_u64 v[60:61], s[68:69], 0, v[60:61]
	v_readlane_b32 s50, v254, 5
	v_readlane_b32 s51, v254, 6
	v_readlane_b32 s52, v254, 7
	v_readlane_b32 s53, v254, 8
	v_readlane_b32 s54, v254, 9
	v_readlane_b32 s55, v254, 10
	v_readlane_b32 s56, v254, 11
	v_readlane_b32 s57, v254, 12
	v_readlane_b32 s58, v254, 13
	v_readlane_b32 s59, v254, 14
	v_readlane_b32 s60, v254, 15
	v_readlane_b32 s61, v254, 16
	v_readlane_b32 s62, v254, 17
	v_readlane_b32 s63, v254, 18
	s_waitcnt vmcnt(1)
	v_pk_add_f32 v[46:47], v[46:47], v[52:53]
	v_pk_add_f32 v[44:45], v[44:45], v[50:51]
	s_waitcnt vmcnt(0)
	v_pk_add_f32 v[42:43], v[42:43], v[56:57]
	v_pk_add_f32 v[40:41], v[40:41], v[54:55]
	v_cvt_pk_bf16_f32 v50, v44, v45
	v_cvt_pk_bf16_f32 v51, v46, v47
	v_cvt_pk_bf16_f32 v52, v40, v41
	v_cvt_pk_bf16_f32 v53, v42, v43
	v_lshl_add_u64 v[228:229], v[60:61], 0, v[230:231]
	v_lshl_add_u64 v[232:233], v[60:61], 0, v[244:245]
	ds_swizzle_b32 v236, v40 offset:swizzle(SWAP,8)
	ds_swizzle_b32 v237, v41 offset:swizzle(SWAP,8)
	ds_swizzle_b32 v238, v42 offset:swizzle(SWAP,8)
	ds_swizzle_b32 v239, v43 offset:swizzle(SWAP,8)
	ds_swizzle_b32 v240, v44 offset:swizzle(SWAP,8)
	ds_swizzle_b32 v241, v45 offset:swizzle(SWAP,8)
	ds_swizzle_b32 v242, v46 offset:swizzle(SWAP,8)
	ds_swizzle_b32 v243, v47 offset:swizzle(SWAP,8)
	s_waitcnt lgkmcnt(0)
	v_cndmask_b32_e64 v236, v236, v44, s[98:99]
	v_cndmask_b32_e64 v237, v237, v45, s[98:99]
	v_cndmask_b32_e64 v238, v238, v46, s[98:99]
	v_cndmask_b32_e64 v239, v239, v47, s[98:99]
	v_cndmask_b32_e64 v240, v40, v240, s[98:99]
	v_cndmask_b32_e64 v241, v41, v241, s[98:99]
	v_cndmask_b32_e64 v242, v42, v242, s[98:99]
	v_cndmask_b32_e64 v243, v43, v243, s[98:99]
	global_store_dwordx4 v[228:229], v[236:239], off
	global_store_dwordx4 v[232:233], v[240:243], off
	global_store_dwordx4 v[58:59], v[50:53], off
	global_load_dwordx4 v[50:53], v[62:63], off offset:512
	s_nop 0
	global_load_dwordx4 v[54:57], v[62:63], off offset:528
	v_mul_f32_e32 v45, v45, v45
	v_mul_f32_e32 v47, v47, v47
	v_mul_f32_e32 v41, v41, v41
	v_mul_f32_e32 v43, v43, v43
	v_fmac_f32_e32 v45, v44, v44
	v_fmac_f32_e32 v47, v46, v46
	v_fmac_f32_e32 v41, v40, v40
	v_fmac_f32_e32 v43, v42, v42
	v_add_f32_e32 v40, v45, v47
	v_add_f32_e32 v41, v41, v43
	v_add_f32_e32 v44, v40, v41
	s_waitcnt vmcnt(1)
	v_pk_add_f32 v[38:39], v[38:39], v[52:53]
	v_pk_add_f32 v[36:37], v[36:37], v[50:51]
	s_waitcnt vmcnt(0)
	v_pk_add_f32 v[42:43], v[34:35], v[56:57]
	v_pk_add_f32 v[40:41], v[32:33], v[54:55]
	v_mul_f32_e32 v32, v37, v37
	v_mul_f32_e32 v33, v39, v39
	v_mul_f32_e32 v34, v41, v41
	v_mul_f32_e32 v35, v43, v43
	v_fmac_f32_e32 v32, v36, v36
	v_fmac_f32_e32 v33, v38, v38
	v_fmac_f32_e32 v34, v40, v40
	v_fmac_f32_e32 v35, v42, v42
	v_add_f32_e32 v32, v32, v33
	v_add_f32_e32 v33, v34, v35
	v_add_f32_e32 v32, v32, v33
	v_add_f32_e32 v32, v44, v32
	ds_bpermute_b32 v33, v120, v32
	v_lshl_add_u64 v[228:229], v[60:61], 0, v[230:231]
	v_lshl_add_u64 v[232:233], v[60:61], 0, v[244:245]
	ds_swizzle_b32 v236, v40 offset:swizzle(SWAP,8)
	ds_swizzle_b32 v237, v41 offset:swizzle(SWAP,8)
	ds_swizzle_b32 v238, v42 offset:swizzle(SWAP,8)
	ds_swizzle_b32 v239, v43 offset:swizzle(SWAP,8)
	ds_swizzle_b32 v240, v36 offset:swizzle(SWAP,8)
	ds_swizzle_b32 v241, v37 offset:swizzle(SWAP,8)
	ds_swizzle_b32 v242, v38 offset:swizzle(SWAP,8)
	ds_swizzle_b32 v243, v39 offset:swizzle(SWAP,8)
	s_waitcnt lgkmcnt(0)
	v_cndmask_b32_e64 v236, v236, v36, s[98:99]
	v_cndmask_b32_e64 v237, v237, v37, s[98:99]
	v_cndmask_b32_e64 v238, v238, v38, s[98:99]
	v_cndmask_b32_e64 v239, v239, v39, s[98:99]
	v_cndmask_b32_e64 v240, v40, v240, s[98:99]
	v_cndmask_b32_e64 v241, v41, v241, s[98:99]
	v_cndmask_b32_e64 v242, v42, v242, s[98:99]
	v_cndmask_b32_e64 v243, v43, v243, s[98:99]
	global_store_dwordx4 v[228:229], v[236:239], off offset:512
	global_store_dwordx4 v[232:233], v[240:243], off offset:512
	v_cvt_pk_bf16_f32 v34, v36, v37
	v_cvt_pk_bf16_f32 v35, v38, v39
	v_cvt_pk_bf16_f32 v36, v40, v41
	s_waitcnt lgkmcnt(0)
	v_add_f32_e32 v32, v32, v33
	ds_bpermute_b32 v33, v114, v32
	v_cvt_pk_bf16_f32 v37, v42, v43
	global_store_dwordx4 v[58:59], v[34:37], off offset:256
	s_and_saveexec_b64 s[24:25], s[2:3]
	s_cbranch_execz .LBB0_673
	v_readlane_b32 s26, v254, 41
	s_waitcnt lgkmcnt(0)
	v_add_f32_e32 v34, v32, v33
	v_lshlrev_b64 v[32:33], 6, v[48:49]
	v_readlane_b32 s27, v254, 42
	s_lshl_b32 s6, s38, 2
	s_nop 0
	v_lshl_add_u64 v[32:33], s[26:27], 0, v[32:33]
	v_lshl_add_u64 v[32:33], s[22:23], 2, v[32:33]
	v_lshl_add_u64 v[32:33], v[32:33], 0, s[6:7]
	global_store_dword v[32:33], v34, off
; __device__ __forceinline__ unsigned cvt_pk_bf16(float lo, float hi) { const f32x2_t v = {lo, hi}; const bf16x2_t b = __builtin_convertvector(v, bf16x2_t); return __builtin_bit_cast(unsigned, b); }
;     __device__ __forceinline__ void operator()(const f32x4 (&acc)[2][2][4][2], const Unit& u, int wr, int wc, int fr, int fq, const PG8_LAS float*) const {
;     ...
;             for (int m = 0; m < 4; ++m) { const int row = row0 + ai * HALF + m * 16; const size_t off = (size_t)row * ldc + col0; float ss = 0.f;
; #pragma unroll
;                 for (int bj = 0; bj < 2; ++bj) {
;                     const f32x4 b0 = *(const f32x4*)(base + off + bj * HALF), b1 = *(const f32x4*)(base + off + bj * HALF + 4);
;                     const f32x4 v0 = b0 + acc[ai][bj][m][0], v1 = b1 + acc[ai][bj][m][1];
;                     *(f32x4*)(out + off + bj * HALF) = v0; *(f32x4*)(out + off + bj * HALF + 4) = v1;
;                     if (xb) { u32x4 w; w.x = cvt_pk_bf16(v0[0], v0[1]); w.y = cvt_pk_bf16(v0[2], v0[3]); w.z = cvt_pk_bf16(v1[0], v1[1]); w.w = cvt_pk_bf16(v1[2], v1[3]);
;                         *(u32x4*)(xb + off + bj * HALF) = w;
;                         ss += ((v0[0] * v0[0] + v0[1] * v0[1]) + (v0[2] * v0[2] + v0[3] * v0[3])) + ((v1[0] * v1[0] + v1[1] * v1[1]) + (v1[2] * v1[2] + v1[3] * v1[3])); } }
;                 if (xb) { ss += __shfl_xor(ss, 16); ss += __shfl_xor(ss, 32); if (fq == 0) ssq[(size_t)row * 16 + u.pn * 4 + wc] = ss; } }
.LBB0_673:
	s_or_b64 exec, exec, s[24:25]
	v_add_u32_e32 v32, 0xa0, v146
	s_waitcnt lgkmcnt(0)
	v_ashrrev_i32_e32 v33, 31, v32
	v_lshlrev_b64 v[34:35], 10, v[32:33]
	v_lshl_add_u64 v[42:43], v[34:35], 0, v[144:145]
	v_readlane_b32 s48, v254, 3
	v_lshlrev_b64 v[44:45], 2, v[42:43]
	v_readlane_b32 s49, v254, 4
	v_readlane_b32 s24, v254, 39
	v_readlane_b32 s25, v254, 40
	v_lshl_add_u64 v[46:47], s[48:49], 0, v[44:45]
	global_load_dwordx4 v[34:37], v[46:47], off
	global_load_dwordx4 v[38:41], v[46:47], off offset:16
	v_lshl_add_u64 v[42:43], v[42:43], 1, s[24:25]
	v_lshl_add_u64 v[44:45], s[68:69], 0, v[44:45]
	v_readlane_b32 s50, v254, 5
	v_readlane_b32 s51, v254, 6
	v_readlane_b32 s52, v254, 7
	v_readlane_b32 s53, v254, 8
	v_readlane_b32 s54, v254, 9
	v_readlane_b32 s55, v254, 10
	v_readlane_b32 s56, v254, 11
	v_readlane_b32 s57, v254, 12
	v_readlane_b32 s58, v254, 13
	v_readlane_b32 s59, v254, 14
	v_readlane_b32 s60, v254, 15
	v_readlane_b32 s61, v254, 16
	v_readlane_b32 s62, v254, 17
	v_readlane_b32 s63, v254, 18
	s_waitcnt vmcnt(1)
	v_pk_add_f32 v[30:31], v[30:31], v[36:37]
	v_pk_add_f32 v[28:29], v[28:29], v[34:35]
	s_waitcnt vmcnt(0)
	v_pk_add_f32 v[26:27], v[26:27], v[40:41]
	v_pk_add_f32 v[24:25], v[24:25], v[38:39]
	v_cvt_pk_bf16_f32 v34, v28, v29
	v_cvt_pk_bf16_f32 v35, v30, v31
	v_cvt_pk_bf16_f32 v36, v24, v25
	v_cvt_pk_bf16_f32 v37, v26, v27
	v_lshl_add_u64 v[228:229], v[44:45], 0, v[230:231]
	v_lshl_add_u64 v[232:233], v[44:45], 0, v[244:245]
	ds_swizzle_b32 v236, v24 offset:swizzle(SWAP,8)
	ds_swizzle_b32 v237, v25 offset:swizzle(SWAP,8)
	ds_swizzle_b32 v238, v26 offset:swizzle(SWAP,8)
	ds_swizzle_b32 v239, v27 offset:swizzle(SWAP,8)
	ds_swizzle_b32 v240, v28 offset:swizzle(SWAP,8)
	ds_swizzle_b32 v241, v29 offset:swizzle(SWAP,8)
	ds_swizzle_b32 v242, v30 offset:swizzle(SWAP,8)
	ds_swizzle_b32 v243, v31 offset:swizzle(SWAP,8)
	s_waitcnt lgkmcnt(0)
	v_cndmask_b32_e64 v236, v236, v28, s[98:99]
	v_cndmask_b32_e64 v237, v237, v29, s[98:99]
	v_cndmask_b32_e64 v238, v238, v30, s[98:99]
	v_cndmask_b32_e64 v239, v239, v31, s[98:99]
	v_cndmask_b32_e64 v240, v24, v240, s[98:99]
	v_cndmask_b32_e64 v241, v25, v241, s[98:99]
	v_cndmask_b32_e64 v242, v26, v242, s[98:99]
	v_cndmask_b32_e64 v243, v27, v243, s[98:99]
	global_store_dwordx4 v[228:229], v[236:239], off
	global_store_dwordx4 v[232:233], v[240:243], off
	global_store_dwordx4 v[42:43], v[34:37], off
	global_load_dwordx4 v[34:37], v[46:47], off offset:512
	s_nop 0
	global_load_dwordx4 v[38:41], v[46:47], off offset:528
	v_mul_f32_e32 v29, v29, v29
	v_mul_f32_e32 v31, v31, v31
	v_mul_f32_e32 v25, v25, v25
	v_mul_f32_e32 v27, v27, v27
	v_fmac_f32_e32 v29, v28, v28
	v_fmac_f32_e32 v31, v30, v30
	v_fmac_f32_e32 v25, v24, v24
	v_fmac_f32_e32 v27, v26, v26
	v_add_f32_e32 v24, v29, v31
	v_add_f32_e32 v25, v25, v27
	v_add_f32_e32 v28, v24, v25
	s_waitcnt vmcnt(1)
	v_pk_add_f32 v[22:23], v[22:23], v[36:37]
	v_pk_add_f32 v[20:21], v[20:21], v[34:35]
	s_waitcnt vmcnt(0)
	v_pk_add_f32 v[26:27], v[18:19], v[40:41]
	v_pk_add_f32 v[24:25], v[16:17], v[38:39]
	v_mul_f32_e32 v16, v21, v21
	v_mul_f32_e32 v17, v23, v23
	v_mul_f32_e32 v18, v25, v25
	v_mul_f32_e32 v19, v27, v27
	v_fmac_f32_e32 v16, v20, v20
	v_fmac_f32_e32 v17, v22, v22
	v_fmac_f32_e32 v18, v24, v24
	v_fmac_f32_e32 v19, v26, v26
	v_add_f32_e32 v16, v16, v17
	v_add_f32_e32 v17, v18, v19
	v_add_f32_e32 v16, v16, v17
	v_add_f32_e32 v16, v28, v16
	ds_bpermute_b32 v17, v120, v16
	v_lshl_add_u64 v[228:229], v[44:45], 0, v[230:231]
	v_lshl_add_u64 v[232:233], v[44:45], 0, v[244:245]
	ds_swizzle_b32 v236, v24 offset:swizzle(SWAP,8)
	ds_swizzle_b32 v237, v25 offset:swizzle(SWAP,8)
	ds_swizzle_b32 v238, v26 offset:swizzle(SWAP,8)
	ds_swizzle_b32 v239, v27 offset:swizzle(SWAP,8)
	ds_swizzle_b32 v240, v20 offset:swizzle(SWAP,8)
	ds_swizzle_b32 v241, v21 offset:swizzle(SWAP,8)
	ds_swizzle_b32 v242, v22 offset:swizzle(SWAP,8)
	ds_swizzle_b32 v243, v23 offset:swizzle(SWAP,8)
	s_waitcnt lgkmcnt(0)
	v_cndmask_b32_e64 v236, v236, v20, s[98:99]
	v_cndmask_b32_e64 v237, v237, v21, s[98:99]
	v_cndmask_b32_e64 v238, v238, v22, s[98:99]
	v_cndmask_b32_e64 v239, v239, v23, s[98:99]
	v_cndmask_b32_e64 v240, v24, v240, s[98:99]
	v_cndmask_b32_e64 v241, v25, v241, s[98:99]
	v_cndmask_b32_e64 v242, v26, v242, s[98:99]
	v_cndmask_b32_e64 v243, v27, v243, s[98:99]
	global_store_dwordx4 v[228:229], v[236:239], off offset:512
	global_store_dwordx4 v[232:233], v[240:243], off offset:512
	v_cvt_pk_bf16_f32 v18, v20, v21
	v_cvt_pk_bf16_f32 v19, v22, v23
	v_cvt_pk_bf16_f32 v20, v24, v25
	s_waitcnt lgkmcnt(0)
	v_add_f32_e32 v16, v16, v17
	ds_bpermute_b32 v17, v114, v16
	v_cvt_pk_bf16_f32 v21, v26, v27
	global_store_dwordx4 v[42:43], v[18:21], off offset:256
	s_and_saveexec_b64 s[24:25], s[2:3]
	s_cbranch_execz .LBB0_675
	v_readlane_b32 s26, v254, 41
	s_waitcnt lgkmcnt(0)
	v_add_f32_e32 v18, v16, v17
	v_lshlrev_b64 v[16:17], 6, v[32:33]
	v_readlane_b32 s27, v254, 42
	s_lshl_b32 s6, s38, 2
	s_nop 0
	v_lshl_add_u64 v[16:17], s[26:27], 0, v[16:17]
	v_lshl_add_u64 v[16:17], s[22:23], 2, v[16:17]
	v_lshl_add_u64 v[16:17], v[16:17], 0, s[6:7]
	global_store_dword v[16:17], v18, off
; __device__ __forceinline__ unsigned cvt_pk_bf16(float lo, float hi) { const f32x2_t v = {lo, hi}; const bf16x2_t b = __builtin_convertvector(v, bf16x2_t); return __builtin_bit_cast(unsigned, b); }
;     __device__ __forceinline__ void operator()(const f32x4 (&acc)[2][2][4][2], const Unit& u, int wr, int wc, int fr, int fq, const PG8_LAS float*) const {
;     ...
;             for (int m = 0; m < 4; ++m) { const int row = row0 + ai * HALF + m * 16; const size_t off = (size_t)row * ldc + col0; float ss = 0.f;
; #pragma unroll
;                 for (int bj = 0; bj < 2; ++bj) {
;                     const f32x4 b0 = *(const f32x4*)(base + off + bj * HALF), b1 = *(const f32x4*)(base + off + bj * HALF + 4);
;                     const f32x4 v0 = b0 + acc[ai][bj][m][0], v1 = b1 + acc[ai][bj][m][1];
;                     *(f32x4*)(out + off + bj * HALF) = v0; *(f32x4*)(out + off + bj * HALF + 4) = v1;
;                     if (xb) { u32x4 w; w.x = cvt_pk_bf16(v0[0], v0[1]); w.y = cvt_pk_bf16(v0[2], v0[3]); w.z = cvt_pk_bf16(v1[0], v1[1]); w.w = cvt_pk_bf16(v1[2], v1[3]);
;                         *(u32x4*)(xb + off + bj * HALF) = w;
;                         ss += ((v0[0] * v0[0] + v0[1] * v0[1]) + (v0[2] * v0[2] + v0[3] * v0[3])) + ((v1[0] * v1[0] + v1[1] * v1[1]) + (v1[2] * v1[2] + v1[3] * v1[3])); } }
;                 if (xb) { ss += __shfl_xor(ss, 16); ss += __shfl_xor(ss, 32); if (fq == 0) ssq[(size_t)row * 16 + u.pn * 4 + wc] = ss; } }
.LBB0_675:
	s_or_b64 exec, exec, s[24:25]
	v_add_u32_e32 v16, 0xb0, v146
	s_waitcnt lgkmcnt(0)
	v_ashrrev_i32_e32 v17, 31, v16
	v_lshlrev_b64 v[18:19], 10, v[16:17]
	v_lshl_add_u64 v[26:27], v[18:19], 0, v[144:145]
	v_readlane_b32 s48, v254, 3
	v_lshlrev_b64 v[28:29], 2, v[26:27]
	v_readlane_b32 s49, v254, 4
	v_readlane_b32 s24, v254, 39
	v_readlane_b32 s25, v254, 40
	v_lshl_add_u64 v[30:31], s[48:49], 0, v[28:29]
	global_load_dwordx4 v[18:21], v[30:31], off
	global_load_dwordx4 v[22:25], v[30:31], off offset:16
	v_lshl_add_u64 v[26:27], v[26:27], 1, s[24:25]
	v_lshl_add_u64 v[28:29], s[68:69], 0, v[28:29]
	v_readlane_b32 s50, v254, 5
	v_readlane_b32 s51, v254, 6
	v_readlane_b32 s52, v254, 7
	v_readlane_b32 s53, v254, 8
	v_readlane_b32 s54, v254, 9
	v_readlane_b32 s55, v254, 10
	v_readlane_b32 s56, v254, 11
	v_readlane_b32 s57, v254, 12
	v_readlane_b32 s58, v254, 13
	v_readlane_b32 s59, v254, 14
	v_readlane_b32 s60, v254, 15
	v_readlane_b32 s61, v254, 16
	v_readlane_b32 s62, v254, 17
	v_readlane_b32 s63, v254, 18
	s_waitcnt vmcnt(1)
	v_pk_add_f32 v[14:15], v[14:15], v[20:21]
	v_pk_add_f32 v[12:13], v[12:13], v[18:19]
	s_waitcnt vmcnt(0)
	v_pk_add_f32 v[10:11], v[10:11], v[24:25]
	v_pk_add_f32 v[8:9], v[8:9], v[22:23]
	v_cvt_pk_bf16_f32 v18, v12, v13
	v_cvt_pk_bf16_f32 v19, v14, v15
	v_cvt_pk_bf16_f32 v20, v8, v9
	v_cvt_pk_bf16_f32 v21, v10, v11
	v_lshl_add_u64 v[228:229], v[28:29], 0, v[230:231]
	v_lshl_add_u64 v[232:233], v[28:29], 0, v[244:245]
	ds_swizzle_b32 v236, v8 offset:swizzle(SWAP,8)
	ds_swizzle_b32 v237, v9 offset:swizzle(SWAP,8)
	ds_swizzle_b32 v238, v10 offset:swizzle(SWAP,8)
	ds_swizzle_b32 v239, v11 offset:swizzle(SWAP,8)
	ds_swizzle_b32 v240, v12 offset:swizzle(SWAP,8)
	ds_swizzle_b32 v241, v13 offset:swizzle(SWAP,8)
	ds_swizzle_b32 v242, v14 offset:swizzle(SWAP,8)
	ds_swizzle_b32 v243, v15 offset:swizzle(SWAP,8)
	s_waitcnt lgkmcnt(0)
	v_cndmask_b32_e64 v236, v236, v12, s[98:99]
	v_cndmask_b32_e64 v237, v237, v13, s[98:99]
	v_cndmask_b32_e64 v238, v238, v14, s[98:99]
	v_cndmask_b32_e64 v239, v239, v15, s[98:99]
	v_cndmask_b32_e64 v240, v8, v240, s[98:99]
	v_cndmask_b32_e64 v241, v9, v241, s[98:99]
	v_cndmask_b32_e64 v242, v10, v242, s[98:99]
	v_cndmask_b32_e64 v243, v11, v243, s[98:99]
	global_store_dwordx4 v[228:229], v[236:239], off
	global_store_dwordx4 v[232:233], v[240:243], off
	global_store_dwordx4 v[26:27], v[18:21], off
	global_load_dwordx4 v[18:21], v[30:31], off offset:512
	s_nop 0
	global_load_dwordx4 v[22:25], v[30:31], off offset:528
	v_mul_f32_e32 v13, v13, v13
	v_mul_f32_e32 v15, v15, v15
	v_mul_f32_e32 v9, v9, v9
	v_mul_f32_e32 v11, v11, v11
	v_fmac_f32_e32 v13, v12, v12
	v_fmac_f32_e32 v15, v14, v14
	v_fmac_f32_e32 v9, v8, v8
	v_fmac_f32_e32 v11, v10, v10
	v_add_f32_e32 v8, v13, v15
	v_add_f32_e32 v9, v9, v11
	v_add_f32_e32 v12, v8, v9
	s_waitcnt vmcnt(1)
	v_pk_add_f32 v[6:7], v[6:7], v[20:21]
	v_pk_add_f32 v[4:5], v[4:5], v[18:19]
	s_waitcnt vmcnt(0)
	v_pk_add_f32 v[10:11], v[2:3], v[24:25]
	v_pk_add_f32 v[8:9], v[0:1], v[22:23]
	v_mul_f32_e32 v0, v5, v5
	v_mul_f32_e32 v1, v7, v7
	v_mul_f32_e32 v2, v9, v9
	v_mul_f32_e32 v3, v11, v11
	v_fmac_f32_e32 v0, v4, v4
	v_fmac_f32_e32 v1, v6, v6
	v_fmac_f32_e32 v2, v8, v8
	v_fmac_f32_e32 v3, v10, v10
	v_add_f32_e32 v0, v0, v1
	v_add_f32_e32 v1, v2, v3
	v_add_f32_e32 v0, v0, v1
	v_add_f32_e32 v0, v12, v0
	ds_bpermute_b32 v1, v120, v0
	v_lshl_add_u64 v[228:229], v[28:29], 0, v[230:231]
	v_lshl_add_u64 v[232:233], v[28:29], 0, v[244:245]
	ds_swizzle_b32 v236, v8 offset:swizzle(SWAP,8)
	ds_swizzle_b32 v237, v9 offset:swizzle(SWAP,8)
	ds_swizzle_b32 v238, v10 offset:swizzle(SWAP,8)
	ds_swizzle_b32 v239, v11 offset:swizzle(SWAP,8)
	ds_swizzle_b32 v240, v4 offset:swizzle(SWAP,8)
	ds_swizzle_b32 v241, v5 offset:swizzle(SWAP,8)
	ds_swizzle_b32 v242, v6 offset:swizzle(SWAP,8)
	ds_swizzle_b32 v243, v7 offset:swizzle(SWAP,8)
	s_waitcnt lgkmcnt(0)
	v_cndmask_b32_e64 v236, v236, v4, s[98:99]
	v_cndmask_b32_e64 v237, v237, v5, s[98:99]
	v_cndmask_b32_e64 v238, v238, v6, s[98:99]
	v_cndmask_b32_e64 v239, v239, v7, s[98:99]
	v_cndmask_b32_e64 v240, v8, v240, s[98:99]
	v_cndmask_b32_e64 v241, v9, v241, s[98:99]
	v_cndmask_b32_e64 v242, v10, v242, s[98:99]
	v_cndmask_b32_e64 v243, v11, v243, s[98:99]
	global_store_dwordx4 v[228:229], v[236:239], off offset:512
	global_store_dwordx4 v[232:233], v[240:243], off offset:512
	v_cvt_pk_bf16_f32 v2, v4, v5
	v_cvt_pk_bf16_f32 v3, v6, v7
	v_cvt_pk_bf16_f32 v4, v8, v9
	s_waitcnt lgkmcnt(0)
	v_add_f32_e32 v0, v0, v1
	ds_bpermute_b32 v1, v114, v0
	v_cvt_pk_bf16_f32 v5, v10, v11
	global_store_dwordx4 v[26:27], v[2:5], off offset:256
	s_and_saveexec_b64 s[24:25], s[2:3]
	s_cbranch_execz .LBB0_677
	v_readlane_b32 s26, v254, 41
	s_waitcnt lgkmcnt(0)
	v_add_f32_e32 v2, v0, v1
	v_lshlrev_b64 v[0:1], 6, v[16:17]
	v_readlane_b32 s27, v254, 42
	s_lshl_b32 s6, s38, 2
	s_nop 0
	v_lshl_add_u64 v[0:1], s[26:27], 0, v[0:1]
	v_lshl_add_u64 v[0:1], s[22:23], 2, v[0:1]
	v_lshl_add_u64 v[0:1], v[0:1], 0, s[6:7]
	global_store_dword v[0:1], v2, off

; #define PG8_STAGE(bufoff, gbase, voff) do { _Pragma("unroll") for (int _i = 0; _i < 2; ++_i) \
;         __builtin_amdgcn_global_load_lds((const unsigned*)((const char*)(gbase) + (voff)[_i]), (PG8_LAS unsigned*)(lds + (bufoff) + ldsw + _i * 8192), 16, 0, 0); } while (0)
; #define PG8_LDA(dst, b, h) do { _Pragma("unroll") for (int m = 0; m < 4; ++m) _Pragma("unroll") for (int k = 0; k < 2; ++k) dst[m][k] = *(const PG8_LAS bf16x8*)(lds + PG8_SA(b, h) + aoff + m * 2048 + k * 1024); } while (0)
; #define PG8_LDB(dst, b, h) do { _Pragma("unroll") for (int n = 0; n < 2; ++n) _Pragma("unroll") for (int k = 0; k < 2; ++k) dst[n][k] = *(const PG8_LAS bf16x8*)(lds + PG8_SB(b, h) + boff + n * 2048 + k * 1024); } while (0)
; #define PG8_MMA(ai, bj, At, Bt) do { __builtin_amdgcn_s_setprio(1); _Pragma("unroll") for (int m = 0; m < 4; ++m) _Pragma("unroll") for (int n = 0; n < 2; ++n) _Pragma("unroll") for (int k = 0; k < 2; ++k) \
;         acc[ai][bj][m][n] = __builtin_amdgcn_mfma_f32_16x16x32_bf16(Bt[n][k], At[m][k], acc[ai][bj][m][n], 0, 0, 0); __builtin_amdgcn_s_setprio(0); } while (0)
; #define PG8_WAIT_V(n) asm volatile("s_waitcnt vmcnt(" #n ")" ::: "memory")
; #define PG8_WAIT_L(n) asm volatile("s_waitcnt lgkmcnt(" #n ")" ::: "memory")
; #define PG8_BAR __builtin_amdgcn_s_barrier()
; #define PG8_SCHED __builtin_amdgcn_sched_barrier(0)
; template <class Epi, class Sched, bool ALIGN_EPI = false, bool SP2 = false>
; __device__ __forceinline__ void gemm_phase(PG8_LAS unsigned char* lds, const Gemm g, const Sched& S, const Epi& E) {
;     ...
;             PG8_LDB(B0, 0, 0); PG8_LDB(B1, 0, 1); PG8_SCHED; PG8_LDA(At, 0, 0); PG8_STAGE(PG8_SA(1, 1), a1 + hstep, voffA);
;             PG8_WAIT_V(8); PG8_WAIT_L(0); PG8_BAR; PG8_MMA(0, 0, At, B0); PG8_MMA(0, 1, At, B1); PG8_BAR; PG8_SCHED;
;             PG8_LDA(At, 0, 1); PG8_STAGE(PG8_SB(0, 0), b2, voffB); PG8_STAGE(PG8_SB(0, 1), b2 + hstep, voffB); PG8_STAGE(PG8_SA(0, 0), a2, voffA);
;             PG8_WAIT_V(8); PG8_WAIT_L(0); PG8_BAR; PG8_MMA(1, 0, At, B0); PG8_MMA(1, 1, At, B1); PG8_BAR; PG8_SCHED;
;             PG8_LDB(B0, 1, 0); PG8_LDB(B1, 1, 1); PG8_SCHED; PG8_LDA(At, 1, 0); PG8_STAGE(PG8_SA(0, 1), a2 + hstep, voffA);
.LBB0_842:
	ds_read_b128 v[144:147], v151
	ds_read_b128 v[156:159], v151 offset:1024
	ds_read_b128 v[160:163], v151 offset:2048
	ds_read_b128 v[168:171], v151 offset:3072
	ds_read_b128 v[172:175], v152
	ds_read_b128 v[176:179], v152 offset:1024
	ds_read_b128 v[180:183], v152 offset:2048
	ds_read_b128 v[184:187], v152 offset:3072
	s_add_u32 s26, s24, 0xfff00080
	s_addc_u32 s27, s25, -1
	s_cmp_eq_u32 s50, 60
	s_cselect_b32 s29, s17, s27
	s_cselect_b32 s28, s23, s26
	s_cselect_b32 s27, s15, s49
	s_cselect_b32 s26, s47, s48
	v_lshl_add_u64 v[164:165], s[24:25], 0, v[136:137]
	s_add_i32 m0, s34, 0xc000
	ds_read_b128 v[188:191], v153
	ds_read_b128 v[192:195], v153 offset:1024
	ds_read_b128 v[196:199], v153 offset:2048
	ds_read_b128 v[200:203], v153 offset:3072
	ds_read_b128 v[204:207], v153 offset:4096
	ds_read_b128 v[208:211], v153 offset:5120
	ds_read_b128 v[212:215], v153 offset:6144
	ds_read_b128 v[216:219], v153 offset:7168
	global_load_lds_dwordx4 v[164:165], off
	v_lshl_add_u64 v[164:165], s[24:25], 0, v[138:139]
	s_add_i32 m0, s34, 0xe000
	s_nop 0
	global_load_lds_dwordx4 v[164:165], off
	s_waitcnt vmcnt(8)
	s_waitcnt lgkmcnt(0)
	s_barrier
	s_setprio 1
	s_waitcnt lgkmcnt(0)
	v_mfma_f32_16x16x32_bf16 v[124:127], v[144:147], v[188:191], v[124:127]
	v_mfma_f32_16x16x32_bf16 v[120:123], v[160:163], v[188:191], v[120:123]
	v_mfma_f32_16x16x32_bf16 v[108:111], v[144:147], v[196:199], v[108:111]
	v_mfma_f32_16x16x32_bf16 v[104:107], v[160:163], v[196:199], v[104:107]
	v_mfma_f32_16x16x32_bf16 v[92:95], v[144:147], v[204:207], v[92:95]
	v_mfma_f32_16x16x32_bf16 v[88:91], v[160:163], v[204:207], v[88:91]
	v_mfma_f32_16x16x32_bf16 v[76:79], v[144:147], v[212:215], v[76:79]
	v_mfma_f32_16x16x32_bf16 v[72:75], v[160:163], v[212:215], v[72:75]
	v_mfma_f32_16x16x32_bf16 v[124:127], v[156:159], v[192:195], v[124:127]
	v_mfma_f32_16x16x32_bf16 v[120:123], v[168:171], v[192:195], v[120:123]
	v_mfma_f32_16x16x32_bf16 v[108:111], v[156:159], v[200:203], v[108:111]
	v_mfma_f32_16x16x32_bf16 v[104:107], v[168:171], v[200:203], v[104:107]
	v_mfma_f32_16x16x32_bf16 v[92:95], v[156:159], v[208:211], v[92:95]
	v_mfma_f32_16x16x32_bf16 v[88:91], v[168:171], v[208:211], v[88:91]
	v_mfma_f32_16x16x32_bf16 v[76:79], v[156:159], v[216:219], v[76:79]
	v_mfma_f32_16x16x32_bf16 v[72:75], v[168:171], v[216:219], v[72:75]
	s_setprio 0
	s_setprio 1
	v_mfma_f32_16x16x32_bf16 v[116:119], v[172:175], v[188:191], v[116:119]
	v_mfma_f32_16x16x32_bf16 v[112:115], v[180:183], v[188:191], v[112:115]
	v_mfma_f32_16x16x32_bf16 v[100:103], v[172:175], v[196:199], v[100:103]
	v_mfma_f32_16x16x32_bf16 v[96:99], v[180:183], v[196:199], v[96:99]
	v_mfma_f32_16x16x32_bf16 v[84:87], v[172:175], v[204:207], v[84:87]
	v_mfma_f32_16x16x32_bf16 v[80:83], v[180:183], v[204:207], v[80:83]
	v_mfma_f32_16x16x32_bf16 v[68:71], v[172:175], v[212:215], v[68:71]
	v_mfma_f32_16x16x32_bf16 v[64:67], v[180:183], v[212:215], v[64:67]
	v_mfma_f32_16x16x32_bf16 v[116:119], v[176:179], v[192:195], v[116:119]
	v_mfma_f32_16x16x32_bf16 v[112:115], v[184:187], v[192:195], v[112:115]
	v_mfma_f32_16x16x32_bf16 v[100:103], v[176:179], v[200:203], v[100:103]
	v_mfma_f32_16x16x32_bf16 v[96:99], v[184:187], v[200:203], v[96:99]
	v_mfma_f32_16x16x32_bf16 v[84:87], v[176:179], v[208:211], v[84:87]
	v_mfma_f32_16x16x32_bf16 v[80:83], v[184:187], v[208:211], v[80:83]
	v_mfma_f32_16x16x32_bf16 v[68:71], v[176:179], v[216:219], v[68:71]
	v_mfma_f32_16x16x32_bf16 v[64:67], v[184:187], v[216:219], v[64:67]
	s_setprio 0
	s_barrier
	s_add_i32 s51, s44, s33
	v_lshl_add_u64 v[164:165], s[26:27], 0, v[130:131]
	s_mov_b32 m0, s51
	ds_read_b128 v[188:191], v153 offset:16384
	ds_read_b128 v[192:195], v153 offset:17408
	ds_read_b128 v[196:199], v153 offset:18432
	ds_read_b128 v[200:203], v153 offset:19456
	ds_read_b128 v[204:207], v153 offset:20480
	ds_read_b128 v[208:211], v153 offset:21504
	ds_read_b128 v[212:215], v153 offset:22528
	ds_read_b128 v[216:219], v153 offset:23552
	global_load_lds_dwordx4 v[164:165], off
	s_add_i32 m0, s51, 0x2000
	s_add_u32 s52, s26, 0x100000
	v_lshl_add_u64 v[220:221], s[26:27], 0, v[134:135]
	s_addc_u32 s53, s27, 0
	s_add_i32 s51, s45, s33
	global_load_lds_dwordx4 v[220:221], off
	v_lshl_add_u64 v[222:223], s[52:53], 0, v[130:131]
	s_mov_b32 m0, s51
	v_lshl_add_u64 v[224:225], s[28:29], 0, v[132:133]
	global_load_lds_dwordx4 v[222:223], off
	v_lshl_add_u64 v[222:223], s[52:53], 0, v[134:135]
	s_add_i32 m0, s51, 0x2000
	s_nop 0
	global_load_lds_dwordx4 v[222:223], off
	v_lshl_add_u64 v[222:223], s[28:29], 0, v[128:129]
	s_mov_b32 m0, s34
	s_nop 0
	global_load_lds_dwordx4 v[222:223], off
	s_mov_b32 m0, s35
	s_nop 0
	global_load_lds_dwordx4 v[224:225], off
	s_waitcnt vmcnt(8)
	s_waitcnt lgkmcnt(0)
	s_barrier
; #define PG8_STAGE(bufoff, gbase, voff) do { _Pragma("unroll") for (int _i = 0; _i < 2; ++_i) \
;         __builtin_amdgcn_global_load_lds((const unsigned*)((const char*)(gbase) + (voff)[_i]), (PG8_LAS unsigned*)(lds + (bufoff) + ldsw + _i * 8192), 16, 0, 0); } while (0)
; #define PG8_LDA(dst, b, h) do { _Pragma("unroll") for (int m = 0; m < 4; ++m) _Pragma("unroll") for (int k = 0; k < 2; ++k) dst[m][k] = *(const PG8_LAS bf16x8*)(lds + PG8_SA(b, h) + aoff + m * 2048 + k * 1024); } while (0)
; #define PG8_LDB(dst, b, h) do { _Pragma("unroll") for (int n = 0; n < 2; ++n) _Pragma("unroll") for (int k = 0; k < 2; ++k) dst[n][k] = *(const PG8_LAS bf16x8*)(lds + PG8_SB(b, h) + boff + n * 2048 + k * 1024); } while (0)
; #define PG8_MMA(ai, bj, At, Bt) do { __builtin_amdgcn_s_setprio(1); _Pragma("unroll") for (int m = 0; m < 4; ++m) _Pragma("unroll") for (int n = 0; n < 2; ++n) _Pragma("unroll") for (int k = 0; k < 2; ++k) \
;         acc[ai][bj][m][n] = __builtin_amdgcn_mfma_f32_16x16x32_bf16(Bt[n][k], At[m][k], acc[ai][bj][m][n], 0, 0, 0); __builtin_amdgcn_s_setprio(0); } while (0)
; #define PG8_WAIT_V(n) asm volatile("s_waitcnt vmcnt(" #n ")" ::: "memory")
; #define PG8_WAIT_L(n) asm volatile("s_waitcnt lgkmcnt(" #n ")" ::: "memory")
; #define PG8_BAR __builtin_amdgcn_s_barrier()
; #define PG8_SCHED __builtin_amdgcn_sched_barrier(0)
; template <class Epi, class Sched, bool ALIGN_EPI = false, bool SP2 = false>
; __device__ __forceinline__ void gemm_phase(PG8_LAS unsigned char* lds, const Gemm g, const Sched& S, const Epi& E) {
;     ...
;             PG8_WAIT_V(8); PG8_WAIT_L(0); PG8_BAR; PG8_MMA(1, 0, At, B0); PG8_MMA(1, 1, At, B1); PG8_BAR; PG8_SCHED;
;             PG8_LDB(B0, 1, 0); PG8_LDB(B1, 1, 1); PG8_SCHED; PG8_LDA(At, 1, 0); PG8_STAGE(PG8_SA(0, 1), a2 + hstep, voffA);
;             PG8_WAIT_V(8); PG8_WAIT_L(0); PG8_BAR; PG8_MMA(0, 0, At, B0); PG8_MMA(0, 1, At, B1); PG8_BAR; PG8_SCHED;
;             PG8_LDA(At, 1, 1); PG8_STAGE(PG8_SB(1, 0), b3, voffB); PG8_STAGE(PG8_SB(1, 1), b3 + hstep, voffB); PG8_STAGE(PG8_SA(1, 0), a3, voffA);
	s_setprio 1
	s_waitcnt lgkmcnt(0)
	v_mfma_f32_16x16x32_bf16 v[60:63], v[144:147], v[188:191], v[60:63]
	v_mfma_f32_16x16x32_bf16 v[56:59], v[160:163], v[188:191], v[56:59]
	v_mfma_f32_16x16x32_bf16 v[44:47], v[144:147], v[196:199], v[44:47]
	v_mfma_f32_16x16x32_bf16 v[40:43], v[160:163], v[196:199], v[40:43]
	v_mfma_f32_16x16x32_bf16 v[28:31], v[144:147], v[204:207], v[28:31]
	v_mfma_f32_16x16x32_bf16 v[24:27], v[160:163], v[204:207], v[24:27]
	v_mfma_f32_16x16x32_bf16 v[12:15], v[144:147], v[212:215], v[12:15]
	v_mfma_f32_16x16x32_bf16 v[8:11], v[160:163], v[212:215], v[8:11]
	v_mfma_f32_16x16x32_bf16 v[60:63], v[156:159], v[192:195], v[60:63]
	v_mfma_f32_16x16x32_bf16 v[56:59], v[168:171], v[192:195], v[56:59]
	v_mfma_f32_16x16x32_bf16 v[44:47], v[156:159], v[200:203], v[44:47]
	v_mfma_f32_16x16x32_bf16 v[40:43], v[168:171], v[200:203], v[40:43]
	v_mfma_f32_16x16x32_bf16 v[28:31], v[156:159], v[208:211], v[28:31]
	v_mfma_f32_16x16x32_bf16 v[24:27], v[168:171], v[208:211], v[24:27]
	v_mfma_f32_16x16x32_bf16 v[12:15], v[156:159], v[216:219], v[12:15]
	v_mfma_f32_16x16x32_bf16 v[8:11], v[168:171], v[216:219], v[8:11]
	s_setprio 0
	s_setprio 1
	v_mfma_f32_16x16x32_bf16 v[52:55], v[172:175], v[188:191], v[52:55]
	v_mfma_f32_16x16x32_bf16 v[48:51], v[180:183], v[188:191], v[48:51]
	v_mfma_f32_16x16x32_bf16 v[36:39], v[172:175], v[196:199], v[36:39]
	v_mfma_f32_16x16x32_bf16 v[32:35], v[180:183], v[196:199], v[32:35]
	v_mfma_f32_16x16x32_bf16 v[20:23], v[172:175], v[204:207], v[20:23]
	v_mfma_f32_16x16x32_bf16 v[16:19], v[180:183], v[204:207], v[16:19]
	v_mfma_f32_16x16x32_bf16 v[4:7], v[172:175], v[212:215], v[4:7]
	v_mfma_f32_16x16x32_bf16 v[0:3], v[180:183], v[212:215], v[0:3]
	v_mfma_f32_16x16x32_bf16 v[52:55], v[176:179], v[192:195], v[52:55]
	v_mfma_f32_16x16x32_bf16 v[48:51], v[184:187], v[192:195], v[48:51]
	v_mfma_f32_16x16x32_bf16 v[36:39], v[176:179], v[200:203], v[36:39]
	v_mfma_f32_16x16x32_bf16 v[32:35], v[184:187], v[200:203], v[32:35]
	v_mfma_f32_16x16x32_bf16 v[20:23], v[176:179], v[208:211], v[20:23]
	v_mfma_f32_16x16x32_bf16 v[16:19], v[184:187], v[208:211], v[16:19]
	v_mfma_f32_16x16x32_bf16 v[4:7], v[176:179], v[216:219], v[4:7]
	v_mfma_f32_16x16x32_bf16 v[0:3], v[184:187], v[216:219], v[0:3]
	s_setprio 0
	s_barrier
	s_add_i32 s51, 0, 0x18000
	v_add_u32_e32 v155, s51, v149
	s_add_i32 s52, 0, 0x1c000
	ds_read_b128 v[144:147], v155
	ds_read_b128 v[156:159], v155 offset:1024
	ds_read_b128 v[160:163], v155 offset:2048
	ds_read_b128 v[168:171], v155 offset:3072
	v_add_u32_e32 v155, s52, v149
	ds_read_b128 v[172:175], v155
	ds_read_b128 v[176:179], v155 offset:1024
	ds_read_b128 v[180:183], v155 offset:2048
	ds_read_b128 v[184:187], v155 offset:3072
	s_add_u32 s28, s28, 0x100000
	s_addc_u32 s29, s29, 0
	s_mov_b32 m0, s36
	v_lshl_add_u64 v[226:227], s[28:29], 0, v[128:129]
	ds_read_b128 v[188:191], v153 offset:32768
	ds_read_b128 v[192:195], v153 offset:33792
	ds_read_b128 v[196:199], v153 offset:34816
	ds_read_b128 v[200:203], v153 offset:35840
	ds_read_b128 v[204:207], v153 offset:36864
	ds_read_b128 v[208:211], v153 offset:37888
	ds_read_b128 v[212:215], v153 offset:38912
	ds_read_b128 v[216:219], v153 offset:39936
	global_load_lds_dwordx4 v[226:227], off
	v_lshl_add_u64 v[226:227], s[28:29], 0, v[132:133]
	s_mov_b32 m0, s37
	s_nop 0
	global_load_lds_dwordx4 v[226:227], off
	s_waitcnt vmcnt(8)
	s_waitcnt lgkmcnt(0)
	s_barrier
	s_setprio 1
	s_waitcnt lgkmcnt(0)
	v_mfma_f32_16x16x32_bf16 v[124:127], v[144:147], v[188:191], v[124:127]
	v_mfma_f32_16x16x32_bf16 v[120:123], v[160:163], v[188:191], v[120:123]
	v_mfma_f32_16x16x32_bf16 v[108:111], v[144:147], v[196:199], v[108:111]
	v_mfma_f32_16x16x32_bf16 v[104:107], v[160:163], v[196:199], v[104:107]
	v_mfma_f32_16x16x32_bf16 v[92:95], v[144:147], v[204:207], v[92:95]
	v_mfma_f32_16x16x32_bf16 v[88:91], v[160:163], v[204:207], v[88:91]
	v_mfma_f32_16x16x32_bf16 v[76:79], v[144:147], v[212:215], v[76:79]
	v_mfma_f32_16x16x32_bf16 v[72:75], v[160:163], v[212:215], v[72:75]
	v_mfma_f32_16x16x32_bf16 v[124:127], v[156:159], v[192:195], v[124:127]
	v_mfma_f32_16x16x32_bf16 v[120:123], v[168:171], v[192:195], v[120:123]
	v_mfma_f32_16x16x32_bf16 v[108:111], v[156:159], v[200:203], v[108:111]
	v_mfma_f32_16x16x32_bf16 v[104:107], v[168:171], v[200:203], v[104:107]
	v_mfma_f32_16x16x32_bf16 v[92:95], v[156:159], v[208:211], v[92:95]
	v_mfma_f32_16x16x32_bf16 v[88:91], v[168:171], v[208:211], v[88:91]
	v_mfma_f32_16x16x32_bf16 v[76:79], v[156:159], v[216:219], v[76:79]
	v_mfma_f32_16x16x32_bf16 v[72:75], v[168:171], v[216:219], v[72:75]
	s_setprio 0
	s_setprio 1
	v_mfma_f32_16x16x32_bf16 v[116:119], v[172:175], v[188:191], v[116:119]
	v_mfma_f32_16x16x32_bf16 v[112:115], v[180:183], v[188:191], v[112:115]
	v_mfma_f32_16x16x32_bf16 v[100:103], v[172:175], v[196:199], v[100:103]
	v_mfma_f32_16x16x32_bf16 v[96:99], v[180:183], v[196:199], v[96:99]
	v_mfma_f32_16x16x32_bf16 v[84:87], v[172:175], v[204:207], v[84:87]
	v_mfma_f32_16x16x32_bf16 v[80:83], v[180:183], v[204:207], v[80:83]
	v_mfma_f32_16x16x32_bf16 v[68:71], v[172:175], v[212:215], v[68:71]
	v_mfma_f32_16x16x32_bf16 v[64:67], v[180:183], v[212:215], v[64:67]
	v_mfma_f32_16x16x32_bf16 v[116:119], v[176:179], v[192:195], v[116:119]
	v_mfma_f32_16x16x32_bf16 v[112:115], v[184:187], v[192:195], v[112:115]
	v_mfma_f32_16x16x32_bf16 v[100:103], v[176:179], v[200:203], v[100:103]
	v_mfma_f32_16x16x32_bf16 v[96:99], v[184:187], v[200:203], v[96:99]
	v_mfma_f32_16x16x32_bf16 v[84:87], v[176:179], v[208:211], v[84:87]
	v_mfma_f32_16x16x32_bf16 v[80:83], v[184:187], v[208:211], v[80:83]
	v_mfma_f32_16x16x32_bf16 v[68:71], v[176:179], v[216:219], v[68:71]
	v_mfma_f32_16x16x32_bf16 v[64:67], v[184:187], v[216:219], v[64:67]
	s_setprio 0
	s_barrier
; __device__ __forceinline__ unsigned cvt_pk_bf16(float lo, float hi) { const f32x2_t v = {lo, hi}; const bf16x2_t b = __builtin_convertvector(v, bf16x2_t); return __builtin_bit_cast(unsigned, b); }
; #define PG8_STAGE(bufoff, gbase, voff) do { _Pragma("unroll") for (int _i = 0; _i < 2; ++_i) \
;         __builtin_amdgcn_global_load_lds((const unsigned*)((const char*)(gbase) + (voff)[_i]), (PG8_LAS unsigned*)(lds + (bufoff) + ldsw + _i * 8192), 16, 0, 0); } while (0)
;     __device__ __forceinline__ void operator()(const f32x4 (&acc)[2][2][4][2], const Unit& u, int wr, int wc, int fr, int fq, const PG8_LAS float*) const {
;         const int row0 = u.pm * BM + wr * 64 + fr; const int col0 = u.pn * BM + wc * 32 + 8 * fq;
; #pragma unroll
;         for (int ai = 0; ai < 2; ++ai)
; #pragma unroll
;             for (int m = 0; m < 4; ++m) { const int row = row0 + ai * HALF + m * 16; const size_t off = (size_t)row * ldc + col0; float ss = 0.f;
; #pragma unroll
;                 for (int bj = 0; bj < 2; ++bj) {
;                     const f32x4 b0 = *(const f32x4*)(base + off + bj * HALF), b1 = *(const f32x4*)(base + off + bj * HALF + 4);
;                     const f32x4 v0 = b0 + acc[ai][bj][m][0], v1 = b1 + acc[ai][bj][m][1];
;                     *(f32x4*)(out + off + bj * HALF) = v0; *(f32x4*)(out + off + bj * HALF + 4) = v1;
;                     if (xb) { u32x4 w; w.x = cvt_pk_bf16(v0[0], v0[1]); w.y = cvt_pk_bf16(v0[2], v0[3]); w.z = cvt_pk_bf16(v1[0], v1[1]); w.w = cvt_pk_bf16(v1[2], v1[3]);
;                         *(u32x4*)(xb + off + bj * HALF) = w;
;                         ss += ((v0[0] * v0[0] + v0[1] * v0[1]) + (v0[2] * v0[2] + v0[3] * v0[3])) + ((v1[0] * v1[0] + v1[1] * v1[1]) + (v1[2] * v1[2] + v1[3] * v1[3])); } }
;                 if (xb) { ss += __shfl_xor(ss, 16); ss += __shfl_xor(ss, 32); if (fq == 0) ssq[(size_t)row * 16 + u.pn * 4 + wc] = ss; } }
; template <class Epi, class Sched, bool ALIGN_EPI = false, bool SP2 = false>
; __device__ __forceinline__ void gemm_phase(PG8_LAS unsigned char* lds, const Gemm g, const Sched& S, const Epi& E) {
;     ...
;             PG8_LDA(At, 1, 1); PG8_STAGE(PG8_SB(1, 0), b3, voffB); PG8_STAGE(PG8_SB(1, 1), b3 + hstep, voffB); PG8_STAGE(PG8_SA(1, 0), a3, voffA);
;             PG8_WAIT_V(8); PG8_WAIT_L(0); PG8_BAR; PG8_MMA(1, 0, At, B0); PG8_MMA(1, 1, At, B1); PG8_BAR; PG8_SCHED;
	s_add_i32 s28, s51, s33
	v_lshl_add_u64 v[164:165], v[164:165], 0, s[10:11]
	s_mov_b32 m0, s28
	ds_read_b128 v[188:191], v153 offset:49152
	ds_read_b128 v[192:195], v153 offset:50176
	ds_read_b128 v[196:199], v153 offset:51200
	ds_read_b128 v[200:203], v153 offset:52224
	ds_read_b128 v[204:207], v153 offset:53248
	ds_read_b128 v[208:211], v153 offset:54272
	ds_read_b128 v[212:215], v153 offset:55296
	ds_read_b128 v[216:219], v153 offset:56320
	global_load_lds_dwordx4 v[164:165], off
	s_add_i32 m0, s28, 0x2000
	s_add_u32 s26, s26, 0x100080
	v_lshl_add_u64 v[164:165], v[220:221], 0, s[10:11]
	s_addc_u32 s27, s27, 0
	s_add_i32 s28, s52, s33
	global_load_lds_dwordx4 v[164:165], off
	v_lshl_add_u64 v[164:165], s[26:27], 0, v[130:131]
	s_mov_b32 m0, s28
	s_nop 0
	global_load_lds_dwordx4 v[164:165], off
	v_lshl_add_u64 v[164:165], s[26:27], 0, v[134:135]
	s_add_i32 m0, s28, 0x2000
	s_nop 0
	global_load_lds_dwordx4 v[164:165], off
	v_lshl_add_u64 v[164:165], v[222:223], 0, s[10:11]
	s_mov_b32 m0, s39
	s_nop 0
	global_load_lds_dwordx4 v[164:165], off
	v_lshl_add_u64 v[164:165], v[224:225], 0, s[10:11]
	s_mov_b32 m0, s40
	s_nop 0
	global_load_lds_dwordx4 v[164:165], off
	s_waitcnt vmcnt(8)
	s_waitcnt lgkmcnt(0)
	s_barrier
	s_setprio 1
	s_waitcnt lgkmcnt(0)
	v_mfma_f32_16x16x32_bf16 v[60:63], v[144:147], v[188:191], v[60:63]
	v_mfma_f32_16x16x32_bf16 v[56:59], v[160:163], v[188:191], v[56:59]
	v_mfma_f32_16x16x32_bf16 v[44:47], v[144:147], v[196:199], v[44:47]
	v_mfma_f32_16x16x32_bf16 v[40:43], v[160:163], v[196:199], v[40:43]
	v_mfma_f32_16x16x32_bf16 v[28:31], v[144:147], v[204:207], v[28:31]
	v_mfma_f32_16x16x32_bf16 v[24:27], v[160:163], v[204:207], v[24:27]
	v_mfma_f32_16x16x32_bf16 v[12:15], v[144:147], v[212:215], v[12:15]
	v_mfma_f32_16x16x32_bf16 v[8:11], v[160:163], v[212:215], v[8:11]
	v_mfma_f32_16x16x32_bf16 v[60:63], v[156:159], v[192:195], v[60:63]
	v_mfma_f32_16x16x32_bf16 v[56:59], v[168:171], v[192:195], v[56:59]
	v_mfma_f32_16x16x32_bf16 v[44:47], v[156:159], v[200:203], v[44:47]
	v_mfma_f32_16x16x32_bf16 v[40:43], v[168:171], v[200:203], v[40:43]
	v_mfma_f32_16x16x32_bf16 v[28:31], v[156:159], v[208:211], v[28:31]
	v_mfma_f32_16x16x32_bf16 v[24:27], v[168:171], v[208:211], v[24:27]
	v_mfma_f32_16x16x32_bf16 v[12:15], v[156:159], v[216:219], v[12:15]
	v_mfma_f32_16x16x32_bf16 v[8:11], v[168:171], v[216:219], v[8:11]
	s_setprio 0
	s_setprio 1
	v_mfma_f32_16x16x32_bf16 v[52:55], v[172:175], v[188:191], v[52:55]
	v_mfma_f32_16x16x32_bf16 v[48:51], v[180:183], v[188:191], v[48:51]
	v_mfma_f32_16x16x32_bf16 v[36:39], v[172:175], v[196:199], v[36:39]
	v_mfma_f32_16x16x32_bf16 v[32:35], v[180:183], v[196:199], v[32:35]
	v_mfma_f32_16x16x32_bf16 v[20:23], v[172:175], v[204:207], v[20:23]
	v_mfma_f32_16x16x32_bf16 v[16:19], v[180:183], v[204:207], v[16:19]
	v_mfma_f32_16x16x32_bf16 v[4:7], v[172:175], v[212:215], v[4:7]
	v_mfma_f32_16x16x32_bf16 v[0:3], v[180:183], v[212:215], v[0:3]
	v_mfma_f32_16x16x32_bf16 v[52:55], v[176:179], v[192:195], v[52:55]
	v_mfma_f32_16x16x32_bf16 v[48:51], v[184:187], v[192:195], v[48:51]
	v_mfma_f32_16x16x32_bf16 v[36:39], v[176:179], v[200:203], v[36:39]
	v_mfma_f32_16x16x32_bf16 v[32:35], v[184:187], v[200:203], v[32:35]
	v_mfma_f32_16x16x32_bf16 v[20:23], v[176:179], v[208:211], v[20:23]
	v_mfma_f32_16x16x32_bf16 v[16:19], v[184:187], v[208:211], v[16:19]
	v_mfma_f32_16x16x32_bf16 v[4:7], v[176:179], v[216:219], v[4:7]
	v_mfma_f32_16x16x32_bf16 v[0:3], v[184:187], v[216:219], v[0:3]
	s_setprio 0
	s_barrier
	s_add_i32 s50, s50, 2
	s_add_u32 s24, s24, 0x100
	s_addc_u32 s25, s25, 0
	s_add_u32 s48, s48, 0x100
	s_addc_u32 s49, s49, 0
	s_cmp_gt_u32 s50, 61
	s_cbranch_scc0 .LBB0_842
	v_mbcnt_lo_u32_b32 v234, -1, 0
	v_mbcnt_hi_u32_b32 v234, -1, v234
	v_bfe_u32 v234, v234, 3, 1
	v_sub_u32_e32 v231, 0, v234
	v_and_b32_e32 v230, 0xffff8010, v231
	v_and_b32_e32 v235, 0x7ff0, v231
	v_sub_u32_e32 v244, 0x8000, v235
	v_mov_b32_e32 v245, 0
	s_mov_b32 s98, 0xff00ff
	s_mov_b32 s99, 0xff00ff
	s_and_b64 vcc, exec, s[12:13]
	s_cbranch_vccz .LBB0_845
	s_barrier
.LBB0_845:
	v_lshl_add_u32 v146, s22, 8, v148
	v_lshl_or_b32 v144, s6, 8, v150
	v_ashrrev_i32_e32 v147, 31, v146
	v_ashrrev_i32_e32 v145, 31, v144
	v_lshlrev_b64 v[156:157], 10, v[146:147]
	v_lshl_add_u64 v[164:165], v[156:157], 0, v[144:145]
	v_lshl_add_u64 v[172:173], v[164:165], 2, s[68:69]
	global_load_dwordx4 v[156:159], v[172:173], off
	global_load_dwordx4 v[160:163], v[172:173], off offset:16
	v_readlane_b32 s22, v254, 39
	v_readlane_b32 s23, v254, 40
	v_xor_b32_e32 v155, 32, v154
	s_waitcnt vmcnt(0)
	v_pk_add_f32 v[126:127], v[126:127], v[158:159]
	v_pk_add_f32 v[124:125], v[124:125], v[156:157]
	v_pk_add_f32 v[158:159], v[122:123], v[162:163]
	v_pk_add_f32 v[156:157], v[120:121], v[160:161]
	v_lshl_add_u64 v[164:165], v[164:165], 1, s[22:23]
	v_cvt_pk_bf16_f32 v120, v124, v125
	v_cvt_pk_bf16_f32 v121, v126, v127
	v_cvt_pk_bf16_f32 v122, v156, v157
	v_cvt_pk_bf16_f32 v123, v158, v159
	v_lshl_add_u64 v[228:229], v[172:173], 0, v[230:231]
	v_lshl_add_u64 v[232:233], v[172:173], 0, v[244:245]
	ds_swizzle_b32 v236, v156 offset:swizzle(SWAP,8)
	ds_swizzle_b32 v237, v157 offset:swizzle(SWAP,8)
	ds_swizzle_b32 v238, v158 offset:swizzle(SWAP,8)
	ds_swizzle_b32 v239, v159 offset:swizzle(SWAP,8)
	ds_swizzle_b32 v240, v124 offset:swizzle(SWAP,8)
	ds_swizzle_b32 v241, v125 offset:swizzle(SWAP,8)
	ds_swizzle_b32 v242, v126 offset:swizzle(SWAP,8)
	ds_swizzle_b32 v243, v127 offset:swizzle(SWAP,8)
	s_waitcnt lgkmcnt(0)
; __device__ __forceinline__ unsigned cvt_pk_bf16(float lo, float hi) { const f32x2_t v = {lo, hi}; const bf16x2_t b = __builtin_convertvector(v, bf16x2_t); return __builtin_bit_cast(unsigned, b); }
;     __device__ __forceinline__ void operator()(const f32x4 (&acc)[2][2][4][2], const Unit& u, int wr, int wc, int fr, int fq, const PG8_LAS float*) const {
;     ...
;             for (int m = 0; m < 4; ++m) { const int row = row0 + ai * HALF + m * 16; const size_t off = (size_t)row * ldc + col0; float ss = 0.f;
; #pragma unroll
;                 for (int bj = 0; bj < 2; ++bj) {
;                     const f32x4 b0 = *(const f32x4*)(base + off + bj * HALF), b1 = *(const f32x4*)(base + off + bj * HALF + 4);
;                     const f32x4 v0 = b0 + acc[ai][bj][m][0], v1 = b1 + acc[ai][bj][m][1];
;                     *(f32x4*)(out + off + bj * HALF) = v0; *(f32x4*)(out + off + bj * HALF + 4) = v1;
;                     if (xb) { u32x4 w; w.x = cvt_pk_bf16(v0[0], v0[1]); w.y = cvt_pk_bf16(v0[2], v0[3]); w.z = cvt_pk_bf16(v1[0], v1[1]); w.w = cvt_pk_bf16(v1[2], v1[3]);
;                         *(u32x4*)(xb + off + bj * HALF) = w;
;                         ss += ((v0[0] * v0[0] + v0[1] * v0[1]) + (v0[2] * v0[2] + v0[3] * v0[3])) + ((v1[0] * v1[0] + v1[1] * v1[1]) + (v1[2] * v1[2] + v1[3] * v1[3])); } }
;                 if (xb) { ss += __shfl_xor(ss, 16); ss += __shfl_xor(ss, 32); if (fq == 0) ssq[(size_t)row * 16 + u.pn * 4 + wc] = ss; } }
	v_cndmask_b32_e64 v236, v236, v124, s[98:99]
	v_cndmask_b32_e64 v237, v237, v125, s[98:99]
	v_cndmask_b32_e64 v238, v238, v126, s[98:99]
	v_cndmask_b32_e64 v239, v239, v127, s[98:99]
	v_cndmask_b32_e64 v240, v156, v240, s[98:99]
	v_cndmask_b32_e64 v241, v157, v241, s[98:99]
	v_cndmask_b32_e64 v242, v158, v242, s[98:99]
	v_cndmask_b32_e64 v243, v159, v243, s[98:99]
	global_store_dwordx4 v[228:229], v[236:239], off
	global_store_dwordx4 v[232:233], v[240:243], off
	global_store_dwordx4 v[164:165], v[120:123], off
	global_load_dwordx4 v[160:163], v[172:173], off offset:512
	global_load_dwordx4 v[168:171], v[172:173], off offset:528
	v_mul_f32_e32 v122, v125, v125
	v_mul_f32_e32 v123, v127, v127
	v_mul_f32_e32 v125, v157, v157
	v_mul_f32_e32 v127, v159, v159
	v_fmac_f32_e32 v122, v124, v124
	v_fmac_f32_e32 v123, v126, v126
	v_fmac_f32_e32 v125, v156, v156
	v_fmac_f32_e32 v127, v158, v158
	v_add_f32_e32 v122, v122, v123
	v_add_f32_e32 v123, v125, v127
	v_add_f32_e32 v126, v122, v123
	v_and_b32_e32 v121, 64, v154
	v_xor_b32_e32 v120, 16, v154
	v_add_u32_e32 v121, 64, v121
	v_cmp_lt_i32_e32 vcc, v120, v121
	s_lshl_b32 s22, s6, 2
	s_ashr_i32 s23, s22, 31
	v_cndmask_b32_e32 v120, v154, v120, vcc
	v_lshlrev_b32_e32 v120, 2, v120
	v_cmp_lt_i32_e32 vcc, v155, v121
	s_waitcnt vmcnt(1)
	v_pk_add_f32 v[118:119], v[118:119], v[162:163]
	v_pk_add_f32 v[116:117], v[116:117], v[160:161]
	s_waitcnt vmcnt(0)
	v_pk_add_f32 v[124:125], v[114:115], v[170:171]
	v_pk_add_f32 v[122:123], v[112:113], v[168:169]
	v_mul_f32_e32 v112, v117, v117
	v_mul_f32_e32 v113, v119, v119
	v_mul_f32_e32 v114, v123, v123
	v_mul_f32_e32 v115, v125, v125
	v_fmac_f32_e32 v112, v116, v116
	v_fmac_f32_e32 v113, v118, v118
	v_fmac_f32_e32 v114, v122, v122
	v_fmac_f32_e32 v115, v124, v124
	v_add_f32_e32 v112, v112, v113
	v_add_f32_e32 v113, v114, v115
	v_add_f32_e32 v112, v112, v113
	v_add_f32_e32 v112, v126, v112
	ds_bpermute_b32 v113, v120, v112
	v_cndmask_b32_e32 v114, v154, v155, vcc
	v_lshlrev_b32_e32 v114, 2, v114
	v_lshl_add_u64 v[228:229], v[172:173], 0, v[230:231]
	v_lshl_add_u64 v[232:233], v[172:173], 0, v[244:245]
	ds_swizzle_b32 v236, v122 offset:swizzle(SWAP,8)
	ds_swizzle_b32 v237, v123 offset:swizzle(SWAP,8)
	ds_swizzle_b32 v238, v124 offset:swizzle(SWAP,8)
	ds_swizzle_b32 v239, v125 offset:swizzle(SWAP,8)
	ds_swizzle_b32 v240, v116 offset:swizzle(SWAP,8)
	ds_swizzle_b32 v241, v117 offset:swizzle(SWAP,8)
	ds_swizzle_b32 v242, v118 offset:swizzle(SWAP,8)
	ds_swizzle_b32 v243, v119 offset:swizzle(SWAP,8)
	s_waitcnt lgkmcnt(0)
	v_cndmask_b32_e64 v236, v236, v116, s[98:99]
	v_cndmask_b32_e64 v237, v237, v117, s[98:99]
	v_cndmask_b32_e64 v238, v238, v118, s[98:99]
	v_cndmask_b32_e64 v239, v239, v119, s[98:99]
	v_cndmask_b32_e64 v240, v122, v240, s[98:99]
	v_cndmask_b32_e64 v241, v123, v241, s[98:99]
	v_cndmask_b32_e64 v242, v124, v242, s[98:99]
	v_cndmask_b32_e64 v243, v125, v243, s[98:99]
	global_store_dwordx4 v[228:229], v[236:239], off offset:512
	global_store_dwordx4 v[232:233], v[240:243], off offset:512
	s_waitcnt lgkmcnt(0)
	v_add_f32_e32 v112, v112, v113
	ds_bpermute_b32 v113, v114, v112
	v_cvt_pk_bf16_f32 v116, v116, v117
	v_cvt_pk_bf16_f32 v117, v118, v119
	v_cvt_pk_bf16_f32 v118, v122, v123
	v_cvt_pk_bf16_f32 v119, v124, v125
	global_store_dwordx4 v[164:165], v[116:119], off offset:256
	s_and_saveexec_b64 s[24:25], s[2:3]
	s_cbranch_execz .LBB0_847
	v_readlane_b32 s26, v254, 41
	s_waitcnt lgkmcnt(0)
	v_add_f32_e32 v115, v112, v113
	v_lshlrev_b64 v[112:113], 6, v[146:147]
	v_readlane_b32 s27, v254, 42
	s_lshl_b32 s6, s38, 2
	s_nop 0
	v_lshl_add_u64 v[112:113], s[26:27], 0, v[112:113]
	v_lshl_add_u64 v[112:113], s[22:23], 2, v[112:113]
	v_lshl_add_u64 v[112:113], v[112:113], 0, s[6:7]
	global_store_dword v[112:113], v115, off
.LBB0_847:
	s_or_b64 exec, exec, s[24:25]
	v_or_b32_e32 v112, 16, v146
	s_waitcnt lgkmcnt(0)
	v_ashrrev_i32_e32 v113, 31, v112
	v_lshlrev_b64 v[116:117], 10, v[112:113]
	v_lshl_add_u64 v[126:127], v[116:117], 0, v[144:145]
	v_lshl_add_u64 v[156:157], v[126:127], 2, s[68:69]
	global_load_dwordx4 v[116:119], v[156:157], off
	global_load_dwordx4 v[122:125], v[156:157], off offset:16
	v_readlane_b32 s24, v254, 39
	v_readlane_b32 s25, v254, 40
	s_waitcnt vmcnt(1)
	v_pk_add_f32 v[110:111], v[110:111], v[118:119]
	v_pk_add_f32 v[108:109], v[108:109], v[116:117]
	s_waitcnt vmcnt(0)
	v_pk_add_f32 v[106:107], v[106:107], v[124:125]
	v_pk_add_f32 v[104:105], v[104:105], v[122:123]
	v_lshl_add_u64 v[126:127], v[126:127], 1, s[24:25]
	v_cvt_pk_bf16_f32 v116, v108, v109
	v_cvt_pk_bf16_f32 v117, v110, v111
	v_cvt_pk_bf16_f32 v118, v104, v105
	v_cvt_pk_bf16_f32 v119, v106, v107
	v_lshl_add_u64 v[228:229], v[156:157], 0, v[230:231]
	v_lshl_add_u64 v[232:233], v[156:157], 0, v[244:245]
	ds_swizzle_b32 v236, v104 offset:swizzle(SWAP,8)
	ds_swizzle_b32 v237, v105 offset:swizzle(SWAP,8)
	ds_swizzle_b32 v238, v106 offset:swizzle(SWAP,8)
	ds_swizzle_b32 v239, v107 offset:swizzle(SWAP,8)
	ds_swizzle_b32 v240, v108 offset:swizzle(SWAP,8)
	ds_swizzle_b32 v241, v109 offset:swizzle(SWAP,8)
	ds_swizzle_b32 v242, v110 offset:swizzle(SWAP,8)
	ds_swizzle_b32 v243, v111 offset:swizzle(SWAP,8)
	s_waitcnt lgkmcnt(0)
; __device__ __forceinline__ unsigned cvt_pk_bf16(float lo, float hi) { const f32x2_t v = {lo, hi}; const bf16x2_t b = __builtin_convertvector(v, bf16x2_t); return __builtin_bit_cast(unsigned, b); }
;     __device__ __forceinline__ void operator()(const f32x4 (&acc)[2][2][4][2], const Unit& u, int wr, int wc, int fr, int fq, const PG8_LAS float*) const {
;     ...
;             for (int m = 0; m < 4; ++m) { const int row = row0 + ai * HALF + m * 16; const size_t off = (size_t)row * ldc + col0; float ss = 0.f;
; #pragma unroll
;                 for (int bj = 0; bj < 2; ++bj) {
;                     const f32x4 b0 = *(const f32x4*)(base + off + bj * HALF), b1 = *(const f32x4*)(base + off + bj * HALF + 4);
;                     const f32x4 v0 = b0 + acc[ai][bj][m][0], v1 = b1 + acc[ai][bj][m][1];
;                     *(f32x4*)(out + off + bj * HALF) = v0; *(f32x4*)(out + off + bj * HALF + 4) = v1;
;                     if (xb) { u32x4 w; w.x = cvt_pk_bf16(v0[0], v0[1]); w.y = cvt_pk_bf16(v0[2], v0[3]); w.z = cvt_pk_bf16(v1[0], v1[1]); w.w = cvt_pk_bf16(v1[2], v1[3]);
;                         *(u32x4*)(xb + off + bj * HALF) = w;
;                         ss += ((v0[0] * v0[0] + v0[1] * v0[1]) + (v0[2] * v0[2] + v0[3] * v0[3])) + ((v1[0] * v1[0] + v1[1] * v1[1]) + (v1[2] * v1[2] + v1[3] * v1[3])); } }
;                 if (xb) { ss += __shfl_xor(ss, 16); ss += __shfl_xor(ss, 32); if (fq == 0) ssq[(size_t)row * 16 + u.pn * 4 + wc] = ss; } }
	v_cndmask_b32_e64 v236, v236, v108, s[98:99]
	v_cndmask_b32_e64 v237, v237, v109, s[98:99]
	v_cndmask_b32_e64 v238, v238, v110, s[98:99]
	v_cndmask_b32_e64 v239, v239, v111, s[98:99]
	v_cndmask_b32_e64 v240, v104, v240, s[98:99]
	v_cndmask_b32_e64 v241, v105, v241, s[98:99]
	v_cndmask_b32_e64 v242, v106, v242, s[98:99]
	v_cndmask_b32_e64 v243, v107, v243, s[98:99]
	global_store_dwordx4 v[228:229], v[236:239], off
	global_store_dwordx4 v[232:233], v[240:243], off
	global_store_dwordx4 v[126:127], v[116:119], off
	global_load_dwordx4 v[116:119], v[156:157], off offset:512
	s_nop 0
	global_load_dwordx4 v[122:125], v[156:157], off offset:528
	v_mul_f32_e32 v109, v109, v109
	v_mul_f32_e32 v111, v111, v111
	v_mul_f32_e32 v105, v105, v105
	v_mul_f32_e32 v107, v107, v107
	v_fmac_f32_e32 v109, v108, v108
	v_fmac_f32_e32 v111, v110, v110
	v_fmac_f32_e32 v105, v104, v104
	v_fmac_f32_e32 v107, v106, v106
	v_add_f32_e32 v104, v109, v111
	v_add_f32_e32 v105, v105, v107
	v_add_f32_e32 v108, v104, v105
	s_waitcnt vmcnt(1)
	v_pk_add_f32 v[102:103], v[102:103], v[118:119]
	v_pk_add_f32 v[100:101], v[100:101], v[116:117]
	s_waitcnt vmcnt(0)
	v_pk_add_f32 v[106:107], v[98:99], v[124:125]
	v_pk_add_f32 v[104:105], v[96:97], v[122:123]
	v_mul_f32_e32 v96, v101, v101
	v_mul_f32_e32 v97, v103, v103
	v_mul_f32_e32 v98, v105, v105
	v_mul_f32_e32 v99, v107, v107
	v_fmac_f32_e32 v96, v100, v100
	v_fmac_f32_e32 v97, v102, v102
	v_fmac_f32_e32 v98, v104, v104
	v_fmac_f32_e32 v99, v106, v106
	v_add_f32_e32 v96, v96, v97
	v_add_f32_e32 v97, v98, v99
	v_add_f32_e32 v96, v96, v97
	v_add_f32_e32 v96, v108, v96
	ds_bpermute_b32 v97, v120, v96
	v_lshl_add_u64 v[228:229], v[156:157], 0, v[230:231]
	v_lshl_add_u64 v[232:233], v[156:157], 0, v[244:245]
	ds_swizzle_b32 v236, v104 offset:swizzle(SWAP,8)
	ds_swizzle_b32 v237, v105 offset:swizzle(SWAP,8)
	ds_swizzle_b32 v238, v106 offset:swizzle(SWAP,8)
	ds_swizzle_b32 v239, v107 offset:swizzle(SWAP,8)
	ds_swizzle_b32 v240, v100 offset:swizzle(SWAP,8)
	ds_swizzle_b32 v241, v101 offset:swizzle(SWAP,8)
	ds_swizzle_b32 v242, v102 offset:swizzle(SWAP,8)
	ds_swizzle_b32 v243, v103 offset:swizzle(SWAP,8)
	s_waitcnt lgkmcnt(0)
	v_cndmask_b32_e64 v236, v236, v100, s[98:99]
	v_cndmask_b32_e64 v237, v237, v101, s[98:99]
	v_cndmask_b32_e64 v238, v238, v102, s[98:99]
	v_cndmask_b32_e64 v239, v239, v103, s[98:99]
	v_cndmask_b32_e64 v240, v104, v240, s[98:99]
	v_cndmask_b32_e64 v241, v105, v241, s[98:99]
	v_cndmask_b32_e64 v242, v106, v242, s[98:99]
	v_cndmask_b32_e64 v243, v107, v243, s[98:99]
	global_store_dwordx4 v[228:229], v[236:239], off offset:512
	global_store_dwordx4 v[232:233], v[240:243], off offset:512
	v_cvt_pk_bf16_f32 v98, v100, v101
	v_cvt_pk_bf16_f32 v99, v102, v103
	v_cvt_pk_bf16_f32 v100, v104, v105
	s_waitcnt lgkmcnt(0)
	v_add_f32_e32 v96, v96, v97
	ds_bpermute_b32 v97, v114, v96
	v_cvt_pk_bf16_f32 v101, v106, v107
	global_store_dwordx4 v[126:127], v[98:101], off offset:256
	s_and_saveexec_b64 s[24:25], s[2:3]
	s_cbranch_execz .LBB0_849
	v_readlane_b32 s26, v254, 41
	s_waitcnt lgkmcnt(0)
	v_add_f32_e32 v98, v96, v97
	v_lshlrev_b64 v[96:97], 6, v[112:113]
	v_readlane_b32 s27, v254, 42
	s_lshl_b32 s6, s38, 2
	s_nop 0
	v_lshl_add_u64 v[96:97], s[26:27], 0, v[96:97]
	v_lshl_add_u64 v[96:97], s[22:23], 2, v[96:97]
	v_lshl_add_u64 v[96:97], v[96:97], 0, s[6:7]
	global_store_dword v[96:97], v98, off
.LBB0_849:
	s_or_b64 exec, exec, s[24:25]
	v_or_b32_e32 v96, 32, v146
	s_waitcnt lgkmcnt(0)
	v_ashrrev_i32_e32 v97, 31, v96
	v_lshlrev_b64 v[98:99], 10, v[96:97]
	v_lshl_add_u64 v[106:107], v[98:99], 0, v[144:145]
	v_lshl_add_u64 v[108:109], v[106:107], 2, s[68:69]
	global_load_dwordx4 v[98:101], v[108:109], off
	global_load_dwordx4 v[102:105], v[108:109], off offset:16
	v_readlane_b32 s24, v254, 39
	v_readlane_b32 s25, v254, 40
	s_waitcnt vmcnt(1)
	v_pk_add_f32 v[94:95], v[94:95], v[100:101]
	v_pk_add_f32 v[92:93], v[92:93], v[98:99]
	s_waitcnt vmcnt(0)
	v_pk_add_f32 v[90:91], v[90:91], v[104:105]
	v_pk_add_f32 v[88:89], v[88:89], v[102:103]
	v_lshl_add_u64 v[106:107], v[106:107], 1, s[24:25]
	v_cvt_pk_bf16_f32 v98, v92, v93
	v_cvt_pk_bf16_f32 v99, v94, v95
	v_cvt_pk_bf16_f32 v100, v88, v89
	v_cvt_pk_bf16_f32 v101, v90, v91
	v_lshl_add_u64 v[228:229], v[108:109], 0, v[230:231]
	v_lshl_add_u64 v[232:233], v[108:109], 0, v[244:245]
	ds_swizzle_b32 v236, v88 offset:swizzle(SWAP,8)
	ds_swizzle_b32 v237, v89 offset:swizzle(SWAP,8)
	ds_swizzle_b32 v238, v90 offset:swizzle(SWAP,8)
	ds_swizzle_b32 v239, v91 offset:swizzle(SWAP,8)
	ds_swizzle_b32 v240, v92 offset:swizzle(SWAP,8)
	ds_swizzle_b32 v241, v93 offset:swizzle(SWAP,8)
	ds_swizzle_b32 v242, v94 offset:swizzle(SWAP,8)
	ds_swizzle_b32 v243, v95 offset:swizzle(SWAP,8)
	s_waitcnt lgkmcnt(0)
	v_cndmask_b32_e64 v236, v236, v92, s[98:99]
	v_cndmask_b32_e64 v237, v237, v93, s[98:99]
	v_cndmask_b32_e64 v238, v238, v94, s[98:99]
	v_cndmask_b32_e64 v239, v239, v95, s[98:99]
	v_cndmask_b32_e64 v240, v88, v240, s[98:99]
	v_cndmask_b32_e64 v241, v89, v241, s[98:99]
	v_cndmask_b32_e64 v242, v90, v242, s[98:99]
	v_cndmask_b32_e64 v243, v91, v243, s[98:99]
	global_store_dwordx4 v[228:229], v[236:239], off
	global_store_dwordx4 v[232:233], v[240:243], off
	global_store_dwordx4 v[106:107], v[98:101], off
	global_load_dwordx4 v[98:101], v[108:109], off offset:512
	s_nop 0
	global_load_dwordx4 v[102:105], v[108:109], off offset:528
	v_mul_f32_e32 v93, v93, v93
	v_mul_f32_e32 v95, v95, v95
	v_mul_f32_e32 v89, v89, v89
	v_mul_f32_e32 v91, v91, v91
	v_fmac_f32_e32 v93, v92, v92
	v_fmac_f32_e32 v95, v94, v94
	v_fmac_f32_e32 v89, v88, v88
	v_fmac_f32_e32 v91, v90, v90
	v_add_f32_e32 v88, v93, v95
	v_add_f32_e32 v89, v89, v91
	v_add_f32_e32 v92, v88, v89
	s_waitcnt vmcnt(1)
; __device__ __forceinline__ unsigned cvt_pk_bf16(float lo, float hi) { const f32x2_t v = {lo, hi}; const bf16x2_t b = __builtin_convertvector(v, bf16x2_t); return __builtin_bit_cast(unsigned, b); }
;     __device__ __forceinline__ void operator()(const f32x4 (&acc)[2][2][4][2], const Unit& u, int wr, int wc, int fr, int fq, const PG8_LAS float*) const {
;     ...
;             for (int m = 0; m < 4; ++m) { const int row = row0 + ai * HALF + m * 16; const size_t off = (size_t)row * ldc + col0; float ss = 0.f;
; #pragma unroll
;                 for (int bj = 0; bj < 2; ++bj) {
;                     const f32x4 b0 = *(const f32x4*)(base + off + bj * HALF), b1 = *(const f32x4*)(base + off + bj * HALF + 4);
;                     const f32x4 v0 = b0 + acc[ai][bj][m][0], v1 = b1 + acc[ai][bj][m][1];
;                     *(f32x4*)(out + off + bj * HALF) = v0; *(f32x4*)(out + off + bj * HALF + 4) = v1;
;                     if (xb) { u32x4 w; w.x = cvt_pk_bf16(v0[0], v0[1]); w.y = cvt_pk_bf16(v0[2], v0[3]); w.z = cvt_pk_bf16(v1[0], v1[1]); w.w = cvt_pk_bf16(v1[2], v1[3]);
;                         *(u32x4*)(xb + off + bj * HALF) = w;
;                         ss += ((v0[0] * v0[0] + v0[1] * v0[1]) + (v0[2] * v0[2] + v0[3] * v0[3])) + ((v1[0] * v1[0] + v1[1] * v1[1]) + (v1[2] * v1[2] + v1[3] * v1[3])); } }
;                 if (xb) { ss += __shfl_xor(ss, 16); ss += __shfl_xor(ss, 32); if (fq == 0) ssq[(size_t)row * 16 + u.pn * 4 + wc] = ss; } }
	v_pk_add_f32 v[86:87], v[86:87], v[100:101]
	v_pk_add_f32 v[84:85], v[84:85], v[98:99]
	s_waitcnt vmcnt(0)
	v_pk_add_f32 v[90:91], v[82:83], v[104:105]
	v_pk_add_f32 v[88:89], v[80:81], v[102:103]
	v_mul_f32_e32 v80, v85, v85
	v_mul_f32_e32 v81, v87, v87
	v_mul_f32_e32 v82, v89, v89
	v_mul_f32_e32 v83, v91, v91
	v_fmac_f32_e32 v80, v84, v84
	v_fmac_f32_e32 v81, v86, v86
	v_fmac_f32_e32 v82, v88, v88
	v_fmac_f32_e32 v83, v90, v90
	v_add_f32_e32 v80, v80, v81
	v_add_f32_e32 v81, v82, v83
	v_add_f32_e32 v80, v80, v81
	v_add_f32_e32 v80, v92, v80
	ds_bpermute_b32 v81, v120, v80
	v_lshl_add_u64 v[228:229], v[108:109], 0, v[230:231]
	v_lshl_add_u64 v[232:233], v[108:109], 0, v[244:245]
	ds_swizzle_b32 v236, v88 offset:swizzle(SWAP,8)
	ds_swizzle_b32 v237, v89 offset:swizzle(SWAP,8)
	ds_swizzle_b32 v238, v90 offset:swizzle(SWAP,8)
	ds_swizzle_b32 v239, v91 offset:swizzle(SWAP,8)
	ds_swizzle_b32 v240, v84 offset:swizzle(SWAP,8)
	ds_swizzle_b32 v241, v85 offset:swizzle(SWAP,8)
	ds_swizzle_b32 v242, v86 offset:swizzle(SWAP,8)
	ds_swizzle_b32 v243, v87 offset:swizzle(SWAP,8)
	s_waitcnt lgkmcnt(0)
	v_cndmask_b32_e64 v236, v236, v84, s[98:99]
	v_cndmask_b32_e64 v237, v237, v85, s[98:99]
	v_cndmask_b32_e64 v238, v238, v86, s[98:99]
	v_cndmask_b32_e64 v239, v239, v87, s[98:99]
	v_cndmask_b32_e64 v240, v88, v240, s[98:99]
	v_cndmask_b32_e64 v241, v89, v241, s[98:99]
	v_cndmask_b32_e64 v242, v90, v242, s[98:99]
	v_cndmask_b32_e64 v243, v91, v243, s[98:99]
	global_store_dwordx4 v[228:229], v[236:239], off offset:512
	global_store_dwordx4 v[232:233], v[240:243], off offset:512
	v_cvt_pk_bf16_f32 v82, v84, v85
	v_cvt_pk_bf16_f32 v83, v86, v87
	v_cvt_pk_bf16_f32 v84, v88, v89
	s_waitcnt lgkmcnt(0)
	v_add_f32_e32 v80, v80, v81
	ds_bpermute_b32 v81, v114, v80
	v_cvt_pk_bf16_f32 v85, v90, v91
	global_store_dwordx4 v[106:107], v[82:85], off offset:256
	s_and_saveexec_b64 s[24:25], s[2:3]
	s_cbranch_execz .LBB0_851
	v_readlane_b32 s26, v254, 41
	s_waitcnt lgkmcnt(0)
	v_add_f32_e32 v82, v80, v81
	v_lshlrev_b64 v[80:81], 6, v[96:97]
	v_readlane_b32 s27, v254, 42
	s_lshl_b32 s6, s38, 2
	s_nop 0
	v_lshl_add_u64 v[80:81], s[26:27], 0, v[80:81]
	v_lshl_add_u64 v[80:81], s[22:23], 2, v[80:81]
	v_lshl_add_u64 v[80:81], v[80:81], 0, s[6:7]
	global_store_dword v[80:81], v82, off
.LBB0_851:
	s_or_b64 exec, exec, s[24:25]
	v_or_b32_e32 v80, 48, v146
	s_waitcnt lgkmcnt(0)
	v_ashrrev_i32_e32 v81, 31, v80
	v_lshlrev_b64 v[82:83], 10, v[80:81]
	v_lshl_add_u64 v[90:91], v[82:83], 0, v[144:145]
	v_lshl_add_u64 v[92:93], v[90:91], 2, s[68:69]
	global_load_dwordx4 v[82:85], v[92:93], off
	global_load_dwordx4 v[86:89], v[92:93], off offset:16
	v_readlane_b32 s24, v254, 39
	v_readlane_b32 s25, v254, 40
	s_waitcnt vmcnt(1)
	v_pk_add_f32 v[78:79], v[78:79], v[84:85]
	v_pk_add_f32 v[76:77], v[76:77], v[82:83]
	s_waitcnt vmcnt(0)
	v_pk_add_f32 v[74:75], v[74:75], v[88:89]
	v_pk_add_f32 v[72:73], v[72:73], v[86:87]
	v_lshl_add_u64 v[90:91], v[90:91], 1, s[24:25]
	v_cvt_pk_bf16_f32 v82, v76, v77
	v_cvt_pk_bf16_f32 v83, v78, v79
	v_cvt_pk_bf16_f32 v84, v72, v73
	v_cvt_pk_bf16_f32 v85, v74, v75
	v_lshl_add_u64 v[228:229], v[92:93], 0, v[230:231]
	v_lshl_add_u64 v[232:233], v[92:93], 0, v[244:245]
	ds_swizzle_b32 v236, v72 offset:swizzle(SWAP,8)
	ds_swizzle_b32 v237, v73 offset:swizzle(SWAP,8)
	ds_swizzle_b32 v238, v74 offset:swizzle(SWAP,8)
	ds_swizzle_b32 v239, v75 offset:swizzle(SWAP,8)
	ds_swizzle_b32 v240, v76 offset:swizzle(SWAP,8)
	ds_swizzle_b32 v241, v77 offset:swizzle(SWAP,8)
	ds_swizzle_b32 v242, v78 offset:swizzle(SWAP,8)
	ds_swizzle_b32 v243, v79 offset:swizzle(SWAP,8)
	s_waitcnt lgkmcnt(0)
	v_cndmask_b32_e64 v236, v236, v76, s[98:99]
	v_cndmask_b32_e64 v237, v237, v77, s[98:99]
	v_cndmask_b32_e64 v238, v238, v78, s[98:99]
	v_cndmask_b32_e64 v239, v239, v79, s[98:99]
	v_cndmask_b32_e64 v240, v72, v240, s[98:99]
	v_cndmask_b32_e64 v241, v73, v241, s[98:99]
	v_cndmask_b32_e64 v242, v74, v242, s[98:99]
	v_cndmask_b32_e64 v243, v75, v243, s[98:99]
	global_store_dwordx4 v[228:229], v[236:239], off
	global_store_dwordx4 v[232:233], v[240:243], off
	global_store_dwordx4 v[90:91], v[82:85], off
	global_load_dwordx4 v[82:85], v[92:93], off offset:512
	s_nop 0
	global_load_dwordx4 v[86:89], v[92:93], off offset:528
	v_mul_f32_e32 v77, v77, v77
	v_mul_f32_e32 v79, v79, v79
	v_mul_f32_e32 v73, v73, v73
	v_mul_f32_e32 v75, v75, v75
	v_fmac_f32_e32 v77, v76, v76
	v_fmac_f32_e32 v79, v78, v78
	v_fmac_f32_e32 v73, v72, v72
	v_fmac_f32_e32 v75, v74, v74
	v_add_f32_e32 v72, v77, v79
	v_add_f32_e32 v73, v73, v75
	v_add_f32_e32 v76, v72, v73
	s_waitcnt vmcnt(1)
	v_pk_add_f32 v[70:71], v[70:71], v[84:85]
	v_pk_add_f32 v[68:69], v[68:69], v[82:83]
	s_waitcnt vmcnt(0)
	v_pk_add_f32 v[74:75], v[66:67], v[88:89]
	v_pk_add_f32 v[72:73], v[64:65], v[86:87]
	v_mul_f32_e32 v64, v69, v69
	v_mul_f32_e32 v65, v71, v71
	v_mul_f32_e32 v66, v73, v73
	v_mul_f32_e32 v67, v75, v75
	v_fmac_f32_e32 v64, v68, v68
	v_fmac_f32_e32 v65, v70, v70
	v_fmac_f32_e32 v66, v72, v72
	v_fmac_f32_e32 v67, v74, v74
	v_add_f32_e32 v64, v64, v65
	v_add_f32_e32 v65, v66, v67
	v_add_f32_e32 v64, v64, v65
	v_add_f32_e32 v64, v76, v64
	ds_bpermute_b32 v65, v120, v64
	v_lshl_add_u64 v[228:229], v[92:93], 0, v[230:231]
	v_lshl_add_u64 v[232:233], v[92:93], 0, v[244:245]
	ds_swizzle_b32 v236, v72 offset:swizzle(SWAP,8)
	ds_swizzle_b32 v237, v73 offset:swizzle(SWAP,8)
	ds_swizzle_b32 v238, v74 offset:swizzle(SWAP,8)
	ds_swizzle_b32 v239, v75 offset:swizzle(SWAP,8)
	ds_swizzle_b32 v240, v68 offset:swizzle(SWAP,8)
	ds_swizzle_b32 v241, v69 offset:swizzle(SWAP,8)
	ds_swizzle_b32 v242, v70 offset:swizzle(SWAP,8)
	ds_swizzle_b32 v243, v71 offset:swizzle(SWAP,8)
	s_waitcnt lgkmcnt(0)
	v_cndmask_b32_e64 v236, v236, v68, s[98:99]
	v_cndmask_b32_e64 v237, v237, v69, s[98:99]
	v_cndmask_b32_e64 v238, v238, v70, s[98:99]
	v_cndmask_b32_e64 v239, v239, v71, s[98:99]
	v_cndmask_b32_e64 v240, v72, v240, s[98:99]
	v_cndmask_b32_e64 v241, v73, v241, s[98:99]
	v_cndmask_b32_e64 v242, v74, v242, s[98:99]
	v_cndmask_b32_e64 v243, v75, v243, s[98:99]
	global_store_dwordx4 v[228:229], v[236:239], off offset:512
	global_store_dwordx4 v[232:233], v[240:243], off offset:512
	v_cvt_pk_bf16_f32 v66, v68, v69
	v_cvt_pk_bf16_f32 v67, v70, v71
	v_cvt_pk_bf16_f32 v68, v72, v73
	s_waitcnt lgkmcnt(0)
	v_add_f32_e32 v64, v64, v65
	ds_bpermute_b32 v65, v114, v64
	v_cvt_pk_bf16_f32 v69, v74, v75
	global_store_dwordx4 v[90:91], v[66:69], off offset:256
	s_and_saveexec_b64 s[24:25], s[2:3]
	s_cbranch_execz .LBB0_853
	v_readlane_b32 s26, v254, 41
	s_waitcnt lgkmcnt(0)
	v_add_f32_e32 v66, v64, v65
	v_lshlrev_b64 v[64:65], 6, v[80:81]
	v_readlane_b32 s27, v254, 42
	s_lshl_b32 s6, s38, 2
	s_nop 0
	v_lshl_add_u64 v[64:65], s[26:27], 0, v[64:65]
	v_lshl_add_u64 v[64:65], s[22:23], 2, v[64:65]
	v_lshl_add_u64 v[64:65], v[64:65], 0, s[6:7]
	global_store_dword v[64:65], v66, off
; __device__ __forceinline__ unsigned cvt_pk_bf16(float lo, float hi) { const f32x2_t v = {lo, hi}; const bf16x2_t b = __builtin_convertvector(v, bf16x2_t); return __builtin_bit_cast(unsigned, b); }
;     __device__ __forceinline__ void operator()(const f32x4 (&acc)[2][2][4][2], const Unit& u, int wr, int wc, int fr, int fq, const PG8_LAS float*) const {
;     ...
;             for (int m = 0; m < 4; ++m) { const int row = row0 + ai * HALF + m * 16; const size_t off = (size_t)row * ldc + col0; float ss = 0.f;
; #pragma unroll
;                 for (int bj = 0; bj < 2; ++bj) {
;                     const f32x4 b0 = *(const f32x4*)(base + off + bj * HALF), b1 = *(const f32x4*)(base + off + bj * HALF + 4);
;                     const f32x4 v0 = b0 + acc[ai][bj][m][0], v1 = b1 + acc[ai][bj][m][1];
;                     *(f32x4*)(out + off + bj * HALF) = v0; *(f32x4*)(out + off + bj * HALF + 4) = v1;
;                     if (xb) { u32x4 w; w.x = cvt_pk_bf16(v0[0], v0[1]); w.y = cvt_pk_bf16(v0[2], v0[3]); w.z = cvt_pk_bf16(v1[0], v1[1]); w.w = cvt_pk_bf16(v1[2], v1[3]);
;                         *(u32x4*)(xb + off + bj * HALF) = w;
;                         ss += ((v0[0] * v0[0] + v0[1] * v0[1]) + (v0[2] * v0[2] + v0[3] * v0[3])) + ((v1[0] * v1[0] + v1[1] * v1[1]) + (v1[2] * v1[2] + v1[3] * v1[3])); } }
;                 if (xb) { ss += __shfl_xor(ss, 16); ss += __shfl_xor(ss, 32); if (fq == 0) ssq[(size_t)row * 16 + u.pn * 4 + wc] = ss; } }
.LBB0_853:
	s_or_b64 exec, exec, s[24:25]
	v_add_u32_e32 v64, 0x80, v146
	s_waitcnt lgkmcnt(0)
	v_ashrrev_i32_e32 v65, 31, v64
	v_lshlrev_b64 v[66:67], 10, v[64:65]
	v_lshl_add_u64 v[74:75], v[66:67], 0, v[144:145]
	v_lshl_add_u64 v[76:77], v[74:75], 2, s[68:69]
	global_load_dwordx4 v[66:69], v[76:77], off
	global_load_dwordx4 v[70:73], v[76:77], off offset:16
	v_readlane_b32 s24, v254, 39
	v_readlane_b32 s25, v254, 40
	s_waitcnt vmcnt(1)
	v_pk_add_f32 v[62:63], v[62:63], v[68:69]
	v_pk_add_f32 v[60:61], v[60:61], v[66:67]
	s_waitcnt vmcnt(0)
	v_pk_add_f32 v[58:59], v[58:59], v[72:73]
	v_pk_add_f32 v[56:57], v[56:57], v[70:71]
	v_lshl_add_u64 v[74:75], v[74:75], 1, s[24:25]
	v_cvt_pk_bf16_f32 v66, v60, v61
	v_cvt_pk_bf16_f32 v67, v62, v63
	v_cvt_pk_bf16_f32 v68, v56, v57
	v_cvt_pk_bf16_f32 v69, v58, v59
	v_lshl_add_u64 v[228:229], v[76:77], 0, v[230:231]
	v_lshl_add_u64 v[232:233], v[76:77], 0, v[244:245]
	ds_swizzle_b32 v236, v56 offset:swizzle(SWAP,8)
	ds_swizzle_b32 v237, v57 offset:swizzle(SWAP,8)
	ds_swizzle_b32 v238, v58 offset:swizzle(SWAP,8)
	ds_swizzle_b32 v239, v59 offset:swizzle(SWAP,8)
	ds_swizzle_b32 v240, v60 offset:swizzle(SWAP,8)
	ds_swizzle_b32 v241, v61 offset:swizzle(SWAP,8)
	ds_swizzle_b32 v242, v62 offset:swizzle(SWAP,8)
	ds_swizzle_b32 v243, v63 offset:swizzle(SWAP,8)
	s_waitcnt lgkmcnt(0)
	v_cndmask_b32_e64 v236, v236, v60, s[98:99]
	v_cndmask_b32_e64 v237, v237, v61, s[98:99]
	v_cndmask_b32_e64 v238, v238, v62, s[98:99]
	v_cndmask_b32_e64 v239, v239, v63, s[98:99]
	v_cndmask_b32_e64 v240, v56, v240, s[98:99]
	v_cndmask_b32_e64 v241, v57, v241, s[98:99]
	v_cndmask_b32_e64 v242, v58, v242, s[98:99]
	v_cndmask_b32_e64 v243, v59, v243, s[98:99]
	global_store_dwordx4 v[228:229], v[236:239], off
	global_store_dwordx4 v[232:233], v[240:243], off
	global_store_dwordx4 v[74:75], v[66:69], off
	global_load_dwordx4 v[66:69], v[76:77], off offset:512
	s_nop 0
	global_load_dwordx4 v[70:73], v[76:77], off offset:528
	v_mul_f32_e32 v61, v61, v61
	v_mul_f32_e32 v63, v63, v63
	v_mul_f32_e32 v57, v57, v57
	v_mul_f32_e32 v59, v59, v59
	v_fmac_f32_e32 v61, v60, v60
	v_fmac_f32_e32 v63, v62, v62
	v_fmac_f32_e32 v57, v56, v56
	v_fmac_f32_e32 v59, v58, v58
	v_add_f32_e32 v56, v61, v63
	v_add_f32_e32 v57, v57, v59
	v_add_f32_e32 v60, v56, v57
	s_waitcnt vmcnt(1)
	v_pk_add_f32 v[54:55], v[54:55], v[68:69]
	v_pk_add_f32 v[52:53], v[52:53], v[66:67]
	s_waitcnt vmcnt(0)
	v_pk_add_f32 v[58:59], v[50:51], v[72:73]
	v_pk_add_f32 v[56:57], v[48:49], v[70:71]
	v_mul_f32_e32 v48, v53, v53
	v_mul_f32_e32 v49, v55, v55
	v_mul_f32_e32 v50, v57, v57
	v_mul_f32_e32 v51, v59, v59
	v_fmac_f32_e32 v48, v52, v52
	v_fmac_f32_e32 v49, v54, v54
	v_fmac_f32_e32 v50, v56, v56
	v_fmac_f32_e32 v51, v58, v58
	v_add_f32_e32 v48, v48, v49
	v_add_f32_e32 v49, v50, v51
	v_add_f32_e32 v48, v48, v49
	v_add_f32_e32 v48, v60, v48
	ds_bpermute_b32 v49, v120, v48
	v_lshl_add_u64 v[228:229], v[76:77], 0, v[230:231]
	v_lshl_add_u64 v[232:233], v[76:77], 0, v[244:245]
	ds_swizzle_b32 v236, v56 offset:swizzle(SWAP,8)
	ds_swizzle_b32 v237, v57 offset:swizzle(SWAP,8)
	ds_swizzle_b32 v238, v58 offset:swizzle(SWAP,8)
	ds_swizzle_b32 v239, v59 offset:swizzle(SWAP,8)
	ds_swizzle_b32 v240, v52 offset:swizzle(SWAP,8)
	ds_swizzle_b32 v241, v53 offset:swizzle(SWAP,8)
	ds_swizzle_b32 v242, v54 offset:swizzle(SWAP,8)
	ds_swizzle_b32 v243, v55 offset:swizzle(SWAP,8)
	s_waitcnt lgkmcnt(0)
	v_cndmask_b32_e64 v236, v236, v52, s[98:99]
	v_cndmask_b32_e64 v237, v237, v53, s[98:99]
	v_cndmask_b32_e64 v238, v238, v54, s[98:99]
	v_cndmask_b32_e64 v239, v239, v55, s[98:99]
	v_cndmask_b32_e64 v240, v56, v240, s[98:99]
	v_cndmask_b32_e64 v241, v57, v241, s[98:99]
	v_cndmask_b32_e64 v242, v58, v242, s[98:99]
	v_cndmask_b32_e64 v243, v59, v243, s[98:99]
	global_store_dwordx4 v[228:229], v[236:239], off offset:512
	global_store_dwordx4 v[232:233], v[240:243], off offset:512
	v_cvt_pk_bf16_f32 v50, v52, v53
	v_cvt_pk_bf16_f32 v51, v54, v55
	v_cvt_pk_bf16_f32 v52, v56, v57
	s_waitcnt lgkmcnt(0)
	v_add_f32_e32 v48, v48, v49
	ds_bpermute_b32 v49, v114, v48
	v_cvt_pk_bf16_f32 v53, v58, v59
	global_store_dwordx4 v[74:75], v[50:53], off offset:256
	s_and_saveexec_b64 s[24:25], s[2:3]
	s_cbranch_execz .LBB0_855
	v_readlane_b32 s26, v254, 41
	s_waitcnt lgkmcnt(0)
	v_add_f32_e32 v50, v48, v49
	v_lshlrev_b64 v[48:49], 6, v[64:65]
	v_readlane_b32 s27, v254, 42
	s_lshl_b32 s6, s38, 2
	s_nop 0
	v_lshl_add_u64 v[48:49], s[26:27], 0, v[48:49]
	v_lshl_add_u64 v[48:49], s[22:23], 2, v[48:49]
	v_lshl_add_u64 v[48:49], v[48:49], 0, s[6:7]
	global_store_dword v[48:49], v50, off
; __device__ __forceinline__ unsigned cvt_pk_bf16(float lo, float hi) { const f32x2_t v = {lo, hi}; const bf16x2_t b = __builtin_convertvector(v, bf16x2_t); return __builtin_bit_cast(unsigned, b); }
;     __device__ __forceinline__ void operator()(const f32x4 (&acc)[2][2][4][2], const Unit& u, int wr, int wc, int fr, int fq, const PG8_LAS float*) const {
;     ...
;             for (int m = 0; m < 4; ++m) { const int row = row0 + ai * HALF + m * 16; const size_t off = (size_t)row * ldc + col0; float ss = 0.f;
; #pragma unroll
;                 for (int bj = 0; bj < 2; ++bj) {
;                     const f32x4 b0 = *(const f32x4*)(base + off + bj * HALF), b1 = *(const f32x4*)(base + off + bj * HALF + 4);
;                     const f32x4 v0 = b0 + acc[ai][bj][m][0], v1 = b1 + acc[ai][bj][m][1];
;                     *(f32x4*)(out + off + bj * HALF) = v0; *(f32x4*)(out + off + bj * HALF + 4) = v1;
;                     if (xb) { u32x4 w; w.x = cvt_pk_bf16(v0[0], v0[1]); w.y = cvt_pk_bf16(v0[2], v0[3]); w.z = cvt_pk_bf16(v1[0], v1[1]); w.w = cvt_pk_bf16(v1[2], v1[3]);
;                         *(u32x4*)(xb + off + bj * HALF) = w;
;                         ss += ((v0[0] * v0[0] + v0[1] * v0[1]) + (v0[2] * v0[2] + v0[3] * v0[3])) + ((v1[0] * v1[0] + v1[1] * v1[1]) + (v1[2] * v1[2] + v1[3] * v1[3])); } }
;                 if (xb) { ss += __shfl_xor(ss, 16); ss += __shfl_xor(ss, 32); if (fq == 0) ssq[(size_t)row * 16 + u.pn * 4 + wc] = ss; } }
.LBB0_855:
	s_or_b64 exec, exec, s[24:25]
	v_add_u32_e32 v48, 0x90, v146
	s_waitcnt lgkmcnt(0)
	v_ashrrev_i32_e32 v49, 31, v48
	v_lshlrev_b64 v[50:51], 10, v[48:49]
	v_lshl_add_u64 v[58:59], v[50:51], 0, v[144:145]
	v_lshl_add_u64 v[60:61], v[58:59], 2, s[68:69]
	global_load_dwordx4 v[50:53], v[60:61], off
	global_load_dwordx4 v[54:57], v[60:61], off offset:16
	v_readlane_b32 s24, v254, 39
	v_readlane_b32 s25, v254, 40
	s_waitcnt vmcnt(1)
	v_pk_add_f32 v[46:47], v[46:47], v[52:53]
	v_pk_add_f32 v[44:45], v[44:45], v[50:51]
	s_waitcnt vmcnt(0)
	v_pk_add_f32 v[42:43], v[42:43], v[56:57]
	v_pk_add_f32 v[40:41], v[40:41], v[54:55]
	v_lshl_add_u64 v[58:59], v[58:59], 1, s[24:25]
	v_cvt_pk_bf16_f32 v50, v44, v45
	v_cvt_pk_bf16_f32 v51, v46, v47
	v_cvt_pk_bf16_f32 v52, v40, v41
	v_cvt_pk_bf16_f32 v53, v42, v43
	v_lshl_add_u64 v[228:229], v[60:61], 0, v[230:231]
	v_lshl_add_u64 v[232:233], v[60:61], 0, v[244:245]
	ds_swizzle_b32 v236, v40 offset:swizzle(SWAP,8)
	ds_swizzle_b32 v237, v41 offset:swizzle(SWAP,8)
	ds_swizzle_b32 v238, v42 offset:swizzle(SWAP,8)
	ds_swizzle_b32 v239, v43 offset:swizzle(SWAP,8)
	ds_swizzle_b32 v240, v44 offset:swizzle(SWAP,8)
	ds_swizzle_b32 v241, v45 offset:swizzle(SWAP,8)
	ds_swizzle_b32 v242, v46 offset:swizzle(SWAP,8)
	ds_swizzle_b32 v243, v47 offset:swizzle(SWAP,8)
	s_waitcnt lgkmcnt(0)
	v_cndmask_b32_e64 v236, v236, v44, s[98:99]
	v_cndmask_b32_e64 v237, v237, v45, s[98:99]
	v_cndmask_b32_e64 v238, v238, v46, s[98:99]
	v_cndmask_b32_e64 v239, v239, v47, s[98:99]
	v_cndmask_b32_e64 v240, v40, v240, s[98:99]
	v_cndmask_b32_e64 v241, v41, v241, s[98:99]
	v_cndmask_b32_e64 v242, v42, v242, s[98:99]
	v_cndmask_b32_e64 v243, v43, v243, s[98:99]
	global_store_dwordx4 v[228:229], v[236:239], off
	global_store_dwordx4 v[232:233], v[240:243], off
	global_store_dwordx4 v[58:59], v[50:53], off
	global_load_dwordx4 v[50:53], v[60:61], off offset:512
	s_nop 0
	global_load_dwordx4 v[54:57], v[60:61], off offset:528
	v_mul_f32_e32 v45, v45, v45
	v_mul_f32_e32 v47, v47, v47
	v_mul_f32_e32 v41, v41, v41
	v_mul_f32_e32 v43, v43, v43
	v_fmac_f32_e32 v45, v44, v44
	v_fmac_f32_e32 v47, v46, v46
	v_fmac_f32_e32 v41, v40, v40
	v_fmac_f32_e32 v43, v42, v42
	v_add_f32_e32 v40, v45, v47
	v_add_f32_e32 v41, v41, v43
	v_add_f32_e32 v44, v40, v41
	s_waitcnt vmcnt(1)
	v_pk_add_f32 v[38:39], v[38:39], v[52:53]
	v_pk_add_f32 v[36:37], v[36:37], v[50:51]
	s_waitcnt vmcnt(0)
	v_pk_add_f32 v[42:43], v[34:35], v[56:57]
	v_pk_add_f32 v[40:41], v[32:33], v[54:55]
	v_mul_f32_e32 v32, v37, v37
	v_mul_f32_e32 v33, v39, v39
	v_mul_f32_e32 v34, v41, v41
	v_mul_f32_e32 v35, v43, v43
	v_fmac_f32_e32 v32, v36, v36
	v_fmac_f32_e32 v33, v38, v38
	v_fmac_f32_e32 v34, v40, v40
	v_fmac_f32_e32 v35, v42, v42
	v_add_f32_e32 v32, v32, v33
	v_add_f32_e32 v33, v34, v35
	v_add_f32_e32 v32, v32, v33
	v_add_f32_e32 v32, v44, v32
	ds_bpermute_b32 v33, v120, v32
	v_lshl_add_u64 v[228:229], v[60:61], 0, v[230:231]
	v_lshl_add_u64 v[232:233], v[60:61], 0, v[244:245]
	ds_swizzle_b32 v236, v40 offset:swizzle(SWAP,8)
	ds_swizzle_b32 v237, v41 offset:swizzle(SWAP,8)
	ds_swizzle_b32 v238, v42 offset:swizzle(SWAP,8)
	ds_swizzle_b32 v239, v43 offset:swizzle(SWAP,8)
	ds_swizzle_b32 v240, v36 offset:swizzle(SWAP,8)
	ds_swizzle_b32 v241, v37 offset:swizzle(SWAP,8)
	ds_swizzle_b32 v242, v38 offset:swizzle(SWAP,8)
	ds_swizzle_b32 v243, v39 offset:swizzle(SWAP,8)
	s_waitcnt lgkmcnt(0)
	v_cndmask_b32_e64 v236, v236, v36, s[98:99]
	v_cndmask_b32_e64 v237, v237, v37, s[98:99]
	v_cndmask_b32_e64 v238, v238, v38, s[98:99]
	v_cndmask_b32_e64 v239, v239, v39, s[98:99]
	v_cndmask_b32_e64 v240, v40, v240, s[98:99]
	v_cndmask_b32_e64 v241, v41, v241, s[98:99]
	v_cndmask_b32_e64 v242, v42, v242, s[98:99]
	v_cndmask_b32_e64 v243, v43, v243, s[98:99]
	global_store_dwordx4 v[228:229], v[236:239], off offset:512
	global_store_dwordx4 v[232:233], v[240:243], off offset:512
	v_cvt_pk_bf16_f32 v34, v36, v37
	v_cvt_pk_bf16_f32 v35, v38, v39
	v_cvt_pk_bf16_f32 v36, v40, v41
	s_waitcnt lgkmcnt(0)
	v_add_f32_e32 v32, v32, v33
	ds_bpermute_b32 v33, v114, v32
	v_cvt_pk_bf16_f32 v37, v42, v43
	global_store_dwordx4 v[58:59], v[34:37], off offset:256
	s_and_saveexec_b64 s[24:25], s[2:3]
	s_cbranch_execz .LBB0_857
	v_readlane_b32 s26, v254, 41
	s_waitcnt lgkmcnt(0)
	v_add_f32_e32 v34, v32, v33
	v_lshlrev_b64 v[32:33], 6, v[48:49]
	v_readlane_b32 s27, v254, 42
	s_lshl_b32 s6, s38, 2
	s_nop 0
	v_lshl_add_u64 v[32:33], s[26:27], 0, v[32:33]
	v_lshl_add_u64 v[32:33], s[22:23], 2, v[32:33]
	v_lshl_add_u64 v[32:33], v[32:33], 0, s[6:7]
	global_store_dword v[32:33], v34, off
; __device__ __forceinline__ unsigned cvt_pk_bf16(float lo, float hi) { const f32x2_t v = {lo, hi}; const bf16x2_t b = __builtin_convertvector(v, bf16x2_t); return __builtin_bit_cast(unsigned, b); }
;     __device__ __forceinline__ void operator()(const f32x4 (&acc)[2][2][4][2], const Unit& u, int wr, int wc, int fr, int fq, const PG8_LAS float*) const {
;     ...
;             for (int m = 0; m < 4; ++m) { const int row = row0 + ai * HALF + m * 16; const size_t off = (size_t)row * ldc + col0; float ss = 0.f;
; #pragma unroll
;                 for (int bj = 0; bj < 2; ++bj) {
;                     const f32x4 b0 = *(const f32x4*)(base + off + bj * HALF), b1 = *(const f32x4*)(base + off + bj * HALF + 4);
;                     const f32x4 v0 = b0 + acc[ai][bj][m][0], v1 = b1 + acc[ai][bj][m][1];
;                     *(f32x4*)(out + off + bj * HALF) = v0; *(f32x4*)(out + off + bj * HALF + 4) = v1;
;                     if (xb) { u32x4 w; w.x = cvt_pk_bf16(v0[0], v0[1]); w.y = cvt_pk_bf16(v0[2], v0[3]); w.z = cvt_pk_bf16(v1[0], v1[1]); w.w = cvt_pk_bf16(v1[2], v1[3]);
;                         *(u32x4*)(xb + off + bj * HALF) = w;
;                         ss += ((v0[0] * v0[0] + v0[1] * v0[1]) + (v0[2] * v0[2] + v0[3] * v0[3])) + ((v1[0] * v1[0] + v1[1] * v1[1]) + (v1[2] * v1[2] + v1[3] * v1[3])); } }
;                 if (xb) { ss += __shfl_xor(ss, 16); ss += __shfl_xor(ss, 32); if (fq == 0) ssq[(size_t)row * 16 + u.pn * 4 + wc] = ss; } }
.LBB0_857:
	s_or_b64 exec, exec, s[24:25]
	v_add_u32_e32 v32, 0xa0, v146
	s_waitcnt lgkmcnt(0)
	v_ashrrev_i32_e32 v33, 31, v32
	v_lshlrev_b64 v[34:35], 10, v[32:33]
	v_lshl_add_u64 v[42:43], v[34:35], 0, v[144:145]
	v_lshl_add_u64 v[44:45], v[42:43], 2, s[68:69]
	global_load_dwordx4 v[34:37], v[44:45], off
	global_load_dwordx4 v[38:41], v[44:45], off offset:16
	v_readlane_b32 s24, v254, 39
	v_readlane_b32 s25, v254, 40
	s_waitcnt vmcnt(1)
	v_pk_add_f32 v[30:31], v[30:31], v[36:37]
	v_pk_add_f32 v[28:29], v[28:29], v[34:35]
	s_waitcnt vmcnt(0)
	v_pk_add_f32 v[26:27], v[26:27], v[40:41]
	v_pk_add_f32 v[24:25], v[24:25], v[38:39]
	v_lshl_add_u64 v[42:43], v[42:43], 1, s[24:25]
	v_cvt_pk_bf16_f32 v34, v28, v29
	v_cvt_pk_bf16_f32 v35, v30, v31
	v_cvt_pk_bf16_f32 v36, v24, v25
	v_cvt_pk_bf16_f32 v37, v26, v27
	v_lshl_add_u64 v[228:229], v[44:45], 0, v[230:231]
	v_lshl_add_u64 v[232:233], v[44:45], 0, v[244:245]
	ds_swizzle_b32 v236, v24 offset:swizzle(SWAP,8)
	ds_swizzle_b32 v237, v25 offset:swizzle(SWAP,8)
	ds_swizzle_b32 v238, v26 offset:swizzle(SWAP,8)
	ds_swizzle_b32 v239, v27 offset:swizzle(SWAP,8)
	ds_swizzle_b32 v240, v28 offset:swizzle(SWAP,8)
	ds_swizzle_b32 v241, v29 offset:swizzle(SWAP,8)
	ds_swizzle_b32 v242, v30 offset:swizzle(SWAP,8)
	ds_swizzle_b32 v243, v31 offset:swizzle(SWAP,8)
	s_waitcnt lgkmcnt(0)
	v_cndmask_b32_e64 v236, v236, v28, s[98:99]
	v_cndmask_b32_e64 v237, v237, v29, s[98:99]
	v_cndmask_b32_e64 v238, v238, v30, s[98:99]
	v_cndmask_b32_e64 v239, v239, v31, s[98:99]
	v_cndmask_b32_e64 v240, v24, v240, s[98:99]
	v_cndmask_b32_e64 v241, v25, v241, s[98:99]
	v_cndmask_b32_e64 v242, v26, v242, s[98:99]
	v_cndmask_b32_e64 v243, v27, v243, s[98:99]
	global_store_dwordx4 v[228:229], v[236:239], off
	global_store_dwordx4 v[232:233], v[240:243], off
	global_store_dwordx4 v[42:43], v[34:37], off
	global_load_dwordx4 v[34:37], v[44:45], off offset:512
	s_nop 0
	global_load_dwordx4 v[38:41], v[44:45], off offset:528
	v_mul_f32_e32 v29, v29, v29
	v_mul_f32_e32 v31, v31, v31
	v_mul_f32_e32 v25, v25, v25
	v_mul_f32_e32 v27, v27, v27
	v_fmac_f32_e32 v29, v28, v28
	v_fmac_f32_e32 v31, v30, v30
	v_fmac_f32_e32 v25, v24, v24
	v_fmac_f32_e32 v27, v26, v26
	v_add_f32_e32 v24, v29, v31
	v_add_f32_e32 v25, v25, v27
	v_add_f32_e32 v28, v24, v25
	s_waitcnt vmcnt(1)
	v_pk_add_f32 v[22:23], v[22:23], v[36:37]
	v_pk_add_f32 v[20:21], v[20:21], v[34:35]
	s_waitcnt vmcnt(0)
	v_pk_add_f32 v[26:27], v[18:19], v[40:41]
	v_pk_add_f32 v[24:25], v[16:17], v[38:39]
	v_mul_f32_e32 v16, v21, v21
	v_mul_f32_e32 v17, v23, v23
	v_mul_f32_e32 v18, v25, v25
	v_mul_f32_e32 v19, v27, v27
	v_fmac_f32_e32 v16, v20, v20
	v_fmac_f32_e32 v17, v22, v22
	v_fmac_f32_e32 v18, v24, v24
	v_fmac_f32_e32 v19, v26, v26
	v_add_f32_e32 v16, v16, v17
	v_add_f32_e32 v17, v18, v19
	v_add_f32_e32 v16, v16, v17
	v_add_f32_e32 v16, v28, v16
	ds_bpermute_b32 v17, v120, v16
	v_lshl_add_u64 v[228:229], v[44:45], 0, v[230:231]
	v_lshl_add_u64 v[232:233], v[44:45], 0, v[244:245]
	ds_swizzle_b32 v236, v24 offset:swizzle(SWAP,8)
	ds_swizzle_b32 v237, v25 offset:swizzle(SWAP,8)
	ds_swizzle_b32 v238, v26 offset:swizzle(SWAP,8)
	ds_swizzle_b32 v239, v27 offset:swizzle(SWAP,8)
	ds_swizzle_b32 v240, v20 offset:swizzle(SWAP,8)
	ds_swizzle_b32 v241, v21 offset:swizzle(SWAP,8)
	ds_swizzle_b32 v242, v22 offset:swizzle(SWAP,8)
	ds_swizzle_b32 v243, v23 offset:swizzle(SWAP,8)
	s_waitcnt lgkmcnt(0)
	v_cndmask_b32_e64 v236, v236, v20, s[98:99]
	v_cndmask_b32_e64 v237, v237, v21, s[98:99]
	v_cndmask_b32_e64 v238, v238, v22, s[98:99]
	v_cndmask_b32_e64 v239, v239, v23, s[98:99]
	v_cndmask_b32_e64 v240, v24, v240, s[98:99]
	v_cndmask_b32_e64 v241, v25, v241, s[98:99]
	v_cndmask_b32_e64 v242, v26, v242, s[98:99]
	v_cndmask_b32_e64 v243, v27, v243, s[98:99]
	global_store_dwordx4 v[228:229], v[236:239], off offset:512
	global_store_dwordx4 v[232:233], v[240:243], off offset:512
	v_cvt_pk_bf16_f32 v18, v20, v21
	v_cvt_pk_bf16_f32 v19, v22, v23
	v_cvt_pk_bf16_f32 v20, v24, v25
	s_waitcnt lgkmcnt(0)
	v_add_f32_e32 v16, v16, v17
	ds_bpermute_b32 v17, v114, v16
	v_cvt_pk_bf16_f32 v21, v26, v27
	global_store_dwordx4 v[42:43], v[18:21], off offset:256
	s_and_saveexec_b64 s[24:25], s[2:3]
	s_cbranch_execz .LBB0_859
	v_readlane_b32 s26, v254, 41
	s_waitcnt lgkmcnt(0)
	v_add_f32_e32 v18, v16, v17
	v_lshlrev_b64 v[16:17], 6, v[32:33]
	v_readlane_b32 s27, v254, 42
	s_lshl_b32 s6, s38, 2
	s_nop 0
	v_lshl_add_u64 v[16:17], s[26:27], 0, v[16:17]
	v_lshl_add_u64 v[16:17], s[22:23], 2, v[16:17]
	v_lshl_add_u64 v[16:17], v[16:17], 0, s[6:7]
	global_store_dword v[16:17], v18, off
; __device__ __forceinline__ unsigned cvt_pk_bf16(float lo, float hi) { const f32x2_t v = {lo, hi}; const bf16x2_t b = __builtin_convertvector(v, bf16x2_t); return __builtin_bit_cast(unsigned, b); }
;     __device__ __forceinline__ void operator()(const f32x4 (&acc)[2][2][4][2], const Unit& u, int wr, int wc, int fr, int fq, const PG8_LAS float*) const {
;     ...
;             for (int m = 0; m < 4; ++m) { const int row = row0 + ai * HALF + m * 16; const size_t off = (size_t)row * ldc + col0; float ss = 0.f;
; #pragma unroll
;                 for (int bj = 0; bj < 2; ++bj) {
;                     const f32x4 b0 = *(const f32x4*)(base + off + bj * HALF), b1 = *(const f32x4*)(base + off + bj * HALF + 4);
;                     const f32x4 v0 = b0 + acc[ai][bj][m][0], v1 = b1 + acc[ai][bj][m][1];
;                     *(f32x4*)(out + off + bj * HALF) = v0; *(f32x4*)(out + off + bj * HALF + 4) = v1;
;                     if (xb) { u32x4 w; w.x = cvt_pk_bf16(v0[0], v0[1]); w.y = cvt_pk_bf16(v0[2], v0[3]); w.z = cvt_pk_bf16(v1[0], v1[1]); w.w = cvt_pk_bf16(v1[2], v1[3]);
;                         *(u32x4*)(xb + off + bj * HALF) = w;
;                         ss += ((v0[0] * v0[0] + v0[1] * v0[1]) + (v0[2] * v0[2] + v0[3] * v0[3])) + ((v1[0] * v1[0] + v1[1] * v1[1]) + (v1[2] * v1[2] + v1[3] * v1[3])); } }
;                 if (xb) { ss += __shfl_xor(ss, 16); ss += __shfl_xor(ss, 32); if (fq == 0) ssq[(size_t)row * 16 + u.pn * 4 + wc] = ss; } }
.LBB0_859:
	s_or_b64 exec, exec, s[24:25]
	v_add_u32_e32 v16, 0xb0, v146
	s_waitcnt lgkmcnt(0)
	v_ashrrev_i32_e32 v17, 31, v16
	v_lshlrev_b64 v[18:19], 10, v[16:17]
	v_lshl_add_u64 v[26:27], v[18:19], 0, v[144:145]
	v_lshl_add_u64 v[28:29], v[26:27], 2, s[68:69]
	global_load_dwordx4 v[18:21], v[28:29], off
	global_load_dwordx4 v[22:25], v[28:29], off offset:16
	v_readlane_b32 s24, v254, 39
	v_readlane_b32 s25, v254, 40
	s_waitcnt vmcnt(1)
	v_pk_add_f32 v[14:15], v[14:15], v[20:21]
	v_pk_add_f32 v[12:13], v[12:13], v[18:19]
	s_waitcnt vmcnt(0)
	v_pk_add_f32 v[10:11], v[10:11], v[24:25]
	v_pk_add_f32 v[8:9], v[8:9], v[22:23]
	v_lshl_add_u64 v[26:27], v[26:27], 1, s[24:25]
	v_cvt_pk_bf16_f32 v18, v12, v13
	v_cvt_pk_bf16_f32 v19, v14, v15
	v_cvt_pk_bf16_f32 v20, v8, v9
	v_cvt_pk_bf16_f32 v21, v10, v11
	v_lshl_add_u64 v[228:229], v[28:29], 0, v[230:231]
	v_lshl_add_u64 v[232:233], v[28:29], 0, v[244:245]
	ds_swizzle_b32 v236, v8 offset:swizzle(SWAP,8)
	ds_swizzle_b32 v237, v9 offset:swizzle(SWAP,8)
	ds_swizzle_b32 v238, v10 offset:swizzle(SWAP,8)
	ds_swizzle_b32 v239, v11 offset:swizzle(SWAP,8)
	ds_swizzle_b32 v240, v12 offset:swizzle(SWAP,8)
	ds_swizzle_b32 v241, v13 offset:swizzle(SWAP,8)
	ds_swizzle_b32 v242, v14 offset:swizzle(SWAP,8)
	ds_swizzle_b32 v243, v15 offset:swizzle(SWAP,8)
	s_waitcnt lgkmcnt(0)
	v_cndmask_b32_e64 v236, v236, v12, s[98:99]
	v_cndmask_b32_e64 v237, v237, v13, s[98:99]
	v_cndmask_b32_e64 v238, v238, v14, s[98:99]
	v_cndmask_b32_e64 v239, v239, v15, s[98:99]
	v_cndmask_b32_e64 v240, v8, v240, s[98:99]
	v_cndmask_b32_e64 v241, v9, v241, s[98:99]
	v_cndmask_b32_e64 v242, v10, v242, s[98:99]
	v_cndmask_b32_e64 v243, v11, v243, s[98:99]
	global_store_dwordx4 v[228:229], v[236:239], off
	global_store_dwordx4 v[232:233], v[240:243], off
	global_store_dwordx4 v[26:27], v[18:21], off
	global_load_dwordx4 v[18:21], v[28:29], off offset:512
	s_nop 0
	global_load_dwordx4 v[22:25], v[28:29], off offset:528
	v_mul_f32_e32 v13, v13, v13
	v_mul_f32_e32 v15, v15, v15
	v_mul_f32_e32 v9, v9, v9
	v_mul_f32_e32 v11, v11, v11
	v_fmac_f32_e32 v13, v12, v12
	v_fmac_f32_e32 v15, v14, v14
	v_fmac_f32_e32 v9, v8, v8
	v_fmac_f32_e32 v11, v10, v10
	v_add_f32_e32 v8, v13, v15
	v_add_f32_e32 v9, v9, v11
	v_add_f32_e32 v12, v8, v9
	s_waitcnt vmcnt(1)
	v_pk_add_f32 v[6:7], v[6:7], v[20:21]
	v_pk_add_f32 v[4:5], v[4:5], v[18:19]
	s_waitcnt vmcnt(0)
	v_pk_add_f32 v[10:11], v[2:3], v[24:25]
	v_pk_add_f32 v[8:9], v[0:1], v[22:23]
	v_mul_f32_e32 v0, v5, v5
	v_mul_f32_e32 v1, v7, v7
	v_mul_f32_e32 v2, v9, v9
	v_mul_f32_e32 v3, v11, v11
	v_fmac_f32_e32 v0, v4, v4
	v_fmac_f32_e32 v1, v6, v6
	v_fmac_f32_e32 v2, v8, v8
	v_fmac_f32_e32 v3, v10, v10
	v_add_f32_e32 v0, v0, v1
	v_add_f32_e32 v1, v2, v3
	v_add_f32_e32 v0, v0, v1
	v_add_f32_e32 v0, v12, v0
	ds_bpermute_b32 v1, v120, v0
	v_lshl_add_u64 v[228:229], v[28:29], 0, v[230:231]
	v_lshl_add_u64 v[232:233], v[28:29], 0, v[244:245]
	ds_swizzle_b32 v236, v8 offset:swizzle(SWAP,8)
	ds_swizzle_b32 v237, v9 offset:swizzle(SWAP,8)
	ds_swizzle_b32 v238, v10 offset:swizzle(SWAP,8)
	ds_swizzle_b32 v239, v11 offset:swizzle(SWAP,8)
	ds_swizzle_b32 v240, v4 offset:swizzle(SWAP,8)
	ds_swizzle_b32 v241, v5 offset:swizzle(SWAP,8)
	ds_swizzle_b32 v242, v6 offset:swizzle(SWAP,8)
	ds_swizzle_b32 v243, v7 offset:swizzle(SWAP,8)
	s_waitcnt lgkmcnt(0)
	v_cndmask_b32_e64 v236, v236, v4, s[98:99]
	v_cndmask_b32_e64 v237, v237, v5, s[98:99]
	v_cndmask_b32_e64 v238, v238, v6, s[98:99]
	v_cndmask_b32_e64 v239, v239, v7, s[98:99]
	v_cndmask_b32_e64 v240, v8, v240, s[98:99]
	v_cndmask_b32_e64 v241, v9, v241, s[98:99]
	v_cndmask_b32_e64 v242, v10, v242, s[98:99]
	v_cndmask_b32_e64 v243, v11, v243, s[98:99]
	global_store_dwordx4 v[228:229], v[236:239], off offset:512
	global_store_dwordx4 v[232:233], v[240:243], off offset:512
	v_cvt_pk_bf16_f32 v2, v4, v5
	v_cvt_pk_bf16_f32 v3, v6, v7
	v_cvt_pk_bf16_f32 v4, v8, v9
	s_waitcnt lgkmcnt(0)
	v_add_f32_e32 v0, v0, v1
	ds_bpermute_b32 v1, v114, v0
	v_cvt_pk_bf16_f32 v5, v10, v11
	global_store_dwordx4 v[26:27], v[2:5], off offset:256
	s_and_saveexec_b64 s[24:25], s[2:3]
	s_cbranch_execz .LBB0_861
	v_readlane_b32 s26, v254, 41
	s_waitcnt lgkmcnt(0)
	v_add_f32_e32 v2, v0, v1
	v_lshlrev_b64 v[0:1], 6, v[16:17]
	v_readlane_b32 s27, v254, 42
	s_lshl_b32 s6, s38, 2
	s_nop 0
	v_lshl_add_u64 v[0:1], s[26:27], 0, v[0:1]
	v_lshl_add_u64 v[0:1], s[22:23], 2, v[0:1]
	v_lshl_add_u64 v[0:1], v[0:1], 0, s[6:7]
	global_store_dword v[0:1], v2, off

; #define PG8_STAGE(bufoff, gbase, voff) do { _Pragma("unroll") for (int _i = 0; _i < 2; ++_i) \
;         __builtin_amdgcn_global_load_lds((const unsigned*)((const char*)(gbase) + (voff)[_i]), (PG8_LAS unsigned*)(lds + (bufoff) + ldsw + _i * 8192), 16, 0, 0); } while (0)
; #define PG8_LDA(dst, b, h) do { _Pragma("unroll") for (int m = 0; m < 4; ++m) _Pragma("unroll") for (int k = 0; k < 2; ++k) dst[m][k] = *(const PG8_LAS bf16x8*)(lds + PG8_SA(b, h) + aoff + m * 2048 + k * 1024); } while (0)
; #define PG8_LDB(dst, b, h) do { _Pragma("unroll") for (int n = 0; n < 2; ++n) _Pragma("unroll") for (int k = 0; k < 2; ++k) dst[n][k] = *(const PG8_LAS bf16x8*)(lds + PG8_SB(b, h) + boff + n * 2048 + k * 1024); } while (0)
; #define PG8_MMA(ai, bj, At, Bt) do { __builtin_amdgcn_s_setprio(1); _Pragma("unroll") for (int m = 0; m < 4; ++m) _Pragma("unroll") for (int n = 0; n < 2; ++n) _Pragma("unroll") for (int k = 0; k < 2; ++k) \
;         acc[ai][bj][m][n] = __builtin_amdgcn_mfma_f32_16x16x32_bf16(Bt[n][k], At[m][k], acc[ai][bj][m][n], 0, 0, 0); __builtin_amdgcn_s_setprio(0); } while (0)
; #define PG8_WAIT_V(n) asm volatile("s_waitcnt vmcnt(" #n ")" ::: "memory")
; #define PG8_WAIT_L(n) asm volatile("s_waitcnt lgkmcnt(" #n ")" ::: "memory")
; #define PG8_BAR __builtin_amdgcn_s_barrier()
; #define PG8_SCHED __builtin_amdgcn_sched_barrier(0)
; template <class Epi, class Sched, bool ALIGN_EPI = false, bool SP2 = false>
; __device__ __forceinline__ void gemm_phase(PG8_LAS unsigned char* lds, const Gemm g, const Sched& S, const Epi& E) {
;     ...
;             PG8_LDB(B0, 0, 0); PG8_LDB(B1, 0, 1); PG8_SCHED; PG8_LDA(At, 0, 0); PG8_STAGE(PG8_SA(1, 1), a1 + hstep, voffA);
;             PG8_WAIT_V(8); PG8_WAIT_L(0); PG8_BAR; PG8_MMA(0, 0, At, B0); PG8_MMA(0, 1, At, B1); PG8_BAR; PG8_SCHED;
;             PG8_LDA(At, 0, 1); PG8_STAGE(PG8_SB(0, 0), b2, voffB); PG8_STAGE(PG8_SB(0, 1), b2 + hstep, voffB); PG8_STAGE(PG8_SA(0, 0), a2, voffA);
;             PG8_WAIT_V(8); PG8_WAIT_L(0); PG8_BAR; PG8_MMA(1, 0, At, B0); PG8_MMA(1, 1, At, B1); PG8_BAR; PG8_SCHED;
.LBB0_1641:
	ds_read_b128 v[144:147], v153
	ds_read_b128 v[156:159], v153 offset:1024
	ds_read_b128 v[160:163], v153 offset:2048
	ds_read_b128 v[164:167], v153 offset:3072
	ds_read_b128 v[168:171], v154
	ds_read_b128 v[172:175], v154 offset:1024
	ds_read_b128 v[176:179], v154 offset:2048
	ds_read_b128 v[180:183], v154 offset:3072
	s_add_u32 s30, s28, 0xfff00080
	s_addc_u32 s31, s29, -1
	s_cmp_eq_u32 s58, 60
	s_cselect_b32 s35, s21, s31
	s_cselect_b32 s34, s54, s30
	s_cselect_b32 s31, s19, s57
	s_cselect_b32 s30, s55, s56
	v_lshl_add_u64 v[148:149], s[28:29], 0, v[136:137]
	s_add_i32 m0, s39, 0xc000
	ds_read_b128 v[184:187], v155
	ds_read_b128 v[188:191], v155 offset:1024
	ds_read_b128 v[192:195], v155 offset:2048
	ds_read_b128 v[196:199], v155 offset:3072
	ds_read_b128 v[200:203], v155 offset:4096
	ds_read_b128 v[204:207], v155 offset:5120
	ds_read_b128 v[208:211], v155 offset:6144
	ds_read_b128 v[212:215], v155 offset:7168
	global_load_lds_dwordx4 v[148:149], off
	v_lshl_add_u64 v[148:149], s[28:29], 0, v[138:139]
	s_add_i32 m0, s39, 0xe000
	s_nop 0
	global_load_lds_dwordx4 v[148:149], off
	s_waitcnt vmcnt(8)
	s_waitcnt lgkmcnt(0)
	s_barrier
	s_setprio 1
	s_waitcnt lgkmcnt(0)
	v_mfma_f32_16x16x32_bf16 v[124:127], v[144:147], v[184:187], v[124:127]
	v_mfma_f32_16x16x32_bf16 v[120:123], v[160:163], v[184:187], v[120:123]
	v_mfma_f32_16x16x32_bf16 v[108:111], v[144:147], v[192:195], v[108:111]
	v_mfma_f32_16x16x32_bf16 v[104:107], v[160:163], v[192:195], v[104:107]
	v_mfma_f32_16x16x32_bf16 v[92:95], v[144:147], v[200:203], v[92:95]
	v_mfma_f32_16x16x32_bf16 v[88:91], v[160:163], v[200:203], v[88:91]
	v_mfma_f32_16x16x32_bf16 v[76:79], v[144:147], v[208:211], v[76:79]
	v_mfma_f32_16x16x32_bf16 v[72:75], v[160:163], v[208:211], v[72:75]
	v_mfma_f32_16x16x32_bf16 v[124:127], v[156:159], v[188:191], v[124:127]
	v_mfma_f32_16x16x32_bf16 v[120:123], v[164:167], v[188:191], v[120:123]
	v_mfma_f32_16x16x32_bf16 v[108:111], v[156:159], v[196:199], v[108:111]
	v_mfma_f32_16x16x32_bf16 v[104:107], v[164:167], v[196:199], v[104:107]
	v_mfma_f32_16x16x32_bf16 v[92:95], v[156:159], v[204:207], v[92:95]
	v_mfma_f32_16x16x32_bf16 v[88:91], v[164:167], v[204:207], v[88:91]
	v_mfma_f32_16x16x32_bf16 v[76:79], v[156:159], v[212:215], v[76:79]
	v_mfma_f32_16x16x32_bf16 v[72:75], v[164:167], v[212:215], v[72:75]
	s_setprio 0
	s_setprio 1
	v_mfma_f32_16x16x32_bf16 v[116:119], v[168:171], v[184:187], v[116:119]
	v_mfma_f32_16x16x32_bf16 v[112:115], v[176:179], v[184:187], v[112:115]
	v_mfma_f32_16x16x32_bf16 v[100:103], v[168:171], v[192:195], v[100:103]
	v_mfma_f32_16x16x32_bf16 v[96:99], v[176:179], v[192:195], v[96:99]
	v_mfma_f32_16x16x32_bf16 v[84:87], v[168:171], v[200:203], v[84:87]
	v_mfma_f32_16x16x32_bf16 v[80:83], v[176:179], v[200:203], v[80:83]
	v_mfma_f32_16x16x32_bf16 v[68:71], v[168:171], v[208:211], v[68:71]
	v_mfma_f32_16x16x32_bf16 v[64:67], v[176:179], v[208:211], v[64:67]
	v_mfma_f32_16x16x32_bf16 v[116:119], v[172:175], v[188:191], v[116:119]
	v_mfma_f32_16x16x32_bf16 v[112:115], v[180:183], v[188:191], v[112:115]
	v_mfma_f32_16x16x32_bf16 v[100:103], v[172:175], v[196:199], v[100:103]
	v_mfma_f32_16x16x32_bf16 v[96:99], v[180:183], v[196:199], v[96:99]
	v_mfma_f32_16x16x32_bf16 v[84:87], v[172:175], v[204:207], v[84:87]
	v_mfma_f32_16x16x32_bf16 v[80:83], v[180:183], v[204:207], v[80:83]
	v_mfma_f32_16x16x32_bf16 v[68:71], v[172:175], v[212:215], v[68:71]
	v_mfma_f32_16x16x32_bf16 v[64:67], v[180:183], v[212:215], v[64:67]
	s_setprio 0
	s_barrier
	s_add_i32 s59, s48, s38
	v_lshl_add_u64 v[148:149], s[30:31], 0, v[130:131]
	s_mov_b32 m0, s59
	ds_read_b128 v[184:187], v155 offset:16384
	ds_read_b128 v[188:191], v155 offset:17408
	ds_read_b128 v[192:195], v155 offset:18432
	ds_read_b128 v[196:199], v155 offset:19456
	ds_read_b128 v[200:203], v155 offset:20480
	ds_read_b128 v[204:207], v155 offset:21504
	ds_read_b128 v[208:211], v155 offset:22528
	ds_read_b128 v[212:215], v155 offset:23552
	global_load_lds_dwordx4 v[148:149], off
	s_add_i32 m0, s59, 0x2000
	s_add_u32 s60, s30, 0x100000
	v_lshl_add_u64 v[216:217], s[30:31], 0, v[134:135]
	s_addc_u32 s61, s31, 0
	s_add_i32 s59, s49, s38
	global_load_lds_dwordx4 v[216:217], off
	v_lshl_add_u64 v[218:219], s[60:61], 0, v[130:131]
	s_mov_b32 m0, s59
	v_lshl_add_u64 v[220:221], s[34:35], 0, v[132:133]
	global_load_lds_dwordx4 v[218:219], off
	v_lshl_add_u64 v[218:219], s[60:61], 0, v[134:135]
	s_add_i32 m0, s59, 0x2000
	s_nop 0
	global_load_lds_dwordx4 v[218:219], off
	v_lshl_add_u64 v[218:219], s[34:35], 0, v[128:129]
	s_mov_b32 m0, s39
	s_nop 0
	global_load_lds_dwordx4 v[218:219], off
	s_mov_b32 m0, s40
	s_nop 0
	global_load_lds_dwordx4 v[220:221], off
	s_waitcnt vmcnt(8)
	s_waitcnt lgkmcnt(0)
	s_barrier
; #define PG8_STAGE(bufoff, gbase, voff) do { _Pragma("unroll") for (int _i = 0; _i < 2; ++_i) \
;         __builtin_amdgcn_global_load_lds((const unsigned*)((const char*)(gbase) + (voff)[_i]), (PG8_LAS unsigned*)(lds + (bufoff) + ldsw + _i * 8192), 16, 0, 0); } while (0)
; #define PG8_LDA(dst, b, h) do { _Pragma("unroll") for (int m = 0; m < 4; ++m) _Pragma("unroll") for (int k = 0; k < 2; ++k) dst[m][k] = *(const PG8_LAS bf16x8*)(lds + PG8_SA(b, h) + aoff + m * 2048 + k * 1024); } while (0)
; #define PG8_LDB(dst, b, h) do { _Pragma("unroll") for (int n = 0; n < 2; ++n) _Pragma("unroll") for (int k = 0; k < 2; ++k) dst[n][k] = *(const PG8_LAS bf16x8*)(lds + PG8_SB(b, h) + boff + n * 2048 + k * 1024); } while (0)
; #define PG8_MMA(ai, bj, At, Bt) do { __builtin_amdgcn_s_setprio(1); _Pragma("unroll") for (int m = 0; m < 4; ++m) _Pragma("unroll") for (int n = 0; n < 2; ++n) _Pragma("unroll") for (int k = 0; k < 2; ++k) \
;         acc[ai][bj][m][n] = __builtin_amdgcn_mfma_f32_16x16x32_bf16(Bt[n][k], At[m][k], acc[ai][bj][m][n], 0, 0, 0); __builtin_amdgcn_s_setprio(0); } while (0)
; #define PG8_WAIT_V(n) asm volatile("s_waitcnt vmcnt(" #n ")" ::: "memory")
; #define PG8_WAIT_L(n) asm volatile("s_waitcnt lgkmcnt(" #n ")" ::: "memory")
; #define PG8_BAR __builtin_amdgcn_s_barrier()
; #define PG8_SCHED __builtin_amdgcn_sched_barrier(0)
; template <class Epi, class Sched, bool ALIGN_EPI = false, bool SP2 = false>
; __device__ __forceinline__ void gemm_phase(PG8_LAS unsigned char* lds, const Gemm g, const Sched& S, const Epi& E) {
;     ...
;             PG8_WAIT_V(8); PG8_WAIT_L(0); PG8_BAR; PG8_MMA(1, 0, At, B0); PG8_MMA(1, 1, At, B1); PG8_BAR; PG8_SCHED;
;             PG8_LDB(B0, 1, 0); PG8_LDB(B1, 1, 1); PG8_SCHED; PG8_LDA(At, 1, 0); PG8_STAGE(PG8_SA(0, 1), a2 + hstep, voffA);
;             PG8_WAIT_V(8); PG8_WAIT_L(0); PG8_BAR; PG8_MMA(0, 0, At, B0); PG8_MMA(0, 1, At, B1); PG8_BAR; PG8_SCHED;
;             PG8_LDA(At, 1, 1); PG8_STAGE(PG8_SB(1, 0), b3, voffB); PG8_STAGE(PG8_SB(1, 1), b3 + hstep, voffB); PG8_STAGE(PG8_SA(1, 0), a3, voffA);
	s_setprio 1
	s_waitcnt lgkmcnt(0)
	v_mfma_f32_16x16x32_bf16 v[60:63], v[144:147], v[184:187], v[60:63]
	v_mfma_f32_16x16x32_bf16 v[56:59], v[160:163], v[184:187], v[56:59]
	v_mfma_f32_16x16x32_bf16 v[44:47], v[144:147], v[192:195], v[44:47]
	v_mfma_f32_16x16x32_bf16 v[40:43], v[160:163], v[192:195], v[40:43]
	v_mfma_f32_16x16x32_bf16 v[28:31], v[144:147], v[200:203], v[28:31]
	v_mfma_f32_16x16x32_bf16 v[24:27], v[160:163], v[200:203], v[24:27]
	v_mfma_f32_16x16x32_bf16 v[12:15], v[144:147], v[208:211], v[12:15]
	v_mfma_f32_16x16x32_bf16 v[8:11], v[160:163], v[208:211], v[8:11]
	v_mfma_f32_16x16x32_bf16 v[60:63], v[156:159], v[188:191], v[60:63]
	v_mfma_f32_16x16x32_bf16 v[56:59], v[164:167], v[188:191], v[56:59]
	v_mfma_f32_16x16x32_bf16 v[44:47], v[156:159], v[196:199], v[44:47]
	v_mfma_f32_16x16x32_bf16 v[40:43], v[164:167], v[196:199], v[40:43]
	v_mfma_f32_16x16x32_bf16 v[28:31], v[156:159], v[204:207], v[28:31]
	v_mfma_f32_16x16x32_bf16 v[24:27], v[164:167], v[204:207], v[24:27]
	v_mfma_f32_16x16x32_bf16 v[12:15], v[156:159], v[212:215], v[12:15]
	v_mfma_f32_16x16x32_bf16 v[8:11], v[164:167], v[212:215], v[8:11]
	s_setprio 0
	s_setprio 1
	v_mfma_f32_16x16x32_bf16 v[52:55], v[168:171], v[184:187], v[52:55]
	v_mfma_f32_16x16x32_bf16 v[48:51], v[176:179], v[184:187], v[48:51]
	v_mfma_f32_16x16x32_bf16 v[36:39], v[168:171], v[192:195], v[36:39]
	v_mfma_f32_16x16x32_bf16 v[32:35], v[176:179], v[192:195], v[32:35]
	v_mfma_f32_16x16x32_bf16 v[20:23], v[168:171], v[200:203], v[20:23]
	v_mfma_f32_16x16x32_bf16 v[16:19], v[176:179], v[200:203], v[16:19]
	v_mfma_f32_16x16x32_bf16 v[4:7], v[168:171], v[208:211], v[4:7]
	v_mfma_f32_16x16x32_bf16 v[0:3], v[176:179], v[208:211], v[0:3]
	v_mfma_f32_16x16x32_bf16 v[52:55], v[172:175], v[188:191], v[52:55]
	v_mfma_f32_16x16x32_bf16 v[48:51], v[180:183], v[188:191], v[48:51]
	v_mfma_f32_16x16x32_bf16 v[36:39], v[172:175], v[196:199], v[36:39]
	v_mfma_f32_16x16x32_bf16 v[32:35], v[180:183], v[196:199], v[32:35]
	v_mfma_f32_16x16x32_bf16 v[20:23], v[172:175], v[204:207], v[20:23]
	v_mfma_f32_16x16x32_bf16 v[16:19], v[180:183], v[204:207], v[16:19]
	v_mfma_f32_16x16x32_bf16 v[4:7], v[172:175], v[212:215], v[4:7]
	v_mfma_f32_16x16x32_bf16 v[0:3], v[180:183], v[212:215], v[0:3]
	s_setprio 0
	s_barrier
	s_add_i32 s59, 0, 0x18000
	s_add_i32 s60, 0, 0x1c000
	v_add_u32_e32 v164, s59, v151
	v_add_u32_e32 v180, s60, v151
	ds_read_b128 v[144:147], v164
	ds_read_b128 v[156:159], v164 offset:1024
	ds_read_b128 v[160:163], v164 offset:2048
	ds_read_b128 v[164:167], v164 offset:3072
	ds_read_b128 v[168:171], v180
	ds_read_b128 v[172:175], v180 offset:1024
	ds_read_b128 v[176:179], v180 offset:2048
	ds_read_b128 v[180:183], v180 offset:3072
	s_add_u32 s34, s34, 0x100000
	s_addc_u32 s35, s35, 0
	s_mov_b32 m0, s41
	v_lshl_add_u64 v[222:223], s[34:35], 0, v[128:129]
	ds_read_b128 v[184:187], v155 offset:32768
	ds_read_b128 v[188:191], v155 offset:33792
	ds_read_b128 v[192:195], v155 offset:34816
	ds_read_b128 v[196:199], v155 offset:35840
	ds_read_b128 v[200:203], v155 offset:36864
	ds_read_b128 v[204:207], v155 offset:37888
	ds_read_b128 v[208:211], v155 offset:38912
	ds_read_b128 v[212:215], v155 offset:39936
	global_load_lds_dwordx4 v[222:223], off
	v_lshl_add_u64 v[222:223], s[34:35], 0, v[132:133]
	s_mov_b32 m0, s42
	s_nop 0
	global_load_lds_dwordx4 v[222:223], off
	s_waitcnt vmcnt(8)
	s_waitcnt lgkmcnt(0)
	s_barrier
	s_setprio 1
	s_waitcnt lgkmcnt(0)
	v_mfma_f32_16x16x32_bf16 v[124:127], v[144:147], v[184:187], v[124:127]
	v_mfma_f32_16x16x32_bf16 v[120:123], v[160:163], v[184:187], v[120:123]
	v_mfma_f32_16x16x32_bf16 v[108:111], v[144:147], v[192:195], v[108:111]
	v_mfma_f32_16x16x32_bf16 v[104:107], v[160:163], v[192:195], v[104:107]
	v_mfma_f32_16x16x32_bf16 v[92:95], v[144:147], v[200:203], v[92:95]
	v_mfma_f32_16x16x32_bf16 v[88:91], v[160:163], v[200:203], v[88:91]
	v_mfma_f32_16x16x32_bf16 v[76:79], v[144:147], v[208:211], v[76:79]
	v_mfma_f32_16x16x32_bf16 v[72:75], v[160:163], v[208:211], v[72:75]
	v_mfma_f32_16x16x32_bf16 v[124:127], v[156:159], v[188:191], v[124:127]
	v_mfma_f32_16x16x32_bf16 v[120:123], v[164:167], v[188:191], v[120:123]
	v_mfma_f32_16x16x32_bf16 v[108:111], v[156:159], v[196:199], v[108:111]
	v_mfma_f32_16x16x32_bf16 v[104:107], v[164:167], v[196:199], v[104:107]
	v_mfma_f32_16x16x32_bf16 v[92:95], v[156:159], v[204:207], v[92:95]
	v_mfma_f32_16x16x32_bf16 v[88:91], v[164:167], v[204:207], v[88:91]
	v_mfma_f32_16x16x32_bf16 v[76:79], v[156:159], v[212:215], v[76:79]
	v_mfma_f32_16x16x32_bf16 v[72:75], v[164:167], v[212:215], v[72:75]
	s_setprio 0
	s_setprio 1
	v_mfma_f32_16x16x32_bf16 v[116:119], v[168:171], v[184:187], v[116:119]
	v_mfma_f32_16x16x32_bf16 v[112:115], v[176:179], v[184:187], v[112:115]
	v_mfma_f32_16x16x32_bf16 v[100:103], v[168:171], v[192:195], v[100:103]
	v_mfma_f32_16x16x32_bf16 v[96:99], v[176:179], v[192:195], v[96:99]
	v_mfma_f32_16x16x32_bf16 v[84:87], v[168:171], v[200:203], v[84:87]
	v_mfma_f32_16x16x32_bf16 v[80:83], v[176:179], v[200:203], v[80:83]
	v_mfma_f32_16x16x32_bf16 v[68:71], v[168:171], v[208:211], v[68:71]
	v_mfma_f32_16x16x32_bf16 v[64:67], v[176:179], v[208:211], v[64:67]
	v_mfma_f32_16x16x32_bf16 v[116:119], v[172:175], v[188:191], v[116:119]
	v_mfma_f32_16x16x32_bf16 v[112:115], v[180:183], v[188:191], v[112:115]
	v_mfma_f32_16x16x32_bf16 v[100:103], v[172:175], v[196:199], v[100:103]
	v_mfma_f32_16x16x32_bf16 v[96:99], v[180:183], v[196:199], v[96:99]
	v_mfma_f32_16x16x32_bf16 v[84:87], v[172:175], v[204:207], v[84:87]
	v_mfma_f32_16x16x32_bf16 v[80:83], v[180:183], v[204:207], v[80:83]
	v_mfma_f32_16x16x32_bf16 v[68:71], v[172:175], v[212:215], v[68:71]
	v_mfma_f32_16x16x32_bf16 v[64:67], v[180:183], v[212:215], v[64:67]
	s_setprio 0
	s_barrier
; #define PG8_STAGE(bufoff, gbase, voff) do { _Pragma("unroll") for (int _i = 0; _i < 2; ++_i) \
;         __builtin_amdgcn_global_load_lds((const unsigned*)((const char*)(gbase) + (voff)[_i]), (PG8_LAS unsigned*)(lds + (bufoff) + ldsw + _i * 8192), 16, 0, 0); } while (0)
; #define PG8_LDA(dst, b, h) do { _Pragma("unroll") for (int m = 0; m < 4; ++m) _Pragma("unroll") for (int k = 0; k < 2; ++k) dst[m][k] = *(const PG8_LAS bf16x8*)(lds + PG8_SA(b, h) + aoff + m * 2048 + k * 1024); } while (0)
; #define PG8_MMA(ai, bj, At, Bt) do { __builtin_amdgcn_s_setprio(1); _Pragma("unroll") for (int m = 0; m < 4; ++m) _Pragma("unroll") for (int n = 0; n < 2; ++n) _Pragma("unroll") for (int k = 0; k < 2; ++k) \
;         acc[ai][bj][m][n] = __builtin_amdgcn_mfma_f32_16x16x32_bf16(Bt[n][k], At[m][k], acc[ai][bj][m][n], 0, 0, 0); __builtin_amdgcn_s_setprio(0); } while (0)
; #define PG8_WAIT_V(n) asm volatile("s_waitcnt vmcnt(" #n ")" ::: "memory")
; #define PG8_WAIT_L(n) asm volatile("s_waitcnt lgkmcnt(" #n ")" ::: "memory")
;     __device__ __forceinline__ void operator()(const f32x4 (&acc)[2][2][4][2], const Unit& u, int wr, int wc, int fr, int fq, const PG8_LAS float*) const {
;         const int row0 = u.pm * BM + wr * 64 + fr; const int col0 = u.pn * BM + wc * 32 + 8 * fq;
; #pragma unroll
;         for (int ai = 0; ai < 2; ++ai)
; #pragma unroll
;             for (int m = 0; m < 4; ++m) { const int row = row0 + ai * HALF + m * 16; const size_t off = (size_t)row * ldc + col0; float ss = 0.f;
; #pragma unroll
;                 for (int bj = 0; bj < 2; ++bj) {
;                     const f32x4 b0 = *(const f32x4*)(base + off + bj * HALF), b1 = *(const f32x4*)(base + off + bj * HALF + 4);
;                     const f32x4 v0 = b0 + acc[ai][bj][m][0], v1 = b1 + acc[ai][bj][m][1];
;                     *(f32x4*)(out + off + bj * HALF) = v0; *(f32x4*)(out + off + bj * HALF + 4) = v1;
; template <class Epi, class Sched, bool ALIGN_EPI = false, bool SP2 = false>
; __device__ __forceinline__ void gemm_phase(PG8_LAS unsigned char* lds, const Gemm g, const Sched& S, const Epi& E) {
;     ...
;             PG8_LDA(At, 1, 1); PG8_STAGE(PG8_SB(1, 0), b3, voffB); PG8_STAGE(PG8_SB(1, 1), b3 + hstep, voffB); PG8_STAGE(PG8_SA(1, 0), a3, voffA);
;             PG8_WAIT_V(8); PG8_WAIT_L(0); PG8_BAR; PG8_MMA(1, 0, At, B0); PG8_MMA(1, 1, At, B1); PG8_BAR; PG8_SCHED;
	s_add_i32 s34, s59, s38
	v_lshl_add_u64 v[148:149], v[148:149], 0, s[6:7]
	s_mov_b32 m0, s34
	ds_read_b128 v[184:187], v155 offset:49152
	ds_read_b128 v[188:191], v155 offset:50176
	ds_read_b128 v[192:195], v155 offset:51200
	ds_read_b128 v[196:199], v155 offset:52224
	ds_read_b128 v[200:203], v155 offset:53248
	ds_read_b128 v[204:207], v155 offset:54272
	ds_read_b128 v[208:211], v155 offset:55296
	ds_read_b128 v[212:215], v155 offset:56320
	global_load_lds_dwordx4 v[148:149], off
	s_add_i32 m0, s34, 0x2000
	s_add_u32 s30, s30, 0x100080
	v_lshl_add_u64 v[148:149], v[216:217], 0, s[6:7]
	s_addc_u32 s31, s31, 0
	s_add_i32 s34, s60, s38
	global_load_lds_dwordx4 v[148:149], off
	v_lshl_add_u64 v[148:149], s[30:31], 0, v[130:131]
	s_mov_b32 m0, s34
	s_nop 0
	global_load_lds_dwordx4 v[148:149], off
	v_lshl_add_u64 v[148:149], s[30:31], 0, v[134:135]
	s_add_i32 m0, s34, 0x2000
	s_nop 0
	global_load_lds_dwordx4 v[148:149], off
	v_lshl_add_u64 v[148:149], v[218:219], 0, s[6:7]
	s_mov_b32 m0, s44
	s_nop 0
	global_load_lds_dwordx4 v[148:149], off
	v_lshl_add_u64 v[148:149], v[220:221], 0, s[6:7]
	s_mov_b32 m0, s45
	s_nop 0
	global_load_lds_dwordx4 v[148:149], off
	s_waitcnt vmcnt(8)
	s_waitcnt lgkmcnt(0)
	s_barrier
	s_setprio 1
	s_waitcnt lgkmcnt(0)
	v_mfma_f32_16x16x32_bf16 v[60:63], v[144:147], v[184:187], v[60:63]
	v_mfma_f32_16x16x32_bf16 v[56:59], v[160:163], v[184:187], v[56:59]
	v_mfma_f32_16x16x32_bf16 v[44:47], v[144:147], v[192:195], v[44:47]
	v_mfma_f32_16x16x32_bf16 v[40:43], v[160:163], v[192:195], v[40:43]
	v_mfma_f32_16x16x32_bf16 v[28:31], v[144:147], v[200:203], v[28:31]
	v_mfma_f32_16x16x32_bf16 v[24:27], v[160:163], v[200:203], v[24:27]
	v_mfma_f32_16x16x32_bf16 v[12:15], v[144:147], v[208:211], v[12:15]
	v_mfma_f32_16x16x32_bf16 v[8:11], v[160:163], v[208:211], v[8:11]
	v_mfma_f32_16x16x32_bf16 v[60:63], v[156:159], v[188:191], v[60:63]
	v_mfma_f32_16x16x32_bf16 v[56:59], v[164:167], v[188:191], v[56:59]
	v_mfma_f32_16x16x32_bf16 v[44:47], v[156:159], v[196:199], v[44:47]
	v_mfma_f32_16x16x32_bf16 v[40:43], v[164:167], v[196:199], v[40:43]
	v_mfma_f32_16x16x32_bf16 v[28:31], v[156:159], v[204:207], v[28:31]
	v_mfma_f32_16x16x32_bf16 v[24:27], v[164:167], v[204:207], v[24:27]
	v_mfma_f32_16x16x32_bf16 v[12:15], v[156:159], v[212:215], v[12:15]
	v_mfma_f32_16x16x32_bf16 v[8:11], v[164:167], v[212:215], v[8:11]
	s_setprio 0
	s_setprio 1
	v_mfma_f32_16x16x32_bf16 v[52:55], v[168:171], v[184:187], v[52:55]
	v_mfma_f32_16x16x32_bf16 v[48:51], v[176:179], v[184:187], v[48:51]
	v_mfma_f32_16x16x32_bf16 v[36:39], v[168:171], v[192:195], v[36:39]
	v_mfma_f32_16x16x32_bf16 v[32:35], v[176:179], v[192:195], v[32:35]
	v_mfma_f32_16x16x32_bf16 v[20:23], v[168:171], v[200:203], v[20:23]
	v_mfma_f32_16x16x32_bf16 v[16:19], v[176:179], v[200:203], v[16:19]
	v_mfma_f32_16x16x32_bf16 v[4:7], v[168:171], v[208:211], v[4:7]
	v_mfma_f32_16x16x32_bf16 v[0:3], v[176:179], v[208:211], v[0:3]
	v_mfma_f32_16x16x32_bf16 v[52:55], v[172:175], v[188:191], v[52:55]
	v_mfma_f32_16x16x32_bf16 v[48:51], v[180:183], v[188:191], v[48:51]
	v_mfma_f32_16x16x32_bf16 v[36:39], v[172:175], v[196:199], v[36:39]
	v_mfma_f32_16x16x32_bf16 v[32:35], v[180:183], v[196:199], v[32:35]
	v_mfma_f32_16x16x32_bf16 v[20:23], v[172:175], v[204:207], v[20:23]
	v_mfma_f32_16x16x32_bf16 v[16:19], v[180:183], v[204:207], v[16:19]
	v_mfma_f32_16x16x32_bf16 v[4:7], v[172:175], v[212:215], v[4:7]
	v_mfma_f32_16x16x32_bf16 v[0:3], v[180:183], v[212:215], v[0:3]
	s_setprio 0
	s_barrier
	s_add_i32 s58, s58, 2
	s_add_u32 s28, s28, 0x100
	s_addc_u32 s29, s29, 0
	s_add_u32 s56, s56, 0x100
	s_addc_u32 s57, s57, 0
	s_cmp_gt_u32 s58, 61
	s_cbranch_scc0 .LBB0_1641
	v_mbcnt_lo_u32_b32 v234, -1, 0
	v_mbcnt_hi_u32_b32 v234, -1, v234
	v_bfe_u32 v234, v234, 3, 1
	v_sub_u32_e32 v231, 0, v234
	v_and_b32_e32 v230, 0xffff8010, v231
	v_and_b32_e32 v235, 0x7ff0, v231
	v_sub_u32_e32 v244, 0x8000, v235
	v_mov_b32_e32 v245, 0
	s_mov_b32 s98, 0xff00ff
	s_mov_b32 s99, 0xff00ff
	s_and_b64 vcc, exec, s[8:9]
	s_cbranch_vccz .LBB0_1644
	s_barrier
.LBB0_1644:
	v_lshl_add_u32 v146, s26, 8, v150
	v_lshl_or_b32 v144, s27, 8, v152
	v_ashrrev_i32_e32 v147, 31, v146
	v_ashrrev_i32_e32 v145, 31, v144
	v_lshlrev_b64 v[148:149], 12, v[146:147]
	v_lshl_add_u64 v[156:157], s[68:69], 0, v[148:149]
	v_lshlrev_b64 v[148:149], 2, v[144:145]
	v_lshl_add_u64 v[144:145], v[156:157], 0, v[148:149]
	global_load_dwordx4 v[156:159], v[144:145], off offset:16
	global_load_dwordx4 v[160:163], v[144:145], off
	s_mov_b64 s[26:27], -1
	s_waitcnt vmcnt(0)
	v_pk_add_f32 v[122:123], v[122:123], v[158:159]
	v_pk_add_f32 v[126:127], v[126:127], v[162:163]
	v_pk_add_f32 v[124:125], v[124:125], v[160:161]
	v_pk_add_f32 v[120:121], v[120:121], v[156:157]
	v_lshl_add_u64 v[228:229], v[144:145], 0, v[230:231]
	v_lshl_add_u64 v[232:233], v[144:145], 0, v[244:245]
	ds_swizzle_b32 v236, v120 offset:swizzle(SWAP,8)
	ds_swizzle_b32 v237, v121 offset:swizzle(SWAP,8)
	ds_swizzle_b32 v238, v122 offset:swizzle(SWAP,8)
	ds_swizzle_b32 v239, v123 offset:swizzle(SWAP,8)
	ds_swizzle_b32 v240, v124 offset:swizzle(SWAP,8)
	ds_swizzle_b32 v241, v125 offset:swizzle(SWAP,8)
	ds_swizzle_b32 v242, v126 offset:swizzle(SWAP,8)
	ds_swizzle_b32 v243, v127 offset:swizzle(SWAP,8)
	s_waitcnt lgkmcnt(0)
	v_cndmask_b32_e64 v236, v236, v124, s[98:99]
	v_cndmask_b32_e64 v237, v237, v125, s[98:99]
	v_cndmask_b32_e64 v238, v238, v126, s[98:99]
	v_cndmask_b32_e64 v239, v239, v127, s[98:99]
	v_cndmask_b32_e64 v240, v120, v240, s[98:99]
	v_cndmask_b32_e64 v241, v121, v241, s[98:99]
	v_cndmask_b32_e64 v242, v122, v242, s[98:99]
	v_cndmask_b32_e64 v243, v123, v243, s[98:99]
	global_store_dwordx4 v[228:229], v[236:239], off
	global_store_dwordx4 v[232:233], v[240:243], off
	global_load_dwordx4 v[120:123], v[144:145], off offset:528
	s_nop 0
	global_load_dwordx4 v[124:127], v[144:145], off offset:512
	s_waitcnt vmcnt(1)
;     __device__ __forceinline__ void operator()(const f32x4 (&acc)[2][2][4][2], const Unit& u, int wr, int wc, int fr, int fq, const PG8_LAS float*) const {
;     ...
;             for (int m = 0; m < 4; ++m) { const int row = row0 + ai * HALF + m * 16; const size_t off = (size_t)row * ldc + col0; float ss = 0.f;
; #pragma unroll
;                 for (int bj = 0; bj < 2; ++bj) {
;                     const f32x4 b0 = *(const f32x4*)(base + off + bj * HALF), b1 = *(const f32x4*)(base + off + bj * HALF + 4);
;                     const f32x4 v0 = b0 + acc[ai][bj][m][0], v1 = b1 + acc[ai][bj][m][1];
;                     *(f32x4*)(out + off + bj * HALF) = v0; *(f32x4*)(out + off + bj * HALF + 4) = v1;
	v_pk_add_f32 v[112:113], v[112:113], v[120:121]
	s_waitcnt vmcnt(0)
	v_pk_add_f32 v[118:119], v[118:119], v[126:127]
	v_pk_add_f32 v[116:117], v[116:117], v[124:125]
	v_pk_add_f32 v[114:115], v[114:115], v[122:123]
	v_lshl_add_u64 v[228:229], v[144:145], 0, v[230:231]
	v_lshl_add_u64 v[232:233], v[144:145], 0, v[244:245]
	ds_swizzle_b32 v236, v112 offset:swizzle(SWAP,8)
	ds_swizzle_b32 v237, v113 offset:swizzle(SWAP,8)
	ds_swizzle_b32 v238, v114 offset:swizzle(SWAP,8)
	ds_swizzle_b32 v239, v115 offset:swizzle(SWAP,8)
	ds_swizzle_b32 v240, v116 offset:swizzle(SWAP,8)
	ds_swizzle_b32 v241, v117 offset:swizzle(SWAP,8)
	ds_swizzle_b32 v242, v118 offset:swizzle(SWAP,8)
	ds_swizzle_b32 v243, v119 offset:swizzle(SWAP,8)
	s_waitcnt lgkmcnt(0)
	v_cndmask_b32_e64 v236, v236, v116, s[98:99]
	v_cndmask_b32_e64 v237, v237, v117, s[98:99]
	v_cndmask_b32_e64 v238, v238, v118, s[98:99]
	v_cndmask_b32_e64 v239, v239, v119, s[98:99]
	v_cndmask_b32_e64 v240, v112, v240, s[98:99]
	v_cndmask_b32_e64 v241, v113, v241, s[98:99]
	v_cndmask_b32_e64 v242, v114, v242, s[98:99]
	v_cndmask_b32_e64 v243, v115, v243, s[98:99]
	global_store_dwordx4 v[228:229], v[236:239], off offset:512
	global_store_dwordx4 v[232:233], v[240:243], off offset:512
	s_nop 1
	v_or_b32_e32 v112, 16, v146
	v_ashrrev_i32_e32 v113, 31, v112
	v_lshlrev_b64 v[112:113], 12, v[112:113]
	v_lshl_add_u64 v[112:113], s[68:69], 0, v[112:113]
	v_lshl_add_u64 v[120:121], v[112:113], 0, v[148:149]
	global_load_dwordx4 v[112:115], v[120:121], off offset:16
	global_load_dwordx4 v[116:119], v[120:121], off
	s_waitcnt vmcnt(1)
	v_pk_add_f32 v[106:107], v[106:107], v[114:115]
	s_waitcnt vmcnt(0)
	v_pk_add_f32 v[110:111], v[110:111], v[118:119]
	v_pk_add_f32 v[108:109], v[108:109], v[116:117]
	v_pk_add_f32 v[104:105], v[104:105], v[112:113]
	v_lshl_add_u64 v[228:229], v[120:121], 0, v[230:231]
	v_lshl_add_u64 v[232:233], v[120:121], 0, v[244:245]
	ds_swizzle_b32 v236, v104 offset:swizzle(SWAP,8)
	ds_swizzle_b32 v237, v105 offset:swizzle(SWAP,8)
	ds_swizzle_b32 v238, v106 offset:swizzle(SWAP,8)
	ds_swizzle_b32 v239, v107 offset:swizzle(SWAP,8)
	ds_swizzle_b32 v240, v108 offset:swizzle(SWAP,8)
	ds_swizzle_b32 v241, v109 offset:swizzle(SWAP,8)
	ds_swizzle_b32 v242, v110 offset:swizzle(SWAP,8)
	ds_swizzle_b32 v243, v111 offset:swizzle(SWAP,8)
	s_waitcnt lgkmcnt(0)
	v_cndmask_b32_e64 v236, v236, v108, s[98:99]
	v_cndmask_b32_e64 v237, v237, v109, s[98:99]
	v_cndmask_b32_e64 v238, v238, v110, s[98:99]
	v_cndmask_b32_e64 v239, v239, v111, s[98:99]
	v_cndmask_b32_e64 v240, v104, v240, s[98:99]
	v_cndmask_b32_e64 v241, v105, v241, s[98:99]
	v_cndmask_b32_e64 v242, v106, v242, s[98:99]
	v_cndmask_b32_e64 v243, v107, v243, s[98:99]
	global_store_dwordx4 v[228:229], v[236:239], off
	global_store_dwordx4 v[232:233], v[240:243], off
	global_load_dwordx4 v[104:107], v[120:121], off offset:528
	s_nop 0
	global_load_dwordx4 v[108:111], v[120:121], off offset:512
	s_waitcnt vmcnt(1)
	v_pk_add_f32 v[96:97], v[96:97], v[104:105]
	s_waitcnt vmcnt(0)
	v_pk_add_f32 v[102:103], v[102:103], v[110:111]
	v_pk_add_f32 v[100:101], v[100:101], v[108:109]
	v_pk_add_f32 v[98:99], v[98:99], v[106:107]
	v_lshl_add_u64 v[228:229], v[120:121], 0, v[230:231]
	v_lshl_add_u64 v[232:233], v[120:121], 0, v[244:245]
	ds_swizzle_b32 v236, v96 offset:swizzle(SWAP,8)
	ds_swizzle_b32 v237, v97 offset:swizzle(SWAP,8)
	ds_swizzle_b32 v238, v98 offset:swizzle(SWAP,8)
	ds_swizzle_b32 v239, v99 offset:swizzle(SWAP,8)
	ds_swizzle_b32 v240, v100 offset:swizzle(SWAP,8)
	ds_swizzle_b32 v241, v101 offset:swizzle(SWAP,8)
	ds_swizzle_b32 v242, v102 offset:swizzle(SWAP,8)
	ds_swizzle_b32 v243, v103 offset:swizzle(SWAP,8)
	s_waitcnt lgkmcnt(0)
	v_cndmask_b32_e64 v236, v236, v100, s[98:99]
	v_cndmask_b32_e64 v237, v237, v101, s[98:99]
	v_cndmask_b32_e64 v238, v238, v102, s[98:99]
	v_cndmask_b32_e64 v239, v239, v103, s[98:99]
	v_cndmask_b32_e64 v240, v96, v240, s[98:99]
	v_cndmask_b32_e64 v241, v97, v241, s[98:99]
	v_cndmask_b32_e64 v242, v98, v242, s[98:99]
	v_cndmask_b32_e64 v243, v99, v243, s[98:99]
	global_store_dwordx4 v[228:229], v[236:239], off offset:512
	global_store_dwordx4 v[232:233], v[240:243], off offset:512
	s_nop 1
	v_or_b32_e32 v96, 32, v146
	v_ashrrev_i32_e32 v97, 31, v96
	v_lshlrev_b64 v[96:97], 12, v[96:97]
	v_lshl_add_u64 v[96:97], s[68:69], 0, v[96:97]
	v_lshl_add_u64 v[104:105], v[96:97], 0, v[148:149]
	global_load_dwordx4 v[96:99], v[104:105], off offset:16
	global_load_dwordx4 v[100:103], v[104:105], off
	s_waitcnt vmcnt(1)
	v_pk_add_f32 v[90:91], v[90:91], v[98:99]
	s_waitcnt vmcnt(0)
	v_pk_add_f32 v[94:95], v[94:95], v[102:103]
	v_pk_add_f32 v[92:93], v[92:93], v[100:101]
	v_pk_add_f32 v[88:89], v[88:89], v[96:97]
	v_lshl_add_u64 v[228:229], v[104:105], 0, v[230:231]
	v_lshl_add_u64 v[232:233], v[104:105], 0, v[244:245]
	ds_swizzle_b32 v236, v88 offset:swizzle(SWAP,8)
	ds_swizzle_b32 v237, v89 offset:swizzle(SWAP,8)
	ds_swizzle_b32 v238, v90 offset:swizzle(SWAP,8)
	ds_swizzle_b32 v239, v91 offset:swizzle(SWAP,8)
	ds_swizzle_b32 v240, v92 offset:swizzle(SWAP,8)
	ds_swizzle_b32 v241, v93 offset:swizzle(SWAP,8)
	ds_swizzle_b32 v242, v94 offset:swizzle(SWAP,8)
	ds_swizzle_b32 v243, v95 offset:swizzle(SWAP,8)
	s_waitcnt lgkmcnt(0)
	v_cndmask_b32_e64 v236, v236, v92, s[98:99]
	v_cndmask_b32_e64 v237, v237, v93, s[98:99]
	v_cndmask_b32_e64 v238, v238, v94, s[98:99]
	v_cndmask_b32_e64 v239, v239, v95, s[98:99]
	v_cndmask_b32_e64 v240, v88, v240, s[98:99]
	v_cndmask_b32_e64 v241, v89, v241, s[98:99]
	v_cndmask_b32_e64 v242, v90, v242, s[98:99]
	v_cndmask_b32_e64 v243, v91, v243, s[98:99]
	global_store_dwordx4 v[228:229], v[236:239], off
	global_store_dwordx4 v[232:233], v[240:243], off
	global_load_dwordx4 v[88:91], v[104:105], off offset:528
	s_nop 0
	global_load_dwordx4 v[92:95], v[104:105], off offset:512
	s_waitcnt vmcnt(1)
;     __device__ __forceinline__ void operator()(const f32x4 (&acc)[2][2][4][2], const Unit& u, int wr, int wc, int fr, int fq, const PG8_LAS float*) const {
;     ...
;             for (int m = 0; m < 4; ++m) { const int row = row0 + ai * HALF + m * 16; const size_t off = (size_t)row * ldc + col0; float ss = 0.f;
; #pragma unroll
;                 for (int bj = 0; bj < 2; ++bj) {
;                     const f32x4 b0 = *(const f32x4*)(base + off + bj * HALF), b1 = *(const f32x4*)(base + off + bj * HALF + 4);
;                     const f32x4 v0 = b0 + acc[ai][bj][m][0], v1 = b1 + acc[ai][bj][m][1];
;                     *(f32x4*)(out + off + bj * HALF) = v0; *(f32x4*)(out + off + bj * HALF + 4) = v1;
	v_pk_add_f32 v[80:81], v[80:81], v[88:89]
	s_waitcnt vmcnt(0)
	v_pk_add_f32 v[86:87], v[86:87], v[94:95]
	v_pk_add_f32 v[84:85], v[84:85], v[92:93]
	v_pk_add_f32 v[82:83], v[82:83], v[90:91]
	v_lshl_add_u64 v[228:229], v[104:105], 0, v[230:231]
	v_lshl_add_u64 v[232:233], v[104:105], 0, v[244:245]
	ds_swizzle_b32 v236, v80 offset:swizzle(SWAP,8)
	ds_swizzle_b32 v237, v81 offset:swizzle(SWAP,8)
	ds_swizzle_b32 v238, v82 offset:swizzle(SWAP,8)
	ds_swizzle_b32 v239, v83 offset:swizzle(SWAP,8)
	ds_swizzle_b32 v240, v84 offset:swizzle(SWAP,8)
	ds_swizzle_b32 v241, v85 offset:swizzle(SWAP,8)
	ds_swizzle_b32 v242, v86 offset:swizzle(SWAP,8)
	ds_swizzle_b32 v243, v87 offset:swizzle(SWAP,8)
	s_waitcnt lgkmcnt(0)
	v_cndmask_b32_e64 v236, v236, v84, s[98:99]
	v_cndmask_b32_e64 v237, v237, v85, s[98:99]
	v_cndmask_b32_e64 v238, v238, v86, s[98:99]
	v_cndmask_b32_e64 v239, v239, v87, s[98:99]
	v_cndmask_b32_e64 v240, v80, v240, s[98:99]
	v_cndmask_b32_e64 v241, v81, v241, s[98:99]
	v_cndmask_b32_e64 v242, v82, v242, s[98:99]
	v_cndmask_b32_e64 v243, v83, v243, s[98:99]
	global_store_dwordx4 v[228:229], v[236:239], off offset:512
	global_store_dwordx4 v[232:233], v[240:243], off offset:512
	s_nop 1
	v_or_b32_e32 v80, 48, v146
	v_ashrrev_i32_e32 v81, 31, v80
	v_lshlrev_b64 v[80:81], 12, v[80:81]
	v_lshl_add_u64 v[80:81], s[68:69], 0, v[80:81]
	v_lshl_add_u64 v[88:89], v[80:81], 0, v[148:149]
	global_load_dwordx4 v[80:83], v[88:89], off offset:16
	global_load_dwordx4 v[84:87], v[88:89], off
	s_waitcnt vmcnt(1)
	v_pk_add_f32 v[74:75], v[74:75], v[82:83]
	s_waitcnt vmcnt(0)
	v_pk_add_f32 v[78:79], v[78:79], v[86:87]
	v_pk_add_f32 v[76:77], v[76:77], v[84:85]
	v_pk_add_f32 v[72:73], v[72:73], v[80:81]
	v_lshl_add_u64 v[228:229], v[88:89], 0, v[230:231]
	v_lshl_add_u64 v[232:233], v[88:89], 0, v[244:245]
	ds_swizzle_b32 v236, v72 offset:swizzle(SWAP,8)
	ds_swizzle_b32 v237, v73 offset:swizzle(SWAP,8)
	ds_swizzle_b32 v238, v74 offset:swizzle(SWAP,8)
	ds_swizzle_b32 v239, v75 offset:swizzle(SWAP,8)
	ds_swizzle_b32 v240, v76 offset:swizzle(SWAP,8)
	ds_swizzle_b32 v241, v77 offset:swizzle(SWAP,8)
	ds_swizzle_b32 v242, v78 offset:swizzle(SWAP,8)
	ds_swizzle_b32 v243, v79 offset:swizzle(SWAP,8)
	s_waitcnt lgkmcnt(0)
	v_cndmask_b32_e64 v236, v236, v76, s[98:99]
	v_cndmask_b32_e64 v237, v237, v77, s[98:99]
	v_cndmask_b32_e64 v238, v238, v78, s[98:99]
	v_cndmask_b32_e64 v239, v239, v79, s[98:99]
	v_cndmask_b32_e64 v240, v72, v240, s[98:99]
	v_cndmask_b32_e64 v241, v73, v241, s[98:99]
	v_cndmask_b32_e64 v242, v74, v242, s[98:99]
	v_cndmask_b32_e64 v243, v75, v243, s[98:99]
	global_store_dwordx4 v[228:229], v[236:239], off
	global_store_dwordx4 v[232:233], v[240:243], off
	global_load_dwordx4 v[72:75], v[88:89], off offset:528
	s_nop 0
	global_load_dwordx4 v[76:79], v[88:89], off offset:512
	s_waitcnt vmcnt(1)
	v_pk_add_f32 v[66:67], v[66:67], v[74:75]
	s_waitcnt vmcnt(0)
	v_pk_add_f32 v[70:71], v[70:71], v[78:79]
	v_pk_add_f32 v[68:69], v[68:69], v[76:77]
	v_add_co_u32_e32 v74, vcc, s50, v144
	v_pk_add_f32 v[64:65], v[64:65], v[72:73]
	v_lshl_add_u64 v[228:229], v[88:89], 0, v[230:231]
	v_lshl_add_u64 v[232:233], v[88:89], 0, v[244:245]
	ds_swizzle_b32 v236, v64 offset:swizzle(SWAP,8)
	ds_swizzle_b32 v237, v65 offset:swizzle(SWAP,8)
	ds_swizzle_b32 v238, v66 offset:swizzle(SWAP,8)
	ds_swizzle_b32 v239, v67 offset:swizzle(SWAP,8)
	ds_swizzle_b32 v240, v68 offset:swizzle(SWAP,8)
	ds_swizzle_b32 v241, v69 offset:swizzle(SWAP,8)
	ds_swizzle_b32 v242, v70 offset:swizzle(SWAP,8)
	ds_swizzle_b32 v243, v71 offset:swizzle(SWAP,8)
	s_waitcnt lgkmcnt(0)
	v_cndmask_b32_e64 v236, v236, v68, s[98:99]
	v_cndmask_b32_e64 v237, v237, v69, s[98:99]
	v_cndmask_b32_e64 v238, v238, v70, s[98:99]
	v_cndmask_b32_e64 v239, v239, v71, s[98:99]
	v_cndmask_b32_e64 v240, v64, v240, s[98:99]
	v_cndmask_b32_e64 v241, v65, v241, s[98:99]
	v_cndmask_b32_e64 v242, v66, v242, s[98:99]
	v_cndmask_b32_e64 v243, v67, v243, s[98:99]
	global_store_dwordx4 v[228:229], v[236:239], off offset:512
	global_store_dwordx4 v[232:233], v[240:243], off offset:512
	v_addc_co_u32_e32 v75, vcc, 0, v145, vcc
	v_lshl_add_u64 v[72:73], v[144:145], 0, s[10:11]
	global_load_dwordx4 v[64:67], v[74:75], off
	global_load_dwordx4 v[68:71], v[72:73], off offset:16
	s_waitcnt vmcnt(1)
	v_pk_add_f32 v[62:63], v[62:63], v[66:67]
	v_pk_add_f32 v[60:61], v[60:61], v[64:65]
	s_waitcnt vmcnt(0)
	v_pk_add_f32 v[58:59], v[58:59], v[70:71]
	v_pk_add_f32 v[56:57], v[56:57], v[68:69]
	v_lshl_add_u64 v[228:229], v[74:75], 0, v[230:231]
	v_lshl_add_u64 v[232:233], v[72:73], 0, v[244:245]
	ds_swizzle_b32 v236, v56 offset:swizzle(SWAP,8)
	ds_swizzle_b32 v237, v57 offset:swizzle(SWAP,8)
	ds_swizzle_b32 v238, v58 offset:swizzle(SWAP,8)
	ds_swizzle_b32 v239, v59 offset:swizzle(SWAP,8)
	ds_swizzle_b32 v240, v60 offset:swizzle(SWAP,8)
	ds_swizzle_b32 v241, v61 offset:swizzle(SWAP,8)
	ds_swizzle_b32 v242, v62 offset:swizzle(SWAP,8)
	ds_swizzle_b32 v243, v63 offset:swizzle(SWAP,8)
	s_waitcnt lgkmcnt(0)
	v_cndmask_b32_e64 v236, v236, v60, s[98:99]
	v_cndmask_b32_e64 v237, v237, v61, s[98:99]
	v_cndmask_b32_e64 v238, v238, v62, s[98:99]
	v_cndmask_b32_e64 v239, v239, v63, s[98:99]
	v_cndmask_b32_e64 v240, v56, v240, s[98:99]
	v_cndmask_b32_e64 v241, v57, v241, s[98:99]
	v_cndmask_b32_e64 v242, v58, v242, s[98:99]
	v_cndmask_b32_e64 v243, v59, v243, s[98:99]
	global_store_dwordx4 v[228:229], v[236:239], off
	global_store_dwordx4 v[232:233], v[240:243], off
	global_load_dwordx4 v[56:59], v[72:73], off offset:528
	s_nop 0
	global_load_dwordx4 v[60:63], v[72:73], off offset:512
	s_waitcnt vmcnt(1)
	v_pk_add_f32 v[50:51], v[50:51], v[58:59]
	s_waitcnt vmcnt(0)
;     __device__ __forceinline__ void operator()(const f32x4 (&acc)[2][2][4][2], const Unit& u, int wr, int wc, int fr, int fq, const PG8_LAS float*) const {
;     ...
;             for (int m = 0; m < 4; ++m) { const int row = row0 + ai * HALF + m * 16; const size_t off = (size_t)row * ldc + col0; float ss = 0.f;
; #pragma unroll
;                 for (int bj = 0; bj < 2; ++bj) {
;                     const f32x4 b0 = *(const f32x4*)(base + off + bj * HALF), b1 = *(const f32x4*)(base + off + bj * HALF + 4);
;                     const f32x4 v0 = b0 + acc[ai][bj][m][0], v1 = b1 + acc[ai][bj][m][1];
;                     *(f32x4*)(out + off + bj * HALF) = v0; *(f32x4*)(out + off + bj * HALF + 4) = v1;
	v_pk_add_f32 v[54:55], v[54:55], v[62:63]
	v_pk_add_f32 v[52:53], v[52:53], v[60:61]
	v_add_co_u32_e32 v58, vcc, s51, v144
	v_pk_add_f32 v[48:49], v[48:49], v[56:57]
	v_lshl_add_u64 v[228:229], v[72:73], 0, v[230:231]
	v_lshl_add_u64 v[232:233], v[72:73], 0, v[244:245]
	ds_swizzle_b32 v236, v48 offset:swizzle(SWAP,8)
	ds_swizzle_b32 v237, v49 offset:swizzle(SWAP,8)
	ds_swizzle_b32 v238, v50 offset:swizzle(SWAP,8)
	ds_swizzle_b32 v239, v51 offset:swizzle(SWAP,8)
	ds_swizzle_b32 v240, v52 offset:swizzle(SWAP,8)
	ds_swizzle_b32 v241, v53 offset:swizzle(SWAP,8)
	ds_swizzle_b32 v242, v54 offset:swizzle(SWAP,8)
	ds_swizzle_b32 v243, v55 offset:swizzle(SWAP,8)
	s_waitcnt lgkmcnt(0)
	v_cndmask_b32_e64 v236, v236, v52, s[98:99]
	v_cndmask_b32_e64 v237, v237, v53, s[98:99]
	v_cndmask_b32_e64 v238, v238, v54, s[98:99]
	v_cndmask_b32_e64 v239, v239, v55, s[98:99]
	v_cndmask_b32_e64 v240, v48, v240, s[98:99]
	v_cndmask_b32_e64 v241, v49, v241, s[98:99]
	v_cndmask_b32_e64 v242, v50, v242, s[98:99]
	v_cndmask_b32_e64 v243, v51, v243, s[98:99]
	global_store_dwordx4 v[228:229], v[236:239], off offset:512
	global_store_dwordx4 v[232:233], v[240:243], off offset:512
	v_addc_co_u32_e32 v59, vcc, 0, v145, vcc
	v_lshl_add_u64 v[56:57], v[144:145], 0, s[12:13]
	global_load_dwordx4 v[48:51], v[58:59], off
	global_load_dwordx4 v[52:55], v[56:57], off offset:16
	s_waitcnt vmcnt(1)
	v_pk_add_f32 v[46:47], v[46:47], v[50:51]
	v_pk_add_f32 v[44:45], v[44:45], v[48:49]
	s_waitcnt vmcnt(0)
	v_pk_add_f32 v[42:43], v[42:43], v[54:55]
	v_pk_add_f32 v[40:41], v[40:41], v[52:53]
	v_lshl_add_u64 v[228:229], v[58:59], 0, v[230:231]
	v_lshl_add_u64 v[232:233], v[56:57], 0, v[244:245]
	ds_swizzle_b32 v236, v40 offset:swizzle(SWAP,8)
	ds_swizzle_b32 v237, v41 offset:swizzle(SWAP,8)
	ds_swizzle_b32 v238, v42 offset:swizzle(SWAP,8)
	ds_swizzle_b32 v239, v43 offset:swizzle(SWAP,8)
	ds_swizzle_b32 v240, v44 offset:swizzle(SWAP,8)
	ds_swizzle_b32 v241, v45 offset:swizzle(SWAP,8)
	ds_swizzle_b32 v242, v46 offset:swizzle(SWAP,8)
	ds_swizzle_b32 v243, v47 offset:swizzle(SWAP,8)
	s_waitcnt lgkmcnt(0)
	v_cndmask_b32_e64 v236, v236, v44, s[98:99]
	v_cndmask_b32_e64 v237, v237, v45, s[98:99]
	v_cndmask_b32_e64 v238, v238, v46, s[98:99]
	v_cndmask_b32_e64 v239, v239, v47, s[98:99]
	v_cndmask_b32_e64 v240, v40, v240, s[98:99]
	v_cndmask_b32_e64 v241, v41, v241, s[98:99]
	v_cndmask_b32_e64 v242, v42, v242, s[98:99]
	v_cndmask_b32_e64 v243, v43, v243, s[98:99]
	global_store_dwordx4 v[228:229], v[236:239], off
	global_store_dwordx4 v[232:233], v[240:243], off
	global_load_dwordx4 v[40:43], v[56:57], off offset:528
	s_nop 0
	global_load_dwordx4 v[44:47], v[56:57], off offset:512
	s_waitcnt vmcnt(1)
	v_pk_add_f32 v[34:35], v[34:35], v[42:43]
	s_waitcnt vmcnt(0)
	v_pk_add_f32 v[38:39], v[38:39], v[46:47]
	v_pk_add_f32 v[36:37], v[36:37], v[44:45]
	v_add_co_u32_e32 v42, vcc, s52, v144
	v_pk_add_f32 v[32:33], v[32:33], v[40:41]
	v_lshl_add_u64 v[228:229], v[56:57], 0, v[230:231]
	v_lshl_add_u64 v[232:233], v[56:57], 0, v[244:245]
	ds_swizzle_b32 v236, v32 offset:swizzle(SWAP,8)
	ds_swizzle_b32 v237, v33 offset:swizzle(SWAP,8)
	ds_swizzle_b32 v238, v34 offset:swizzle(SWAP,8)
	ds_swizzle_b32 v239, v35 offset:swizzle(SWAP,8)
	ds_swizzle_b32 v240, v36 offset:swizzle(SWAP,8)
	ds_swizzle_b32 v241, v37 offset:swizzle(SWAP,8)
	ds_swizzle_b32 v242, v38 offset:swizzle(SWAP,8)
	ds_swizzle_b32 v243, v39 offset:swizzle(SWAP,8)
	s_waitcnt lgkmcnt(0)
	v_cndmask_b32_e64 v236, v236, v36, s[98:99]
	v_cndmask_b32_e64 v237, v237, v37, s[98:99]
	v_cndmask_b32_e64 v238, v238, v38, s[98:99]
	v_cndmask_b32_e64 v239, v239, v39, s[98:99]
	v_cndmask_b32_e64 v240, v32, v240, s[98:99]
	v_cndmask_b32_e64 v241, v33, v241, s[98:99]
	v_cndmask_b32_e64 v242, v34, v242, s[98:99]
	v_cndmask_b32_e64 v243, v35, v243, s[98:99]
	global_store_dwordx4 v[228:229], v[236:239], off offset:512
	global_store_dwordx4 v[232:233], v[240:243], off offset:512
	v_addc_co_u32_e32 v43, vcc, 0, v145, vcc
	v_lshl_add_u64 v[40:41], v[144:145], 0, s[14:15]
	global_load_dwordx4 v[32:35], v[42:43], off
	global_load_dwordx4 v[36:39], v[40:41], off offset:16
	s_waitcnt vmcnt(1)
	v_pk_add_f32 v[30:31], v[30:31], v[34:35]
	v_pk_add_f32 v[28:29], v[28:29], v[32:33]
	s_waitcnt vmcnt(0)
	v_pk_add_f32 v[26:27], v[26:27], v[38:39]
	v_pk_add_f32 v[24:25], v[24:25], v[36:37]
	v_lshl_add_u64 v[228:229], v[42:43], 0, v[230:231]
	v_lshl_add_u64 v[232:233], v[40:41], 0, v[244:245]
	ds_swizzle_b32 v236, v24 offset:swizzle(SWAP,8)
	ds_swizzle_b32 v237, v25 offset:swizzle(SWAP,8)
	ds_swizzle_b32 v238, v26 offset:swizzle(SWAP,8)
	ds_swizzle_b32 v239, v27 offset:swizzle(SWAP,8)
	ds_swizzle_b32 v240, v28 offset:swizzle(SWAP,8)
	ds_swizzle_b32 v241, v29 offset:swizzle(SWAP,8)
	ds_swizzle_b32 v242, v30 offset:swizzle(SWAP,8)
	ds_swizzle_b32 v243, v31 offset:swizzle(SWAP,8)
	s_waitcnt lgkmcnt(0)
;     __device__ __forceinline__ void operator()(const f32x4 (&acc)[2][2][4][2], const Unit& u, int wr, int wc, int fr, int fq, const PG8_LAS float*) const {
;     ...
;             for (int m = 0; m < 4; ++m) { const int row = row0 + ai * HALF + m * 16; const size_t off = (size_t)row * ldc + col0; float ss = 0.f;
; #pragma unroll
;                 for (int bj = 0; bj < 2; ++bj) {
;                     const f32x4 b0 = *(const f32x4*)(base + off + bj * HALF), b1 = *(const f32x4*)(base + off + bj * HALF + 4);
;                     const f32x4 v0 = b0 + acc[ai][bj][m][0], v1 = b1 + acc[ai][bj][m][1];
;                     *(f32x4*)(out + off + bj * HALF) = v0; *(f32x4*)(out + off + bj * HALF + 4) = v1;
	v_cndmask_b32_e64 v236, v236, v28, s[98:99]
	v_cndmask_b32_e64 v237, v237, v29, s[98:99]
	v_cndmask_b32_e64 v238, v238, v30, s[98:99]
	v_cndmask_b32_e64 v239, v239, v31, s[98:99]
	v_cndmask_b32_e64 v240, v24, v240, s[98:99]
	v_cndmask_b32_e64 v241, v25, v241, s[98:99]
	v_cndmask_b32_e64 v242, v26, v242, s[98:99]
	v_cndmask_b32_e64 v243, v27, v243, s[98:99]
	global_store_dwordx4 v[228:229], v[236:239], off
	global_store_dwordx4 v[232:233], v[240:243], off
	global_load_dwordx4 v[24:27], v[40:41], off offset:528
	s_nop 0
	global_load_dwordx4 v[28:31], v[40:41], off offset:512
	s_waitcnt vmcnt(1)
	v_pk_add_f32 v[18:19], v[18:19], v[26:27]
	s_waitcnt vmcnt(0)
	v_pk_add_f32 v[22:23], v[22:23], v[30:31]
	v_pk_add_f32 v[20:21], v[20:21], v[28:29]
	v_add_co_u32_e32 v26, vcc, s53, v144
	v_pk_add_f32 v[16:17], v[16:17], v[24:25]
	v_lshl_add_u64 v[228:229], v[40:41], 0, v[230:231]
	v_lshl_add_u64 v[232:233], v[40:41], 0, v[244:245]
	ds_swizzle_b32 v236, v16 offset:swizzle(SWAP,8)
	ds_swizzle_b32 v237, v17 offset:swizzle(SWAP,8)
	ds_swizzle_b32 v238, v18 offset:swizzle(SWAP,8)
	ds_swizzle_b32 v239, v19 offset:swizzle(SWAP,8)
	ds_swizzle_b32 v240, v20 offset:swizzle(SWAP,8)
	ds_swizzle_b32 v241, v21 offset:swizzle(SWAP,8)
	ds_swizzle_b32 v242, v22 offset:swizzle(SWAP,8)
	ds_swizzle_b32 v243, v23 offset:swizzle(SWAP,8)
	s_waitcnt lgkmcnt(0)
	v_cndmask_b32_e64 v236, v236, v20, s[98:99]
	v_cndmask_b32_e64 v237, v237, v21, s[98:99]
	v_cndmask_b32_e64 v238, v238, v22, s[98:99]
	v_cndmask_b32_e64 v239, v239, v23, s[98:99]
	v_cndmask_b32_e64 v240, v16, v240, s[98:99]
	v_cndmask_b32_e64 v241, v17, v241, s[98:99]
	v_cndmask_b32_e64 v242, v18, v242, s[98:99]
	v_cndmask_b32_e64 v243, v19, v243, s[98:99]
	global_store_dwordx4 v[228:229], v[236:239], off offset:512
	global_store_dwordx4 v[232:233], v[240:243], off offset:512
	v_addc_co_u32_e32 v27, vcc, 0, v145, vcc
	s_nop 0
	v_lshl_add_u64 v[16:17], v[144:145], 0, s[16:17]
	global_load_dwordx4 v[18:21], v[26:27], off
	global_load_dwordx4 v[22:25], v[16:17], off offset:16
	s_andn2_b64 vcc, exec, s[2:3]
	s_waitcnt vmcnt(1)
	v_pk_add_f32 v[14:15], v[14:15], v[20:21]
	v_pk_add_f32 v[12:13], v[12:13], v[18:19]
	s_waitcnt vmcnt(0)
	v_pk_add_f32 v[10:11], v[10:11], v[24:25]
	v_pk_add_f32 v[8:9], v[8:9], v[22:23]
	v_lshl_add_u64 v[228:229], v[26:27], 0, v[230:231]
	v_lshl_add_u64 v[232:233], v[16:17], 0, v[244:245]
	ds_swizzle_b32 v236, v8 offset:swizzle(SWAP,8)
	ds_swizzle_b32 v237, v9 offset:swizzle(SWAP,8)
	ds_swizzle_b32 v238, v10 offset:swizzle(SWAP,8)
	ds_swizzle_b32 v239, v11 offset:swizzle(SWAP,8)
	ds_swizzle_b32 v240, v12 offset:swizzle(SWAP,8)
	ds_swizzle_b32 v241, v13 offset:swizzle(SWAP,8)
	ds_swizzle_b32 v242, v14 offset:swizzle(SWAP,8)
	ds_swizzle_b32 v243, v15 offset:swizzle(SWAP,8)
	s_waitcnt lgkmcnt(0)
	v_cndmask_b32_e64 v236, v236, v12, s[98:99]
	v_cndmask_b32_e64 v237, v237, v13, s[98:99]
	v_cndmask_b32_e64 v238, v238, v14, s[98:99]
	v_cndmask_b32_e64 v239, v239, v15, s[98:99]
	v_cndmask_b32_e64 v240, v8, v240, s[98:99]
	v_cndmask_b32_e64 v241, v9, v241, s[98:99]
	v_cndmask_b32_e64 v242, v10, v242, s[98:99]
	v_cndmask_b32_e64 v243, v11, v243, s[98:99]
	global_store_dwordx4 v[228:229], v[236:239], off
	global_store_dwordx4 v[232:233], v[240:243], off
	global_load_dwordx4 v[8:11], v[16:17], off offset:528
	s_nop 0
	global_load_dwordx4 v[12:15], v[16:17], off offset:512
	s_waitcnt vmcnt(1)
	v_pk_add_f32 v[2:3], v[2:3], v[10:11]
	s_waitcnt vmcnt(0)
	v_pk_add_f32 v[6:7], v[6:7], v[14:15]
	v_pk_add_f32 v[4:5], v[4:5], v[12:13]
	v_pk_add_f32 v[0:1], v[0:1], v[8:9]
	v_lshl_add_u64 v[228:229], v[16:17], 0, v[230:231]
	v_lshl_add_u64 v[232:233], v[16:17], 0, v[244:245]
	ds_swizzle_b32 v236, v0 offset:swizzle(SWAP,8)
	ds_swizzle_b32 v237, v1 offset:swizzle(SWAP,8)
	ds_swizzle_b32 v238, v2 offset:swizzle(SWAP,8)
	ds_swizzle_b32 v239, v3 offset:swizzle(SWAP,8)
	ds_swizzle_b32 v240, v4 offset:swizzle(SWAP,8)
	ds_swizzle_b32 v241, v5 offset:swizzle(SWAP,8)
	ds_swizzle_b32 v242, v6 offset:swizzle(SWAP,8)
	ds_swizzle_b32 v243, v7 offset:swizzle(SWAP,8)
	s_waitcnt lgkmcnt(0)
	v_cndmask_b32_e64 v236, v236, v4, s[98:99]
	v_cndmask_b32_e64 v237, v237, v5, s[98:99]
	v_cndmask_b32_e64 v238, v238, v6, s[98:99]
	v_cndmask_b32_e64 v239, v239, v7, s[98:99]
	v_cndmask_b32_e64 v240, v0, v240, s[98:99]
	v_cndmask_b32_e64 v241, v1, v241, s[98:99]
	v_cndmask_b32_e64 v242, v2, v242, s[98:99]
	v_cndmask_b32_e64 v243, v3, v243, s[98:99]
	global_store_dwordx4 v[228:229], v[236:239], off offset:512
	global_store_dwordx4 v[232:233], v[240:243], off offset:512
	s_cbranch_vccnz .LBB0_1633
	s_andn2_b64 vcc, exec, s[4:5]
	s_cbranch_vccnz .LBB0_1632
	s_barrier
	s_branch .LBB0_1632

; #define LAS __attribute__((address_space(3)))
; __global__ void __launch_bounds__(NTHREADS, 2) fwd_kernel(KArgs a) {
;     extern __shared__ __attribute__((aligned(16))) unsigned char lds_raw[];
;     LAS unsigned char* lds = (LAS unsigned char*)lds_raw;
	.amdhsa_kernel _Z10fwd_kernel5KArgs
		.amdhsa_group_segment_fixed_size 0
		.amdhsa_private_segment_fixed_size 0
		.amdhsa_kernarg_size 408
		.amdhsa_user_sgpr_count 2
		.amdhsa_user_sgpr_dispatch_ptr 0
		.amdhsa_user_sgpr_queue_ptr 0
		.amdhsa_user_sgpr_kernarg_segment_ptr 1
		.amdhsa_user_sgpr_dispatch_id 0
		.amdhsa_user_sgpr_kernarg_preload_length 0
		.amdhsa_user_sgpr_kernarg_preload_offset 0
		.amdhsa_user_sgpr_private_segment_size 0
		.amdhsa_uses_dynamic_stack 0
		.amdhsa_enable_private_segment 0
		.amdhsa_system_sgpr_workgroup_id_x 1
		.amdhsa_system_sgpr_workgroup_id_y 0
		.amdhsa_system_sgpr_workgroup_id_z 0
		.amdhsa_system_sgpr_workgroup_info 0
		.amdhsa_system_vgpr_workitem_id 2
		.amdhsa_next_free_vgpr 255
		.amdhsa_next_free_sgpr 100
		.amdhsa_accum_offset 256
		.amdhsa_reserve_vcc 1
		.amdhsa_float_round_mode_32 0
		.amdhsa_float_round_mode_16_64 0
		.amdhsa_float_denorm_mode_32 3
		.amdhsa_float_denorm_mode_16_64 3
		.amdhsa_dx10_clamp 1
		.amdhsa_ieee_mode 1
		.amdhsa_fp16_overflow 0
		.amdhsa_tg_split 0
		.amdhsa_exception_fp_ieee_invalid_op 0
		.amdhsa_exception_fp_denorm_src 0
		.amdhsa_exception_fp_ieee_div_zero 0
		.amdhsa_exception_fp_ieee_overflow 0
		.amdhsa_exception_fp_ieee_underflow 0
		.amdhsa_exception_fp_ieee_inexact 0
		.amdhsa_exception_int_div_zero 0
	.end_amdhsa_kernel

; #define LAS __attribute__((address_space(3)))
; __global__ void __launch_bounds__(NTHREADS, 2) fwd_kernel(KArgs a) {
;     extern __shared__ __attribute__((aligned(16))) unsigned char lds_raw[];
;     LAS unsigned char* lds = (LAS unsigned char*)lds_raw;
amdhsa.kernels:
  - .agpr_count:     0
    .args:
      - .offset:         0
        .size:           152
        .value_kind:     by_value
      - .offset:         152
        .size:           4
        .value_kind:     hidden_block_count_x
      - .offset:         156
        .size:           4
        .value_kind:     hidden_block_count_y
      - .offset:         160
        .size:           4
        .value_kind:     hidden_block_count_z
      - .offset:         164
        .size:           2
        .value_kind:     hidden_group_size_x
      - .offset:         166
        .size:           2
        .value_kind:     hidden_group_size_y
      - .offset:         168
        .size:           2
        .value_kind:     hidden_group_size_z
      - .offset:         170
        .size:           2
        .value_kind:     hidden_remainder_x
      - .offset:         172
        .size:           2
        .value_kind:     hidden_remainder_y
      - .offset:         174
        .size:           2
        .value_kind:     hidden_remainder_z
      - .offset:         192
        .size:           8
        .value_kind:     hidden_global_offset_x
      - .offset:         200
        .size:           8
        .value_kind:     hidden_global_offset_y
      - .offset:         208
        .size:           8
        .value_kind:     hidden_global_offset_z
      - .offset:         216
        .size:           2
        .value_kind:     hidden_grid_dims
      - .offset:         240
        .size:           8
        .value_kind:     hidden_multigrid_sync_arg
      - .offset:         272
        .size:           4
        .value_kind:     hidden_dynamic_lds_size
    .group_segment_fixed_size: 0
    .kernarg_segment_align: 8
    .kernarg_segment_size: 408
    .language:       OpenCL C
    .language_version:
      - 2
      - 0
    .max_flat_workgroup_size: 512
    .name:           _Z10fwd_kernel5KArgs
    .private_segment_fixed_size: 0
    .sgpr_count:     106
    .sgpr_spill_count: 151
    .symbol:         _Z10fwd_kernel5KArgs.kd
    .uniform_work_group_size: 1
    .uses_dynamic_stack: false
    .vgpr_count:     255
    .vgpr_spill_count: 0
    .wavefront_size: 64
